# mixer phases: 15 pairs of f32 division chains on adjacent registers computed as one chain of packed f32 ops (same IEEE operations per element), constant 1.0 numerators inline
# speedup vs baseline: 1.0010x; 1.0010x over previous
; DI size_t kblk(int row, int col, int nrows) { return ((size_t)(col >> 5) * nrows + row) * 32 + (col & 31); }
; DI float bf2f(bf16_t v) { return __uint_as_float(((unsigned)v) << 16); }
; DI unsigned pk2(float a, float b) { hwf32x2 f = {a, b}; hwbf16x2 r = __builtin_convertvector(f, hwbf16x2); return __builtin_bit_cast(unsigned, r); }
; DI float siluf_(float z) { return z / (1.f + __expf(-z)); }
; DI int crow(int reg, int h) { return (reg & 3) + 8 * (reg >> 2) + 4 * h; }
; template <int MODE>
; DI void attn_mfma(const Params& p, int l, int b, int hd, int qb, unsigned char* smem) {
;     ...
;     float* sO = (float*)smem;
;     const int ql = (wv & 1) * 32 + r;
;     __syncthreads();
;     if (mp == 1) {
;       const float i1 = lam / ltot;
; #pragma unroll
;       for (int vt = 0; vt < 2; ++vt)
; #pragma unroll
;         for (int i = 0; i < 16; ++i) sO[ql * 65 + vt * 32 + crow(i, h2)] = O[vt][i] * i1;
;     }
;     __syncthreads();
;     if (mp == 0) {
;       const float i0 = 1.f / ltot;
;       float ss = 0.f;
; #pragma unroll
;       for (int vt = 0; vt < 2; ++vt)
; #pragma unroll
;         for (int i = 0; i < 16; ++i) { const float o = O[vt][i] * i0 - sO[ql * 65 + vt * 32 + crow(i, h2)]; O[vt][i] = o; ss += o * o; }
;       ss += __shfl_xor(ss, 32);
;       const float rstd = rsqrtf(ss * (1.f / 64.f) + EPS) * (1.f - lam_init);
; #pragma unroll
;       for (int vt = 0; vt < 2; ++vt)
; #pragma unroll
;         for (int g4 = 0; g4 < 4; ++g4) {
;           const int v0 = vt * 32 + 8 * g4 + 4 * h2;
;           const ushort4 gt = *(const ushort4*)(P + qrow * PW + GATE + hd * 64 + v0);
;           const float4 gg = *(const float4*)(p.diff_g + l * 64 + v0);
;           uint2 o;
;           o.x = pk2(O[vt][4 * g4 + 0] * rstd * gg.x * siluf_(bf2f(gt.x)), O[vt][4 * g4 + 1] * rstd * gg.y * siluf_(bf2f(gt.y)));
;           o.y = pk2(O[vt][4 * g4 + 2] * rstd * gg.z * siluf_(bf2f(gt.z)), O[vt][4 * g4 + 3] * rstd * gg.w * siluf_(bf2f(gt.w)));
;           *(uint2*)(MIX + kblk((int)qrow, hd * 64 + v0, ROWS)) = o;
;         }
.LBB0_588:
	s_or_b64 exec, exec, s[0:1]
	s_movk_i32 s0, 0x80
	v_cmp_gt_u32_e32 vcc, s0, v196
	s_waitcnt lgkmcnt(0)
	s_barrier
	s_and_saveexec_b64 s[0:1], vcc
	s_xor_b64 s[0:1], exec, s[0:1]
	s_cbranch_execz .LBB0_590
	s_waitcnt vmcnt(0)
	v_rcp_f32_e32 v33, v160
	s_add_u32 s4, s40, 0x1dc6000
	s_addc_u32 s5, s41, 0
	s_lshl_b32 s2, s7, 1
	v_fma_f32 v34, -v160, v33, 1.0
	v_fmac_f32_e32 v33, v34, v33
	v_mul_f32_e32 v35, 1.0, v33
	v_fma_f32 v36, -v160, v35, 1.0
	v_fmac_f32_e32 v35, v36, v33
	v_fma_f32 v32, -v160, v35, 1.0
	v_fma_f32 v32, v32, v33, v35
	v_div_fixup_f32 v44, v32, v160, 1.0
	ds_read2_b32 v[32:33], v197 offset0:56 offset1:57
	s_mul_i32 s6, s6, 0x9000
	v_add_lshl_u32 v160, v165, s6, 6
	v_mov_b32_e32 v165, v161
	s_mov_b64 s[6:7], 0x1a20
	s_waitcnt lgkmcnt(0)
	v_pk_fma_f32 v[34:35], v[12:13], v[44:45], v[32:33] op_sel_hi:[1,0,1] neg_lo:[0,0,1] neg_hi:[0,0,1]
	ds_read2_b32 v[12:13], v197 offset0:58 offset1:59
	ds_read2_b32 v[82:83], v197 offset0:48 offset1:49
	ds_read2_b32 v[48:49], v197 offset1:1
	v_readlane_b32 s8, v254, 27
	v_readlane_b32 s9, v254, 28
	s_waitcnt lgkmcnt(2)
	v_pk_fma_f32 v[32:33], v[14:15], v[44:45], v[12:13] op_sel_hi:[1,0,1] neg_lo:[0,0,1] neg_hi:[0,0,1]
	ds_read2_b32 v[14:15], v197 offset0:2 offset1:3
	v_lshl_add_u64 v[12:13], v[166:167], 0, s[2:3]
	v_lshl_add_u64 v[12:13], v[12:13], 0, v[164:165]
	v_lshl_add_u64 v[36:37], v[12:13], 0, s[6:7]
	global_load_dwordx2 v[204:205], v[36:37], off
	global_load_dwordx2 v[206:207], v[36:37], off offset:16
	global_load_dwordx2 v[208:209], v[36:37], off offset:32
	global_load_dwordx2 v[210:211], v[36:37], off offset:48
	global_load_dwordx2 v[212:213], v[36:37], off offset:64
	global_load_dwordx2 v[214:215], v[36:37], off offset:80
	global_load_dwordx2 v[216:217], v[36:37], off offset:96
	global_load_dwordx2 v[218:219], v[36:37], off offset:112
	global_load_dwordx4 v[220:223], v171, s[8:9]
	global_load_dwordx4 v[224:227], v171, s[8:9] offset:32
	global_load_dwordx4 v[228:231], v171, s[8:9] offset:64
	global_load_dwordx4 v[232:235], v171, s[8:9] offset:96
	global_load_dwordx4 v[236:239], v171, s[8:9] offset:128
	global_load_dwordx4 v[240:243], v171, s[8:9] offset:160
	global_load_dwordx4 v[244:247], v171, s[8:9] offset:192
	global_load_dwordx4 v[248:251], v171, s[8:9] offset:224
	v_add_co_u32_e32 v12, vcc, s16, v12
	s_waitcnt lgkmcnt(0)
	v_pk_fma_f32 v[46:47], v[18:19], v[44:45], v[14:15] op_sel_hi:[1,0,1] neg_lo:[0,0,1] neg_hi:[0,0,1]
	v_addc_co_u32_e32 v13, vcc, 0, v13, vcc
	s_nop 0
	v_pk_fma_f32 v[48:49], v[16:17], v[44:45], v[48:49] op_sel_hi:[1,0,1] neg_lo:[0,0,1] neg_hi:[0,0,1]
	s_nop 0
	v_pk_mul_f32 v[56:57], v[48:49], v[48:49]
	v_pk_mul_f32 v[52:53], v[46:47], v[46:47]
	v_add_f32_e32 v56, v56, v57
	v_add_f32_e32 v52, v56, v52
	v_add_f32_e32 v52, v52, v53
	v_lshl_add_u64 v[38:39], s[4:5], 0, v[160:161]
	v_add_u32_e32 v160, 0x120000, v160
	v_pk_mul_f32 v[40:41], v[34:35], v[34:35]
	v_pk_mul_f32 v[42:43], v[32:33], v[32:33]
	v_lshl_add_u64 v[38:39], v[38:39], 0, v[164:165]
	s_waitcnt vmcnt(0) lgkmcnt(0)
	v_mov_b32_e32 v18, v204
	v_mov_b32_e32 v19, v205
	v_mov_b32_e32 v12, v220
	v_mov_b32_e32 v13, v221
	v_mov_b32_e32 v14, v222
	v_mov_b32_e32 v15, v223
	v_and_b32_e32 v45, 0xffff0000, v18
	v_lshlrev_b32_e32 v18, 16, v18
	v_mul_f32_e32 v16, 0xbfb8aa3b, v18
	v_mul_f32_e32 v17, 0xbfb8aa3b, v45
	v_exp_f32_e32 v16, v16
	v_exp_f32_e32 v17, v17
	s_nop 0
	v_pk_add_f32 v[16:17], v[16:17], 1.0 op_sel_hi:[1,0]
	s_nop 0
	v_mov_b32_e32 v62, v18
	v_mov_b32_e32 v63, v45
	v_rcp_f32_e32 v54, v16
	v_rcp_f32_e32 v55, v17
	s_nop 0
	v_pk_fma_f32 v[60:61], v[16:17], v[54:55], 1.0 op_sel_hi:[1,1,0] neg_lo:[1,0,0] neg_hi:[1,0,0]
	v_pk_fma_f32 v[54:55], v[60:61], v[54:55], v[54:55]
	v_pk_mul_f32 v[58:59], v[62:63], v[54:55]
	v_pk_fma_f32 v[60:61], v[16:17], v[58:59], v[62:63] neg_lo:[1,0,0] neg_hi:[1,0,0]
	v_pk_fma_f32 v[58:59], v[60:61], v[54:55], v[58:59]
	v_pk_fma_f32 v[60:61], v[16:17], v[58:59], v[62:63] neg_lo:[1,0,0] neg_hi:[1,0,0]
	v_pk_fma_f32 v[58:59], v[60:61], v[54:55], v[58:59]
	v_div_fixup_f32 v50, v58, v16, v18
	v_div_fixup_f32 v51, v59, v17, v45
	s_nop 0
	s_nop 0
	v_and_b32_e32 v18, 0xffff0000, v19
	v_lshlrev_b32_e32 v19, 16, v19
	v_mul_f32_e32 v16, 0xbfb8aa3b, v19
	v_mul_f32_e32 v17, 0xbfb8aa3b, v18
	v_exp_f32_e32 v16, v16
	v_exp_f32_e32 v17, v17
	s_nop 0
	v_pk_add_f32 v[16:17], v[16:17], 1.0 op_sel_hi:[1,0]
	s_nop 0
	v_mov_b32_e32 v64, v19
	v_mov_b32_e32 v65, v18
	v_rcp_f32_e32 v58, v16
	v_rcp_f32_e32 v59, v17
	s_nop 0
	v_pk_fma_f32 v[62:63], v[16:17], v[58:59], 1.0 op_sel_hi:[1,1,0] neg_lo:[1,0,0] neg_hi:[1,0,0]
	v_pk_fma_f32 v[58:59], v[62:63], v[58:59], v[58:59]
	v_pk_mul_f32 v[60:61], v[64:65], v[58:59]
	v_pk_fma_f32 v[62:63], v[16:17], v[60:61], v[64:65] neg_lo:[1,0,0] neg_hi:[1,0,0]
	v_pk_fma_f32 v[60:61], v[62:63], v[58:59], v[60:61]
	v_pk_fma_f32 v[62:63], v[16:17], v[60:61], v[64:65] neg_lo:[1,0,0] neg_hi:[1,0,0]
	v_pk_fma_f32 v[60:61], v[62:63], v[58:59], v[60:61]
	v_div_fixup_f32 v54, v60, v16, v19
	v_div_fixup_f32 v55, v61, v17, v18
	s_nop 0
	s_nop 0
	ds_read2_b32 v[16:17], v197 offset0:10 offset1:11
	ds_read2_b32 v[18:19], v197 offset0:8 offset1:9
	s_waitcnt lgkmcnt(1)
	v_pk_fma_f32 v[60:61], v[22:23], v[44:45], v[16:17] op_sel_hi:[1,0,1] neg_lo:[0,0,1] neg_hi:[0,0,1]
	s_nop 0
	s_waitcnt lgkmcnt(0)
; DI float bf2f(bf16_t v) { return __uint_as_float(((unsigned)v) << 16); }
; DI unsigned pk2(float a, float b) { hwf32x2 f = {a, b}; hwbf16x2 r = __builtin_convertvector(f, hwbf16x2); return __builtin_bit_cast(unsigned, r); }
; DI float siluf_(float z) { return z / (1.f + __expf(-z)); }
; DI int crow(int reg, int h) { return (reg & 3) + 8 * (reg >> 2) + 4 * h; }
; template <int MODE>
; DI void attn_mfma(const Params& p, int l, int b, int hd, int qb, unsigned char* smem) {
;     ...
;     if (mp == 0) {
;       const float i0 = 1.f / ltot;
;       float ss = 0.f;
; #pragma unroll
;       for (int vt = 0; vt < 2; ++vt)
; #pragma unroll
;         for (int i = 0; i < 16; ++i) { const float o = O[vt][i] * i0 - sO[ql * 65 + vt * 32 + crow(i, h2)]; O[vt][i] = o; ss += o * o; }
;       ss += __shfl_xor(ss, 32);
;       const float rstd = rsqrtf(ss * (1.f / 64.f) + EPS) * (1.f - lam_init);
; #pragma unroll
;       for (int vt = 0; vt < 2; ++vt)
; #pragma unroll
;         for (int g4 = 0; g4 < 4; ++g4) {
;           const int v0 = vt * 32 + 8 * g4 + 4 * h2;
;           const ushort4 gt = *(const ushort4*)(P + qrow * PW + GATE + hd * 64 + v0);
;           const float4 gg = *(const float4*)(p.diff_g + l * 64 + v0);
;           uint2 o;
;           o.x = pk2(O[vt][4 * g4 + 0] * rstd * gg.x * siluf_(bf2f(gt.x)), O[vt][4 * g4 + 1] * rstd * gg.y * siluf_(bf2f(gt.y)));
;           o.y = pk2(O[vt][4 * g4 + 2] * rstd * gg.z * siluf_(bf2f(gt.z)), O[vt][4 * g4 + 3] * rstd * gg.w * siluf_(bf2f(gt.w)));
	v_pk_fma_f32 v[62:63], v[20:21], v[44:45], v[18:19] op_sel_hi:[1,0,1] neg_lo:[0,0,1] neg_hi:[0,0,1]
	v_pk_mul_f32 v[68:69], v[60:61], v[60:61]
	v_pk_mul_f32 v[70:71], v[62:63], v[62:63]
	s_nop 0
	v_mov_b32_e32 v16, v206
	v_mov_b32_e32 v17, v207
	v_and_b32_e32 v20, 0xffff0000, v16
	v_lshlrev_b32_e32 v16, 16, v16
	v_mul_f32_e32 v18, 0xbfb8aa3b, v16
	v_mul_f32_e32 v19, 0xbfb8aa3b, v20
	v_exp_f32_e32 v18, v18
	v_exp_f32_e32 v19, v19
	v_add_f32_e32 v52, v52, v70
	v_add_f32_e32 v52, v52, v71
	v_add_f32_e32 v52, v52, v68
	v_pk_add_f32 v[18:19], v[18:19], 1.0 op_sel_hi:[1,0]
	v_add_f32_e32 v52, v52, v69
	v_mov_b32_e32 v72, v16
	v_mov_b32_e32 v73, v20
	v_rcp_f32_e32 v22, v18
	v_rcp_f32_e32 v23, v19
	s_nop 0
	v_pk_fma_f32 v[66:67], v[18:19], v[22:23], 1.0 op_sel_hi:[1,1,0] neg_lo:[1,0,0] neg_hi:[1,0,0]
	v_pk_fma_f32 v[22:23], v[66:67], v[22:23], v[22:23]
	v_pk_mul_f32 v[58:59], v[72:73], v[22:23]
	v_pk_fma_f32 v[66:67], v[18:19], v[58:59], v[72:73] neg_lo:[1,0,0] neg_hi:[1,0,0]
	v_pk_fma_f32 v[58:59], v[66:67], v[22:23], v[58:59]
	v_pk_fma_f32 v[66:67], v[18:19], v[58:59], v[72:73] neg_lo:[1,0,0] neg_hi:[1,0,0]
	v_pk_fma_f32 v[58:59], v[66:67], v[22:23], v[58:59]
	v_div_fixup_f32 v64, v58, v18, v16
	v_div_fixup_f32 v65, v59, v19, v20
	s_nop 0
	s_nop 0
	v_and_b32_e32 v18, 0xffff0000, v17
	v_lshlrev_b32_e32 v19, 16, v17
	v_mul_f32_e32 v16, 0xbfb8aa3b, v19
	v_mul_f32_e32 v17, 0xbfb8aa3b, v18
	v_exp_f32_e32 v16, v16
	v_exp_f32_e32 v17, v17
	s_nop 0
	v_pk_add_f32 v[16:17], v[16:17], 1.0 op_sel_hi:[1,0]
	s_nop 0
	v_mov_b32_e32 v72, v19
	v_mov_b32_e32 v73, v18
	v_rcp_f32_e32 v20, v16
	v_rcp_f32_e32 v21, v17
	s_nop 0
	v_pk_fma_f32 v[58:59], v[16:17], v[20:21], 1.0 op_sel_hi:[1,1,0] neg_lo:[1,0,0] neg_hi:[1,0,0]
	v_pk_fma_f32 v[20:21], v[58:59], v[20:21], v[20:21]
	v_pk_mul_f32 v[22:23], v[72:73], v[20:21]
	v_pk_fma_f32 v[58:59], v[16:17], v[22:23], v[72:73] neg_lo:[1,0,0] neg_hi:[1,0,0]
	v_pk_fma_f32 v[22:23], v[58:59], v[20:21], v[22:23]
	v_pk_fma_f32 v[58:59], v[16:17], v[22:23], v[72:73] neg_lo:[1,0,0] neg_hi:[1,0,0]
	v_pk_fma_f32 v[22:23], v[58:59], v[20:21], v[22:23]
	v_div_fixup_f32 v66, v22, v16, v19
	v_div_fixup_f32 v67, v23, v17, v18
	s_nop 0
	v_pk_fma_f32 v[8:9], v[8:9], v[44:45], v[82:83] op_sel_hi:[1,0,1] neg_lo:[0,0,1] neg_hi:[0,0,1]
	ds_read2_b32 v[16:17], v197 offset0:18 offset1:19
	ds_read2_b32 v[18:19], v197 offset0:34 offset1:35
	s_waitcnt lgkmcnt(1)
	v_pk_fma_f32 v[26:27], v[26:27], v[44:45], v[16:17] op_sel_hi:[1,0,1] neg_lo:[0,0,1] neg_hi:[0,0,1]
	ds_read2_b32 v[16:17], v197 offset0:16 offset1:17
	s_waitcnt lgkmcnt(1)
	v_pk_fma_f32 v[18:19], v[2:3], v[44:45], v[18:19] op_sel_hi:[1,0,1] neg_lo:[0,0,1] neg_hi:[0,0,1]
	ds_read2_b32 v[2:3], v197 offset0:32 offset1:33
	v_pk_mul_f32 v[72:73], v[26:27], v[26:27]
	s_waitcnt lgkmcnt(1)
	v_pk_fma_f32 v[58:59], v[24:25], v[44:45], v[16:17] op_sel_hi:[1,0,1] neg_lo:[0,0,1] neg_hi:[0,0,1]
	ds_read2_b32 v[16:17], v197 offset0:26 offset1:27
	s_waitcnt lgkmcnt(1)
	v_pk_fma_f32 v[20:21], v[0:1], v[44:45], v[2:3] op_sel_hi:[1,0,1] neg_lo:[0,0,1] neg_hi:[0,0,1]
	ds_read2_b32 v[2:3], v197 offset0:42 offset1:43
	v_pk_mul_f32 v[74:75], v[58:59], v[58:59]
	v_pk_mul_f32 v[80:81], v[20:21], v[20:21]
	s_waitcnt lgkmcnt(1)
	v_pk_fma_f32 v[22:23], v[30:31], v[44:45], v[16:17] op_sel_hi:[1,0,1] neg_lo:[0,0,1] neg_hi:[0,0,1]
	ds_read2_b32 v[16:17], v197 offset0:24 offset1:25
	v_add_f32_e32 v52, v52, v74
	v_add_f32_e32 v52, v52, v75
	s_waitcnt lgkmcnt(1)
	v_pk_fma_f32 v[6:7], v[6:7], v[44:45], v[2:3] op_sel_hi:[1,0,1] neg_lo:[0,0,1] neg_hi:[0,0,1]
	ds_read2_b32 v[2:3], v197 offset0:40 offset1:41
	s_waitcnt lgkmcnt(1)
	v_pk_fma_f32 v[24:25], v[28:29], v[44:45], v[16:17] op_sel_hi:[1,0,1] neg_lo:[0,0,1] neg_hi:[0,0,1]
	v_add_f32_e32 v52, v52, v72
	v_pk_mul_f32 v[76:77], v[24:25], v[24:25]
	v_add_f32_e32 v52, v52, v73
	v_add_f32_e32 v52, v52, v76
	v_pk_mul_f32 v[30:31], v[22:23], v[22:23]
	v_add_f32_e32 v52, v52, v77
	v_add_f32_e32 v30, v52, v30
	v_add_f32_e32 v30, v30, v31
	v_add_f32_e32 v30, v30, v80
	v_lshl_add_u64 v[16:17], s[4:5], 0, v[160:161]
	v_pk_mul_f32 v[28:29], v[18:19], v[18:19]
	v_add_f32_e32 v30, v30, v81
	v_lshl_add_u64 v[0:1], v[16:17], 0, v[164:165]
	s_waitcnt lgkmcnt(0)
	v_pk_fma_f32 v[16:17], v[4:5], v[44:45], v[2:3] op_sel_hi:[1,0,1] neg_lo:[0,0,1] neg_hi:[0,0,1]
	ds_read2_b32 v[2:3], v197 offset0:50 offset1:51
	v_add_f32_e32 v28, v30, v28
	v_pk_mul_f32 v[4:5], v[16:17], v[16:17]
	v_add_f32_e32 v28, v28, v29
	v_add_f32_e32 v4, v28, v4
	v_pk_mul_f32 v[78:79], v[6:7], v[6:7]
	v_add_f32_e32 v4, v4, v5
	v_add_f32_e32 v4, v4, v78
	s_waitcnt lgkmcnt(0)
	v_pk_fma_f32 v[2:3], v[10:11], v[44:45], v[2:3] op_sel_hi:[1,0,1] neg_lo:[0,0,1] neg_hi:[0,0,1]
	v_pk_mul_f32 v[44:45], v[8:9], v[8:9]
	v_add_f32_e32 v4, v4, v79
	v_add_f32_e32 v4, v4, v44
	v_pk_mul_f32 v[10:11], v[2:3], v[2:3]
	v_add_f32_e32 v4, v4, v45
	v_add_f32_e32 v4, v4, v10
	v_add_f32_e32 v4, v4, v11
	v_add_f32_e32 v4, v4, v40
	v_add_f32_e32 v4, v4, v41
	v_add_f32_e32 v4, v4, v42
	v_add_f32_e32 v4, v4, v43
	ds_bpermute_b32 v5, v170, v4
	s_waitcnt lgkmcnt(0)
; DI size_t kblk(int row, int col, int nrows) { return ((size_t)(col >> 5) * nrows + row) * 32 + (col & 31); }
; DI float bf2f(bf16_t v) { return __uint_as_float(((unsigned)v) << 16); }
; DI unsigned pk2(float a, float b) { hwf32x2 f = {a, b}; hwbf16x2 r = __builtin_convertvector(f, hwbf16x2); return __builtin_bit_cast(unsigned, r); }
; DI float siluf_(float z) { return z / (1.f + __expf(-z)); }
; template <int MODE>
; DI void attn_mfma(const Params& p, int l, int b, int hd, int qb, unsigned char* smem) {
;     ...
;       const float rstd = rsqrtf(ss * (1.f / 64.f) + EPS) * (1.f - lam_init);
; #pragma unroll
;       for (int vt = 0; vt < 2; ++vt)
; #pragma unroll
;         for (int g4 = 0; g4 < 4; ++g4) {
;           const int v0 = vt * 32 + 8 * g4 + 4 * h2;
;           const ushort4 gt = *(const ushort4*)(P + qrow * PW + GATE + hd * 64 + v0);
;           const float4 gg = *(const float4*)(p.diff_g + l * 64 + v0);
;           uint2 o;
;           o.x = pk2(O[vt][4 * g4 + 0] * rstd * gg.x * siluf_(bf2f(gt.x)), O[vt][4 * g4 + 1] * rstd * gg.y * siluf_(bf2f(gt.y)));
;           o.y = pk2(O[vt][4 * g4 + 2] * rstd * gg.z * siluf_(bf2f(gt.z)), O[vt][4 * g4 + 3] * rstd * gg.w * siluf_(bf2f(gt.w)));
;           *(uint2*)(MIX + kblk((int)qrow, hd * 64 + v0, ROWS)) = o;
;         }
	v_add_f32_e32 v4, v4, v5
	v_fmamk_f32 v4, v4, 0x3c800000, v162
	v_cmp_gt_f32_e32 vcc, s38, v4
	v_mul_f32_e32 v5, 0x4b800000, v4
	s_nop 0
	v_cndmask_b32_e32 v4, v4, v5, vcc
	v_rsq_f32_e32 v4, v4
	s_nop 0
	v_mul_f32_e32 v5, 0x45800000, v4
	v_cndmask_b32_e32 v4, v4, v5, vcc
	v_mul_f32_e32 v4, v169, v4
	v_pk_mul_f32 v[10:11], v[48:49], v[4:5] op_sel_hi:[1,0]
	s_nop 0
	v_pk_mul_f32 v[10:11], v[12:13], v[10:11]
	v_pk_mul_f32 v[12:13], v[46:47], v[4:5] op_sel_hi:[1,0]
	v_pk_mul_f32 v[10:11], v[50:51], v[10:11]
	v_pk_mul_f32 v[12:13], v[14:15], v[12:13]
	v_cvt_pk_bf16_f32 v10, v10, v11
	v_pk_mul_f32 v[12:13], v[54:55], v[12:13]
	v_pk_mul_f32 v[14:15], v[62:63], v[4:5] op_sel_hi:[1,0]
	v_cvt_pk_bf16_f32 v11, v12, v13
	global_store_dwordx2 v[38:39], v[10:11], off
	s_nop 0
	s_nop 0
	v_mov_b32_e32 v10, v224
	v_mov_b32_e32 v11, v225
	v_mov_b32_e32 v12, v226
	v_mov_b32_e32 v13, v227
	v_pk_mul_f32 v[10:11], v[14:15], v[10:11]
	v_pk_mul_f32 v[14:15], v[60:61], v[4:5] op_sel_hi:[1,0]
	v_pk_mul_f32 v[10:11], v[10:11], v[64:65]
	v_pk_mul_f32 v[12:13], v[14:15], v[12:13]
	v_cvt_pk_bf16_f32 v10, v10, v11
	v_pk_mul_f32 v[12:13], v[12:13], v[66:67]
	s_nop 0
	v_cvt_pk_bf16_f32 v11, v12, v13
	global_store_dwordx2 v[38:39], v[10:11], off offset:16
	s_nop 0
	s_nop 0
	s_nop 0
	s_waitcnt lgkmcnt(0)
	v_mov_b32_e32 v14, v208
	v_mov_b32_e32 v15, v209
	v_mov_b32_e32 v10, v228
	v_mov_b32_e32 v11, v229
	v_mov_b32_e32 v12, v230
	v_mov_b32_e32 v13, v231
	v_and_b32_e32 v5, 0xffff0000, v14
	v_lshlrev_b32_e32 v14, 16, v14
	v_mul_f32_e32 v28, 0xbfb8aa3b, v14
	v_mul_f32_e32 v29, 0xbfb8aa3b, v5
	v_exp_f32_e32 v28, v28
	v_exp_f32_e32 v29, v29
	v_pk_mul_f32 v[30:31], v[58:59], v[4:5] op_sel_hi:[1,0]
	v_pk_add_f32 v[28:29], v[28:29], 1.0 op_sel_hi:[1,0]
	v_pk_mul_f32 v[10:11], v[30:31], v[10:11]
	v_rcp_f32_e32 v31, v29
	s_nop 0
	v_fma_f32 v40, -v29, v31, 1.0
	v_fmac_f32_e32 v31, v40, v31
	v_mul_f32_e32 v41, v5, v31
	v_fma_f32 v42, -v29, v41, v5
	v_fmac_f32_e32 v41, v42, v31
	v_fma_f32 v30, -v29, v41, v5
	v_fma_f32 v30, v30, v31, v41
	v_div_fixup_f32 v29, v30, v29, v5
	v_rcp_f32_e32 v30, v28
	s_nop 0
	v_fma_f32 v31, -v28, v30, 1.0
	v_fmac_f32_e32 v30, v31, v30
	v_mul_f32_e32 v40, v14, v30
	v_fma_f32 v41, -v28, v40, v14
	v_fmac_f32_e32 v40, v41, v30
	v_fma_f32 v5, -v28, v40, v14
	v_fma_f32 v5, v5, v30, v40
	v_div_fixup_f32 v28, v5, v28, v14
	v_pk_mul_f32 v[10:11], v[10:11], v[28:29]
	v_and_b32_e32 v5, 0xffff0000, v15
	v_cvt_pk_bf16_f32 v10, v10, v11
	v_lshlrev_b32_e32 v11, 16, v15
	v_mul_f32_e32 v14, 0xbfb8aa3b, v11
	v_mul_f32_e32 v15, 0xbfb8aa3b, v5
	v_exp_f32_e32 v14, v14
	v_exp_f32_e32 v15, v15
	v_pk_mul_f32 v[26:27], v[26:27], v[4:5] op_sel_hi:[1,0]
	v_pk_add_f32 v[14:15], v[14:15], 1.0 op_sel_hi:[1,0]
	v_pk_mul_f32 v[12:13], v[26:27], v[12:13]
	v_rcp_f32_e32 v27, v15
	s_nop 0
	v_fma_f32 v28, -v15, v27, 1.0
	v_fmac_f32_e32 v27, v28, v27
	v_mul_f32_e32 v29, v5, v27
	v_fma_f32 v30, -v15, v29, v5
	v_fmac_f32_e32 v29, v30, v27
	v_fma_f32 v26, -v15, v29, v5
	v_fma_f32 v26, v26, v27, v29
	v_div_fixup_f32 v15, v26, v15, v5
	v_rcp_f32_e32 v26, v14
	s_nop 0
	v_fma_f32 v27, -v14, v26, 1.0
	v_fmac_f32_e32 v26, v27, v26
	v_mul_f32_e32 v28, v11, v26
	v_fma_f32 v29, -v14, v28, v11
	v_fmac_f32_e32 v28, v29, v26
	v_fma_f32 v5, -v14, v28, v11
	v_fma_f32 v5, v5, v26, v28
	v_div_fixup_f32 v14, v5, v14, v11
	v_pk_mul_f32 v[12:13], v[12:13], v[14:15]
	s_nop 0
	v_cvt_pk_bf16_f32 v11, v12, v13
	global_store_dwordx2 v[38:39], v[10:11], off offset:32
	s_nop 0
	s_nop 0
	s_nop 0
	s_waitcnt lgkmcnt(0)
	v_mov_b32_e32 v14, v210
	v_mov_b32_e32 v15, v211
	v_mov_b32_e32 v10, v232
	v_mov_b32_e32 v11, v233
	v_mov_b32_e32 v12, v234
	v_mov_b32_e32 v13, v235
	v_and_b32_e32 v5, 0xffff0000, v14
	v_lshlrev_b32_e32 v14, 16, v14
	v_pk_mul_f32 v[24:25], v[24:25], v[4:5] op_sel_hi:[1,0]
	v_mul_f32_e32 v26, 0xbfb8aa3b, v14
	v_pk_mul_f32 v[10:11], v[24:25], v[10:11]
	v_mul_f32_e32 v24, 0xbfb8aa3b, v5
	v_exp_f32_e32 v26, v26
	v_exp_f32_e32 v27, v24
	s_nop 0
	v_pk_add_f32 v[24:25], v[26:27], 1.0 op_sel_hi:[1,0]
	s_nop 0
	v_rcp_f32_e32 v27, v25
	s_nop 0
	v_fma_f32 v28, -v25, v27, 1.0
	v_fmac_f32_e32 v27, v28, v27
	v_mul_f32_e32 v29, v5, v27
	v_fma_f32 v30, -v25, v29, v5
	v_fmac_f32_e32 v29, v30, v27
	v_fma_f32 v26, -v25, v29, v5
	v_fma_f32 v26, v26, v27, v29
	v_div_fixup_f32 v25, v26, v25, v5
	v_rcp_f32_e32 v26, v24
	s_nop 0
	v_fma_f32 v27, -v24, v26, 1.0
	v_fmac_f32_e32 v26, v27, v26
	v_mul_f32_e32 v28, v14, v26
	v_fma_f32 v29, -v24, v28, v14
	v_fmac_f32_e32 v28, v29, v26
	v_fma_f32 v5, -v24, v28, v14
	v_fma_f32 v5, v5, v26, v28
	v_div_fixup_f32 v24, v5, v24, v14
	v_pk_mul_f32 v[10:11], v[10:11], v[24:25]
	v_and_b32_e32 v5, 0xffff0000, v15
	v_cvt_pk_bf16_f32 v10, v10, v11
	v_lshlrev_b32_e32 v11, 16, v15
	v_mul_f32_e32 v14, 0xbfb8aa3b, v11
	v_mul_f32_e32 v15, 0xbfb8aa3b, v5
	v_exp_f32_e32 v14, v14
	v_exp_f32_e32 v15, v15
	v_pk_mul_f32 v[22:23], v[22:23], v[4:5] op_sel_hi:[1,0]
	v_pk_add_f32 v[14:15], v[14:15], 1.0 op_sel_hi:[1,0]
	v_pk_mul_f32 v[12:13], v[22:23], v[12:13]
	v_rcp_f32_e32 v23, v15
	s_nop 0
	v_fma_f32 v24, -v15, v23, 1.0
	v_fmac_f32_e32 v23, v24, v23
	v_mul_f32_e32 v25, v5, v23
	v_fma_f32 v26, -v15, v25, v5
	v_fmac_f32_e32 v25, v26, v23
	v_fma_f32 v22, -v15, v25, v5
	v_fma_f32 v22, v22, v23, v25
	v_div_fixup_f32 v15, v22, v15, v5
	v_rcp_f32_e32 v22, v14
	s_nop 0
	v_fma_f32 v23, -v14, v22, 1.0
	v_fmac_f32_e32 v22, v23, v22
	v_mul_f32_e32 v24, v11, v22
	v_fma_f32 v25, -v14, v24, v11
	v_fmac_f32_e32 v24, v25, v22
	v_fma_f32 v5, -v14, v24, v11
	v_fma_f32 v5, v5, v22, v24
	v_div_fixup_f32 v14, v5, v14, v11
	v_pk_mul_f32 v[12:13], v[12:13], v[14:15]
	s_nop 0
	v_cvt_pk_bf16_f32 v11, v12, v13
	global_store_dwordx2 v[38:39], v[10:11], off offset:48
	s_nop 0
	s_nop 0
	s_nop 0
	s_waitcnt lgkmcnt(0)
; DI size_t kblk(int row, int col, int nrows) { return ((size_t)(col >> 5) * nrows + row) * 32 + (col & 31); }
; DI float bf2f(bf16_t v) { return __uint_as_float(((unsigned)v) << 16); }
; DI unsigned pk2(float a, float b) { hwf32x2 f = {a, b}; hwbf16x2 r = __builtin_convertvector(f, hwbf16x2); return __builtin_bit_cast(unsigned, r); }
; DI float siluf_(float z) { return z / (1.f + __expf(-z)); }
; template <int MODE>
; DI void attn_mfma(const Params& p, int l, int b, int hd, int qb, unsigned char* smem) {
;     ...
; #pragma unroll
;       for (int vt = 0; vt < 2; ++vt)
; #pragma unroll
;         for (int g4 = 0; g4 < 4; ++g4) {
;           const int v0 = vt * 32 + 8 * g4 + 4 * h2;
;           const ushort4 gt = *(const ushort4*)(P + qrow * PW + GATE + hd * 64 + v0);
;           const float4 gg = *(const float4*)(p.diff_g + l * 64 + v0);
;           uint2 o;
;           o.x = pk2(O[vt][4 * g4 + 0] * rstd * gg.x * siluf_(bf2f(gt.x)), O[vt][4 * g4 + 1] * rstd * gg.y * siluf_(bf2f(gt.y)));
;           o.y = pk2(O[vt][4 * g4 + 2] * rstd * gg.z * siluf_(bf2f(gt.z)), O[vt][4 * g4 + 3] * rstd * gg.w * siluf_(bf2f(gt.w)));
;           *(uint2*)(MIX + kblk((int)qrow, hd * 64 + v0, ROWS)) = o;
;         }
	v_mov_b32_e32 v10, v212
	v_mov_b32_e32 v11, v213
	v_mov_b32_e32 v12, v236
	v_mov_b32_e32 v13, v237
	v_mov_b32_e32 v14, v238
	v_mov_b32_e32 v15, v239
	v_and_b32_e32 v5, 0xffff0000, v10
	v_lshlrev_b32_e32 v10, 16, v10
	v_pk_mul_f32 v[20:21], v[20:21], v[4:5] op_sel_hi:[1,0]
	v_mul_f32_e32 v22, 0xbfb8aa3b, v10
	v_pk_mul_f32 v[12:13], v[20:21], v[12:13]
	v_mul_f32_e32 v20, 0xbfb8aa3b, v5
	v_exp_f32_e32 v22, v22
	v_exp_f32_e32 v23, v20
	s_nop 0
	v_pk_add_f32 v[20:21], v[22:23], 1.0 op_sel_hi:[1,0]
	s_nop 0
	v_rcp_f32_e32 v23, v21
	s_nop 0
	v_fma_f32 v24, -v21, v23, 1.0
	v_fmac_f32_e32 v23, v24, v23
	v_mul_f32_e32 v25, v5, v23
	v_fma_f32 v26, -v21, v25, v5
	v_fmac_f32_e32 v25, v26, v23
	v_fma_f32 v22, -v21, v25, v5
	v_fma_f32 v22, v22, v23, v25
	v_div_fixup_f32 v21, v22, v21, v5
	v_rcp_f32_e32 v22, v20
	s_nop 0
	v_fma_f32 v23, -v20, v22, 1.0
	v_fmac_f32_e32 v22, v23, v22
	v_mul_f32_e32 v24, v10, v22
	v_fma_f32 v25, -v20, v24, v10
	v_fmac_f32_e32 v24, v25, v22
	v_fma_f32 v5, -v20, v24, v10
	v_fma_f32 v5, v5, v22, v24
	v_div_fixup_f32 v20, v5, v20, v10
	v_pk_mul_f32 v[12:13], v[12:13], v[20:21]
	v_and_b32_e32 v5, 0xffff0000, v11
	v_lshlrev_b32_e32 v11, 16, v11
	v_cvt_pk_bf16_f32 v10, v12, v13
	v_mul_f32_e32 v12, 0xbfb8aa3b, v11
	v_mul_f32_e32 v13, 0xbfb8aa3b, v5
	v_exp_f32_e32 v12, v12
	v_exp_f32_e32 v13, v13
	v_pk_mul_f32 v[18:19], v[18:19], v[4:5] op_sel_hi:[1,0]
	v_pk_add_f32 v[12:13], v[12:13], 1.0 op_sel_hi:[1,0]
	v_pk_mul_f32 v[14:15], v[18:19], v[14:15]
	v_rcp_f32_e32 v19, v13
	s_nop 0
	v_fma_f32 v20, -v13, v19, 1.0
	v_fmac_f32_e32 v19, v20, v19
	v_mul_f32_e32 v21, v5, v19
	v_fma_f32 v22, -v13, v21, v5
	v_fmac_f32_e32 v21, v22, v19
	v_fma_f32 v18, -v13, v21, v5
	v_fma_f32 v18, v18, v19, v21
	v_div_fixup_f32 v13, v18, v13, v5
	v_rcp_f32_e32 v18, v12
	s_nop 0
	v_fma_f32 v19, -v12, v18, 1.0
	v_fmac_f32_e32 v18, v19, v18
	v_mul_f32_e32 v20, v11, v18
	v_fma_f32 v21, -v12, v20, v11
	v_fmac_f32_e32 v20, v21, v18
	v_fma_f32 v5, -v12, v20, v11
	v_fma_f32 v5, v5, v18, v20
	v_div_fixup_f32 v12, v5, v12, v11
	v_pk_mul_f32 v[12:13], v[14:15], v[12:13]
	s_nop 0
	v_cvt_pk_bf16_f32 v11, v12, v13
	global_store_dwordx2 v[0:1], v[10:11], off
	s_nop 0
	s_nop 0
	s_nop 0
	s_waitcnt lgkmcnt(0)
	v_mov_b32_e32 v14, v214
	v_mov_b32_e32 v15, v215
	v_mov_b32_e32 v10, v240
	v_mov_b32_e32 v11, v241
	v_mov_b32_e32 v12, v242
	v_mov_b32_e32 v13, v243
	v_and_b32_e32 v5, 0xffff0000, v14
	v_lshlrev_b32_e32 v14, 16, v14
	v_pk_mul_f32 v[16:17], v[16:17], v[4:5] op_sel_hi:[1,0]
	v_mul_f32_e32 v18, 0xbfb8aa3b, v14
	v_pk_mul_f32 v[10:11], v[16:17], v[10:11]
	v_mul_f32_e32 v16, 0xbfb8aa3b, v5
	v_exp_f32_e32 v18, v18
	v_exp_f32_e32 v19, v16
	s_nop 0
	v_pk_add_f32 v[16:17], v[18:19], 1.0 op_sel_hi:[1,0]
	s_nop 0
	v_rcp_f32_e32 v19, v17
	s_nop 0
	v_fma_f32 v20, -v17, v19, 1.0
	v_fmac_f32_e32 v19, v20, v19
	v_mul_f32_e32 v21, v5, v19
	v_fma_f32 v22, -v17, v21, v5
	v_fmac_f32_e32 v21, v22, v19
	v_fma_f32 v18, -v17, v21, v5
	v_fma_f32 v18, v18, v19, v21
	v_div_fixup_f32 v17, v18, v17, v5
	v_rcp_f32_e32 v18, v16
	s_nop 0
	v_fma_f32 v19, -v16, v18, 1.0
	v_fmac_f32_e32 v18, v19, v18
	v_mul_f32_e32 v20, v14, v18
	v_fma_f32 v21, -v16, v20, v14
	v_fmac_f32_e32 v20, v21, v18
	v_fma_f32 v5, -v16, v20, v14
	v_fma_f32 v5, v5, v18, v20
	v_div_fixup_f32 v16, v5, v16, v14
	v_pk_mul_f32 v[10:11], v[10:11], v[16:17]
	v_and_b32_e32 v5, 0xffff0000, v15
	v_cvt_pk_bf16_f32 v10, v10, v11
	v_lshlrev_b32_e32 v11, 16, v15
	v_pk_mul_f32 v[6:7], v[6:7], v[4:5] op_sel_hi:[1,0]
	v_mul_f32_e32 v14, 0xbfb8aa3b, v11
	v_pk_mul_f32 v[6:7], v[6:7], v[12:13]
	v_mul_f32_e32 v12, 0xbfb8aa3b, v5
	v_exp_f32_e32 v14, v14
	v_exp_f32_e32 v15, v12
	s_nop 0
	v_pk_add_f32 v[12:13], v[14:15], 1.0 op_sel_hi:[1,0]
	s_nop 0
	v_rcp_f32_e32 v15, v13
	s_nop 0
	v_fma_f32 v16, -v13, v15, 1.0
	v_fmac_f32_e32 v15, v16, v15
	v_mul_f32_e32 v17, v5, v15
	v_fma_f32 v18, -v13, v17, v5
	v_fmac_f32_e32 v17, v18, v15
	v_fma_f32 v14, -v13, v17, v5
	v_fma_f32 v14, v14, v15, v17
	v_div_fixup_f32 v13, v14, v13, v5
	v_rcp_f32_e32 v14, v12
	s_nop 0
	v_fma_f32 v15, -v12, v14, 1.0
	v_fmac_f32_e32 v14, v15, v14
	v_mul_f32_e32 v16, v11, v14
	v_fma_f32 v17, -v12, v16, v11
	v_fmac_f32_e32 v16, v17, v14
	v_fma_f32 v5, -v12, v16, v11
	v_fma_f32 v5, v5, v14, v16
	v_div_fixup_f32 v12, v5, v12, v11
	v_pk_mul_f32 v[6:7], v[6:7], v[12:13]
	s_nop 0
	v_cvt_pk_bf16_f32 v11, v6, v7
	global_store_dwordx2 v[0:1], v[10:11], off offset:16
	s_nop 0
	s_nop 0
	s_nop 0
	s_waitcnt lgkmcnt(0)
; DI size_t kblk(int row, int col, int nrows) { return ((size_t)(col >> 5) * nrows + row) * 32 + (col & 31); }
; DI float bf2f(bf16_t v) { return __uint_as_float(((unsigned)v) << 16); }
; DI unsigned pk2(float a, float b) { hwf32x2 f = {a, b}; hwbf16x2 r = __builtin_convertvector(f, hwbf16x2); return __builtin_bit_cast(unsigned, r); }
; DI float siluf_(float z) { return z / (1.f + __expf(-z)); }
; template <int MODE>
; DI void attn_mfma(const Params& p, int l, int b, int hd, int qb, unsigned char* smem) {
;     ...
; #pragma unroll
;       for (int vt = 0; vt < 2; ++vt)
; #pragma unroll
;         for (int g4 = 0; g4 < 4; ++g4) {
;           const int v0 = vt * 32 + 8 * g4 + 4 * h2;
;           const ushort4 gt = *(const ushort4*)(P + qrow * PW + GATE + hd * 64 + v0);
;           const float4 gg = *(const float4*)(p.diff_g + l * 64 + v0);
;           uint2 o;
;           o.x = pk2(O[vt][4 * g4 + 0] * rstd * gg.x * siluf_(bf2f(gt.x)), O[vt][4 * g4 + 1] * rstd * gg.y * siluf_(bf2f(gt.y)));
;           o.y = pk2(O[vt][4 * g4 + 2] * rstd * gg.z * siluf_(bf2f(gt.z)), O[vt][4 * g4 + 3] * rstd * gg.w * siluf_(bf2f(gt.w)));
;           *(uint2*)(MIX + kblk((int)qrow, hd * 64 + v0, ROWS)) = o;
;         }
	v_mov_b32_e32 v6, v216
	v_mov_b32_e32 v7, v217
	v_mov_b32_e32 v10, v244
	v_mov_b32_e32 v11, v245
	v_mov_b32_e32 v12, v246
	v_mov_b32_e32 v13, v247
	v_and_b32_e32 v5, 0xffff0000, v6
	v_lshlrev_b32_e32 v6, 16, v6
	v_pk_mul_f32 v[8:9], v[8:9], v[4:5] op_sel_hi:[1,0]
	v_mul_f32_e32 v14, 0xbfb8aa3b, v6
	v_pk_mul_f32 v[8:9], v[8:9], v[10:11]
	v_mul_f32_e32 v10, 0xbfb8aa3b, v5
	v_exp_f32_e32 v14, v14
	v_exp_f32_e32 v15, v10
	s_nop 0
	v_pk_add_f32 v[10:11], v[14:15], 1.0 op_sel_hi:[1,0]
	s_nop 0
	v_rcp_f32_e32 v15, v11
	s_nop 0
	v_fma_f32 v16, -v11, v15, 1.0
	v_fmac_f32_e32 v15, v16, v15
	v_mul_f32_e32 v17, v5, v15
	v_fma_f32 v18, -v11, v17, v5
	v_fmac_f32_e32 v17, v18, v15
	v_fma_f32 v14, -v11, v17, v5
	v_fma_f32 v14, v14, v15, v17
	v_div_fixup_f32 v11, v14, v11, v5
	v_rcp_f32_e32 v14, v10
	s_nop 0
	v_fma_f32 v15, -v10, v14, 1.0
	v_fmac_f32_e32 v14, v15, v14
	v_mul_f32_e32 v16, v6, v14
	v_fma_f32 v17, -v10, v16, v6
	v_fmac_f32_e32 v16, v17, v14
	v_fma_f32 v5, -v10, v16, v6
	v_fma_f32 v5, v5, v14, v16
	v_div_fixup_f32 v10, v5, v10, v6
	v_pk_mul_f32 v[8:9], v[8:9], v[10:11]
	v_and_b32_e32 v5, 0xffff0000, v7
	v_lshlrev_b32_e32 v7, 16, v7
	v_cvt_pk_bf16_f32 v6, v8, v9
	v_mul_f32_e32 v8, 0xbfb8aa3b, v7
	v_mul_f32_e32 v9, 0xbfb8aa3b, v5
	v_exp_f32_e32 v8, v8
	v_exp_f32_e32 v9, v9
	v_pk_mul_f32 v[2:3], v[2:3], v[4:5] op_sel_hi:[1,0]
	v_pk_add_f32 v[8:9], v[8:9], 1.0 op_sel_hi:[1,0]
	s_nop 0
	v_rcp_f32_e32 v11, v9
	v_pk_mul_f32 v[2:3], v[2:3], v[12:13]
	v_fma_f32 v12, -v9, v11, 1.0
	v_fmac_f32_e32 v11, v12, v11
	v_mul_f32_e32 v13, v5, v11
	v_fma_f32 v14, -v9, v13, v5
	v_fmac_f32_e32 v13, v14, v11
	v_fma_f32 v10, -v9, v13, v5
	v_fma_f32 v10, v10, v11, v13
	v_div_fixup_f32 v9, v10, v9, v5
	v_rcp_f32_e32 v10, v8
	s_nop 0
	v_fma_f32 v11, -v8, v10, 1.0
	v_fmac_f32_e32 v10, v11, v10
	v_mul_f32_e32 v12, v7, v10
	v_fma_f32 v13, -v8, v12, v7
	v_fmac_f32_e32 v12, v13, v10
	v_fma_f32 v5, -v8, v12, v7
	v_fma_f32 v5, v5, v10, v12
	v_div_fixup_f32 v8, v5, v8, v7
	v_pk_mul_f32 v[2:3], v[2:3], v[8:9]
	s_nop 0
	v_cvt_pk_bf16_f32 v7, v2, v3
	global_store_dwordx2 v[0:1], v[6:7], off offset:32
	s_nop 0
	s_nop 0
	s_nop 0
	s_waitcnt lgkmcnt(0)
	v_mov_b32_e32 v2, v218
	v_mov_b32_e32 v3, v219
	v_mov_b32_e32 v6, v248
	v_mov_b32_e32 v7, v249
	v_mov_b32_e32 v8, v250
	v_mov_b32_e32 v9, v251
	v_and_b32_e32 v5, 0xffff0000, v2
	v_lshlrev_b32_e32 v2, 16, v2
	v_mul_f32_e32 v10, 0xbfb8aa3b, v2
	v_mul_f32_e32 v11, 0xbfb8aa3b, v5
	v_exp_f32_e32 v10, v10
	v_exp_f32_e32 v11, v11
	v_pk_mul_f32 v[12:13], v[34:35], v[4:5] op_sel_hi:[1,0]
	v_pk_add_f32 v[10:11], v[10:11], 1.0 op_sel_hi:[1,0]
	v_pk_mul_f32 v[6:7], v[12:13], v[6:7]
	v_rcp_f32_e32 v13, v11
	s_nop 0
	v_fma_f32 v14, -v11, v13, 1.0
	v_fmac_f32_e32 v13, v14, v13
	v_mul_f32_e32 v15, v5, v13
	v_fma_f32 v16, -v11, v15, v5
	v_fmac_f32_e32 v15, v16, v13
	v_fma_f32 v12, -v11, v15, v5
	v_fma_f32 v12, v12, v13, v15
	v_div_fixup_f32 v11, v12, v11, v5
	v_rcp_f32_e32 v12, v10
	s_nop 0
	v_fma_f32 v13, -v10, v12, 1.0
	v_fmac_f32_e32 v12, v13, v12
	v_mul_f32_e32 v14, v2, v12
	v_fma_f32 v15, -v10, v14, v2
	v_fmac_f32_e32 v14, v15, v12
	v_fma_f32 v5, -v10, v14, v2
	v_fma_f32 v5, v5, v12, v14
	v_div_fixup_f32 v10, v5, v10, v2
	v_pk_mul_f32 v[6:7], v[6:7], v[10:11]
	v_and_b32_e32 v10, 0xffff0000, v3
	v_lshlrev_b32_e32 v3, 16, v3
	v_cvt_pk_bf16_f32 v2, v6, v7
	v_mul_f32_e32 v5, 0xbfb8aa3b, v3
	v_mul_f32_e32 v7, 0xbfb8aa3b, v10
	v_exp_f32_e32 v6, v5
	v_exp_f32_e32 v7, v7
	v_pk_mul_f32 v[4:5], v[32:33], v[4:5] op_sel_hi:[1,0]
	v_pk_add_f32 v[6:7], v[6:7], 1.0 op_sel_hi:[1,0]
	v_pk_mul_f32 v[4:5], v[4:5], v[8:9]
	v_rcp_f32_e32 v9, v7
	s_nop 0
	v_fma_f32 v11, -v7, v9, 1.0
	v_fmac_f32_e32 v9, v11, v9
	v_mul_f32_e32 v12, v10, v9
	v_fma_f32 v13, -v7, v12, v10
	v_fmac_f32_e32 v12, v13, v9
	v_fma_f32 v8, -v7, v12, v10
	v_fma_f32 v8, v8, v9, v12
	v_div_fixup_f32 v7, v8, v7, v10
	v_rcp_f32_e32 v9, v6
	s_nop 0
	v_fma_f32 v10, -v6, v9, 1.0
	v_fmac_f32_e32 v9, v10, v9
	v_mul_f32_e32 v11, v3, v9
	v_fma_f32 v12, -v6, v11, v3
	v_fmac_f32_e32 v11, v12, v9
	v_fma_f32 v8, -v6, v11, v3
	v_fma_f32 v8, v8, v9, v11
	v_div_fixup_f32 v6, v8, v6, v3
	v_pk_mul_f32 v[4:5], v[4:5], v[6:7]
	s_nop 0
	v_cvt_pk_bf16_f32 v3, v4, v5
	global_store_dwordx2 v[0:1], v[2:3], off offset:48

; DI size_t kblk(int row, int col, int nrows) { return ((size_t)(col >> 5) * nrows + row) * 32 + (col & 31); }
; DI unsigned pk2(float a, float b) { hwf32x2 f = {a, b}; hwbf16x2 r = __builtin_convertvector(f, hwbf16x2); return __builtin_bit_cast(unsigned, r); }
; #define MFMA16(a, b, c) __builtin_amdgcn_mfma_f32_16x16x32_bf16((a), (b), (c), 0, 0, 0)
; template <int MX, bool OUT>
; DI void rec_chunk(const Params& p, int l, int b, int h, int dir, int T0, unsigned char* smem, f32x4 (&St)[4], float& nst, float& dtot, int tid, const RecRaw& raw) {
;     ...
; #pragma unroll
;     for (int ks = 0; ks < 2; ++ks) {
;       const bf16x8 fb = *(const bf16x8*)(smem + L_QS + swz(t, ks * 4 + g));
; #pragma unroll
;       for (int a = 0; a < 4; ++a) {
;         const bf16x8 fa = *(const bf16x8*)(smem + L_STT + swz(16 * a + col, ks * 4 + g));
;         O[a] = MFMA16(fa, fb, O[a]);
;       }
;     }
;     if (MX == 1) {
;       const float inv = 1.f / fmaxf(fabsf(den), 1.f);
; #pragma unroll
;       for (int a = 0; a < 4; ++a)
; #pragma unroll
;         for (int j = 0; j < 4; ++j) O[a][j] *= inv;
;     }
;     if (dir == 0) {
; #pragma unroll
;       for (int a = 0; a < 4; ++a) *(uint2*)(MIX + kblk((int)orow, cb + 16 * a + 4 * g, ROWS)) = make_uint2(pk2(O[a][0], O[a][1]), pk2(O[a][2], O[a][3]));
;     } else {
;       float ss = 0.f;
; #pragma unroll
;       for (int a = 0; a < 4; ++a) {
;         const uint2 u = *(const uint2*)(MIX + kblk((int)orow, cb + 16 * a + 4 * g, ROWS));
;         O[a][0] += __uint_as_float(u.x << 16); O[a][1] += __uint_as_float(u.x & 0xffff0000u);
;         O[a][2] += __uint_as_float(u.y << 16); O[a][3] += __uint_as_float(u.y & 0xffff0000u);
.LBB0_683:
	s_or_b64 exec, exec, s[0:1]
	ds_read_b128 v[42:45], v240 offset:32768
	ds_read_b128 v[46:49], v238 offset:57344
	ds_read_b128 v[50:53], v238 offset:59392
	s_add_i32 s0, s13, -1
	v_mov_b32_e32 v40, s0
	v_cndmask_b32_e64 v40, v91, v40, s[24:25]
	s_waitcnt lgkmcnt(1)
	v_mfma_f32_16x16x32_bf16 v[46:49], v[46:49], v[42:45], v[56:59]
	v_lshlrev_b32_e32 v40, 6, v40
	v_add_u32_e32 v160, s12, v40
	v_lshl_add_u64 v[40:41], v[160:161], 0, v[82:83]
	ds_read_b128 v[54:57], v238 offset:61440
	s_waitcnt lgkmcnt(1)
	v_mfma_f32_16x16x32_bf16 v[50:53], v[50:53], v[42:45], v[60:63]
	s_nop 2
	ds_read_b128 v[58:61], v238 offset:63488
	s_waitcnt lgkmcnt(1)
	v_mfma_f32_16x16x32_bf16 v[54:57], v[54:57], v[42:45], v[64:67]
	s_waitcnt lgkmcnt(0)
	v_mfma_f32_16x16x32_bf16 v[42:45], v[58:61], v[42:45], v[72:75]
	ds_read_b128 v[58:61], v239 offset:32768
	ds_read_b128 v[62:65], v237 offset:57344
	s_waitcnt lgkmcnt(0)
	v_mfma_f32_16x16x32_bf16 v[46:49], v[62:65], v[58:61], v[46:49]
	ds_read_b128 v[62:65], v237 offset:59392
	s_waitcnt lgkmcnt(0)
	v_mfma_f32_16x16x32_bf16 v[50:53], v[62:65], v[58:61], v[50:53]
	ds_read_b128 v[62:65], v237 offset:61440
	s_waitcnt lgkmcnt(0)
	v_mfma_f32_16x16x32_bf16 v[62:65], v[62:65], v[58:61], v[54:57]
	s_nop 2
	ds_read_b128 v[54:57], v237 offset:63488
	s_waitcnt lgkmcnt(0)
	v_mfma_f32_16x16x32_bf16 v[42:45], v[54:57], v[58:61], v[42:45]
	v_add_f32_e32 v54, v93, v96
	v_max_f32_e64 v54, |v54|, 1.0
	v_rcp_f32_e32 v56, v54
	s_mov_b64 s[0:1], -1
	v_fma_f32 v57, -v54, v56, 1.0
	v_fmac_f32_e32 v56, v57, v56
	v_mul_f32_e32 v58, 1.0, v56
	v_fma_f32 v59, -v54, v58, 1.0
	v_fmac_f32_e32 v58, v59, v56
	v_fma_f32 v55, -v54, v58, 1.0
	v_fma_f32 v55, v55, v56, v58
	v_div_fixup_f32 v60, v55, v54, 1.0
	v_pk_mul_f32 v[54:55], v[60:61], v[46:47] op_sel_hi:[0,1]
	v_pk_mul_f32 v[46:47], v[60:61], v[42:43] op_sel_hi:[0,1]
	v_ashrrev_i32_e32 v43, 31, v40
	v_mov_b32_e32 v42, v40
	v_pk_mul_f32 v[58:59], v[60:61], v[48:49] op_sel_hi:[0,1]
	v_pk_mul_f32 v[50:51], v[60:61], v[50:51] op_sel_hi:[0,1]
	v_pk_mul_f32 v[56:57], v[60:61], v[52:53] op_sel_hi:[0,1]
	v_pk_mul_f32 v[48:49], v[60:61], v[62:63] op_sel_hi:[0,1]
	v_pk_mul_f32 v[52:53], v[60:61], v[64:65] op_sel_hi:[0,1]
	v_pk_mul_f32 v[44:45], v[60:61], v[44:45] op_sel_hi:[0,1]
	v_lshl_add_u64 v[60:61], v[42:43], 0, s[28:29]
	v_lshl_add_u64 v[62:63], v[42:43], 0, s[30:31]
	v_lshl_add_u64 v[42:43], v[42:43], 0, s[42:43]
	s_andn2_b64 vcc, exec, s[44:45]
	v_lshlrev_b64 v[64:65], 6, v[60:61]
	v_lshlrev_b64 v[62:63], 6, v[62:63]
	v_lshlrev_b64 v[60:61], 6, v[42:43]
	s_cbranch_vccnz .LBB0_685
	v_lshl_add_u64 v[98:99], v[88:89], 0, v[62:63]
	global_load_dwordx2 v[66:67], v[98:99], off
	v_mov_b64_e32 v[42:43], s[18:19]
	v_mad_u64_u32 v[42:43], s[0:1], v40, s33, v[42:43]
	v_mad_i32_i24 v43, v41, s33, v43
	s_mov_b64 s[0:1], 0x1a20
	v_mov_b32_e32 v91, v161
	v_lshl_add_u64 v[74:75], v[42:43], 0, s[0:1]
	v_lshl_add_u64 v[100:101], v[74:75], 0, s[2:3]
	v_lshl_add_u64 v[74:75], v[74:75], 0, v[90:91]
	v_lshl_add_u64 v[102:103], v[84:85], 0, v[64:65]
	v_lshl_add_u64 v[74:75], v[74:75], 0, s[2:3]
	global_load_dwordx2 v[40:41], v[102:103], off
	s_mov_b32 s21, s3
	v_lshl_add_u64 v[42:43], v[42:43], 0, s[20:21]
	v_lshl_add_u64 v[42:43], v[42:43], 0, v[90:91]
	s_mov_b64 s[0:1], 0x1820
	v_lshl_add_u64 v[100:101], v[100:101], 0, v[90:91]
	global_load_dwordx2 v[74:75], v[74:75], off
	s_waitcnt vmcnt(0) lgkmcnt(0)
	v_lshlrev_b32_e32 v96, 16, v66
	v_and_b32_e32 v97, 0xffff0000, v66
	v_lshlrev_b32_e32 v104, 16, v67
	v_and_b32_e32 v105, 0xffff0000, v67
	v_lshl_add_u64 v[66:67], s[22:23], 0, v[60:61]
	v_lshl_add_u64 v[72:73], v[66:67], 0, v[90:91]
	global_load_dwordx2 v[68:69], v[72:73], off
	v_pk_add_f32 v[246:247], v[50:51], v[96:97]
	v_lshlrev_b32_e32 v124, 16, v40
	v_and_b32_e32 v125, 0xffff0000, v40
	v_lshlrev_b32_e32 v40, 16, v41
	v_and_b32_e32 v41, 0xffff0000, v41
	v_pk_add_f32 v[124:125], v[54:55], v[124:125]
	v_pk_mul_f32 v[96:97], v[246:247], v[246:247]
	v_lshlrev_b32_e32 v93, 16, v74
	v_and_b32_e32 v160, 0xffff0000, v74
	v_lshlrev_b32_e32 v126, 16, v75
	v_and_b32_e32 v127, 0xffff0000, v75
	v_lshl_add_u64 v[74:75], v[42:43], 0, s[0:1]
	v_add_co_u32_e32 v42, vcc, s16, v42
	v_mul_f32_e32 v116, 0xbfb8aa3b, v126
	s_nop 0
	v_addc_co_u32_e32 v43, vcc, 0, v43, vcc
	v_mul_f32_e32 v117, 0xbfb8aa3b, v127
	global_load_dwordx2 v[42:43], v[42:43], off offset:2080
	v_exp_f32_e32 v116, v116
	v_exp_f32_e32 v117, v117
	s_waitcnt vmcnt(0) lgkmcnt(0)
; DI size_t kblk(int row, int col, int nrows) { return ((size_t)(col >> 5) * nrows + row) * 32 + (col & 31); }
; DI unsigned pk2(float a, float b) { hwf32x2 f = {a, b}; hwbf16x2 r = __builtin_convertvector(f, hwbf16x2); return __builtin_bit_cast(unsigned, r); }
; DI float sigmoidf_(float z) { return 1.f / (1.f + __expf(-z)); }
; DI float siluf_(float z) { return z / (1.f + __expf(-z)); }
; template <int MX, bool OUT>
; DI void rec_chunk(const Params& p, int l, int b, int h, int dir, int T0, unsigned char* smem, f32x4 (&St)[4], float& nst, float& dtot, int tid, const RecRaw& raw) {
;     ...
;       float ss = 0.f;
; #pragma unroll
;       for (int a = 0; a < 4; ++a) {
;         const uint2 u = *(const uint2*)(MIX + kblk((int)orow, cb + 16 * a + 4 * g, ROWS));
;         O[a][0] += __uint_as_float(u.x << 16); O[a][1] += __uint_as_float(u.x & 0xffff0000u);
;         O[a][2] += __uint_as_float(u.y << 16); O[a][3] += __uint_as_float(u.y & 0xffff0000u);
; #pragma unroll
;         for (int j = 0; j < 4; ++j) ss += O[a][j] * O[a][j];
;       }
;       ss += __shfl_xor(ss, 16);
;       ss += __shfl_xor(ss, 32);
;       const float rstd = rsqrtf(ss * (1.f / 64.f) + EPS);
;       const float* gvec = (MX ? p.ml_g : p.hg_g) + l * 64;
; #pragma unroll
;       for (int a = 0; a < 4; ++a) {
;         const int v0 = 16 * a + 4 * g;
;         const uint2 gt = *(const uint2*)(prow + GATE + cb + v0);
;         const float4 gg = *(const float4*)(gvec + v0);
;         float y0 = O[a][0] * rstd * gg.x * siluf_(__uint_as_float(gt.x << 16));
;         float y1 = O[a][1] * rstd * gg.y * siluf_(__uint_as_float(gt.x & 0xffff0000u));
;         float y2 = O[a][2] * rstd * gg.z * siluf_(__uint_as_float(gt.y << 16));
;         float y3 = O[a][3] * rstd * gg.w * siluf_(__uint_as_float(gt.y & 0xffff0000u));
;         if (MX == 1) {
;           const uint2 og = *(const uint2*)(prow + D_OG + h * 64 + v0);
;           y0 *= sigmoidf_(__uint_as_float(og.x << 16)); y1 *= sigmoidf_(__uint_as_float(og.x & 0xffff0000u));
;           y2 *= sigmoidf_(__uint_as_float(og.y << 16)); y3 *= sigmoidf_(__uint_as_float(og.y & 0xffff0000u));
;         }
;         *(uint2*)(MIX + kblk((int)orow, cb + v0, ROWS)) = make_uint2(pk2(y0, y1), pk2(y2, y3));
	v_lshlrev_b32_e32 v106, 16, v68
	v_and_b32_e32 v107, 0xffff0000, v68
	v_pk_add_f32 v[116:117], v[116:117], 1.0 op_sel_hi:[1,0]
	v_lshlrev_b32_e32 v108, 16, v69
	v_rcp_f32_e32 v70, v116
	v_rcp_f32_e32 v71, v117
	s_nop 0
	v_pk_fma_f32 v[112:113], v[116:117], v[70:71], 1.0 op_sel_hi:[1,1,0] neg_lo:[1,0,0] neg_hi:[1,0,0]
	v_pk_fma_f32 v[70:71], v[112:113], v[70:71], v[70:71]
	v_pk_mul_f32 v[110:111], v[126:127], v[70:71]
	v_pk_fma_f32 v[112:113], v[116:117], v[110:111], v[126:127] neg_lo:[1,0,0] neg_hi:[1,0,0]
	v_pk_fma_f32 v[110:111], v[112:113], v[70:71], v[110:111]
	v_pk_fma_f32 v[112:113], v[116:117], v[110:111], v[126:127] neg_lo:[1,0,0] neg_hi:[1,0,0]
	v_pk_fma_f32 v[110:111], v[112:113], v[70:71], v[110:111]
	v_div_fixup_f32 v116, v110, v116, v126
	v_div_fixup_f32 v117, v111, v117, v127
	v_and_b32_e32 v109, 0xffff0000, v69
	global_load_dwordx2 v[68:69], v[72:73], off offset:32
	v_pk_add_f32 v[106:107], v[48:49], v[106:107]
	v_pk_mul_f32 v[248:249], v[106:107], v[106:107]
	v_lshlrev_b32_e32 v114, 16, v42
	v_and_b32_e32 v42, 0xffff0000, v42
	v_mul_f32_e32 v128, 0xbfb8aa3b, v93
	v_mul_f32_e32 v129, 0xbfb8aa3b, v160
	v_exp_f32_e32 v128, v128
	v_exp_f32_e32 v129, v129
	v_pk_mul_f32 v[126:127], v[124:125], v[124:125]
	v_mul_f32_e32 v114, 0xbfb8aa3b, v114
	v_pk_add_f32 v[128:129], v[128:129], 1.0 op_sel_hi:[1,0]
	v_mul_f32_e32 v42, 0xbfb8aa3b, v42
	v_mov_b32_e32 v118, v93
	v_mov_b32_e32 v119, v160
	v_rcp_f32_e32 v70, v128
	v_rcp_f32_e32 v71, v129
	s_nop 0
	v_pk_fma_f32 v[112:113], v[128:129], v[70:71], 1.0 op_sel_hi:[1,1,0] neg_lo:[1,0,0] neg_hi:[1,0,0]
	v_pk_fma_f32 v[70:71], v[112:113], v[70:71], v[70:71]
	v_pk_mul_f32 v[110:111], v[118:119], v[70:71]
	v_pk_fma_f32 v[112:113], v[128:129], v[110:111], v[118:119] neg_lo:[1,0,0] neg_hi:[1,0,0]
	v_pk_fma_f32 v[110:111], v[112:113], v[70:71], v[110:111]
	v_pk_fma_f32 v[112:113], v[128:129], v[110:111], v[118:119] neg_lo:[1,0,0] neg_hi:[1,0,0]
	v_pk_fma_f32 v[110:111], v[112:113], v[70:71], v[110:111]
	v_div_fixup_f32 v128, v110, v128, v93
	v_div_fixup_f32 v129, v111, v129, v160
	v_add_f32_e32 v91, v126, v127
	v_exp_f32_e32 v122, v114
	v_exp_f32_e32 v123, v42
	v_lshlrev_b32_e32 v42, 16, v43
	v_pk_add_f32 v[114:115], v[58:59], v[40:41]
	v_mul_f32_e32 v42, 0xbfb8aa3b, v42
	v_pk_mul_f32 v[118:119], v[114:115], v[114:115]
	v_exp_f32_e32 v120, v42
	v_and_b32_e32 v42, 0xffff0000, v43
	v_add_f32_e32 v91, v91, v118
	v_mul_f32_e32 v42, 0xbfb8aa3b, v42
	v_add_f32_e32 v91, v119, v91
	v_pk_add_f32 v[122:123], v[122:123], 1.0 op_sel_hi:[1,0]
	v_exp_f32_e32 v121, v42
	global_load_dwordx4 v[40:43], v[86:87], off
	v_rcp_f32_e32 v70, v122
	v_rcp_f32_e32 v71, v123
	s_nop 0
	v_pk_fma_f32 v[112:113], v[122:123], v[70:71], 1.0 op_sel_hi:[1,1,0] neg_lo:[1,0,0] neg_hi:[1,0,0]
	v_pk_fma_f32 v[70:71], v[112:113], v[70:71], v[70:71]
	v_pk_mul_f32 v[110:111], v[70:71], 1.0 op_sel_hi:[1,0]
	v_pk_fma_f32 v[112:113], v[122:123], v[110:111], 1.0 op_sel_hi:[1,1,0] neg_lo:[1,0,0] neg_hi:[1,0,0]
	v_pk_fma_f32 v[110:111], v[112:113], v[70:71], v[110:111]
	v_pk_fma_f32 v[112:113], v[122:123], v[110:111], 1.0 op_sel_hi:[1,1,0] neg_lo:[1,0,0] neg_hi:[1,0,0]
	v_pk_fma_f32 v[110:111], v[112:113], v[70:71], v[110:111]
	v_div_fixup_f32 v122, v110, v122, 1.0
	v_div_fixup_f32 v123, v111, v123, 1.0
	v_pk_add_f32 v[120:121], v[120:121], 1.0 op_sel_hi:[1,0]
	v_add_f32_e32 v91, v96, v91
	v_add_f32_e32 v91, v97, v91
	s_waitcnt vmcnt(0) lgkmcnt(0)
	v_lshlrev_b32_e32 v70, 16, v68
	v_and_b32_e32 v71, 0xffff0000, v68
	v_pk_add_f32 v[70:71], v[46:47], v[70:71]
	v_rcp_f32_e32 v110, v120
	v_rcp_f32_e32 v111, v121
	s_nop 0
	v_pk_fma_f32 v[242:243], v[120:121], v[110:111], 1.0 op_sel_hi:[1,1,0] neg_lo:[1,0,0] neg_hi:[1,0,0]
	v_pk_fma_f32 v[110:111], v[242:243], v[110:111], v[110:111]
	v_pk_mul_f32 v[112:113], v[110:111], 1.0 op_sel_hi:[1,0]
	v_pk_fma_f32 v[242:243], v[120:121], v[112:113], 1.0 op_sel_hi:[1,1,0] neg_lo:[1,0,0] neg_hi:[1,0,0]
	v_pk_fma_f32 v[112:113], v[242:243], v[110:111], v[112:113]
	v_pk_fma_f32 v[242:243], v[120:121], v[112:113], 1.0 op_sel_hi:[1,1,0] neg_lo:[1,0,0] neg_hi:[1,0,0]
	v_pk_fma_f32 v[112:113], v[242:243], v[110:111], v[112:113]
	v_div_fixup_f32 v120, v112, v120, 1.0
	v_div_fixup_f32 v121, v113, v121, 1.0
	v_lshlrev_b32_e32 v68, 16, v69
	v_and_b32_e32 v69, 0xffff0000, v69
	v_pk_mul_f32 v[110:111], v[70:71], v[70:71]
	v_pk_add_f32 v[68:69], v[44:45], v[68:69]
	v_pk_add_f32 v[242:243], v[56:57], v[104:105]
	v_pk_add_f32 v[104:105], v[52:53], v[108:109]
	v_pk_mul_f32 v[244:245], v[242:243], v[242:243]
	v_pk_mul_f32 v[108:109], v[104:105], v[104:105]
	v_add_f32_e32 v91, v244, v91
	v_add_f32_e32 v91, v245, v91
	v_add_f32_e32 v91, v248, v91
	v_add_f32_e32 v91, v249, v91
	v_add_f32_e32 v91, v108, v91
	v_add_f32_e32 v91, v109, v91
	v_add_f32_e32 v91, v110, v91
	v_pk_mul_f32 v[112:113], v[68:69], v[68:69]
	v_add_f32_e32 v91, v111, v91
	v_add_f32_e32 v91, v112, v91
	v_add_f32_e32 v91, v113, v91
	ds_bpermute_b32 v93, v145, v91
	s_waitcnt lgkmcnt(0)
	v_add_f32_e32 v91, v91, v93
	ds_bpermute_b32 v93, v146, v91
	s_waitcnt lgkmcnt(0)
	v_add_f32_e32 v91, v91, v93
	v_fmamk_f32 v91, v91, 0x3c800000, v162
	v_cmp_gt_f32_e32 vcc, s38, v91
	v_mul_f32_e32 v93, 0x4b800000, v91
	s_nop 0
	v_cndmask_b32_e32 v91, v91, v93, vcc
	v_rsq_f32_e32 v91, v91
	s_nop 0
	v_mul_f32_e32 v93, 0x45800000, v91
	v_cndmask_b32_e32 v96, v91, v93, vcc
	v_pk_mul_f32 v[108:109], v[124:125], v[96:97] op_sel_hi:[1,0]
	s_nop 0
	v_pk_mul_f32 v[40:41], v[40:41], v[108:109]
	v_pk_mul_f32 v[108:109], v[114:115], v[96:97] op_sel_hi:[1,0]
	v_pk_mul_f32 v[40:41], v[128:129], v[40:41]
	v_pk_mul_f32 v[42:43], v[42:43], v[108:109]
	v_pk_mul_f32 v[40:41], v[122:123], v[40:41]
	v_pk_mul_f32 v[42:43], v[116:117], v[42:43]
	v_cvt_pk_bf16_f32 v40, v40, v41
	v_pk_mul_f32 v[42:43], v[120:121], v[42:43]
	s_nop 0
	v_cvt_pk_bf16_f32 v41, v42, v43
	global_store_dwordx2 v[102:103], v[40:41], off
	global_load_dwordx2 v[40:41], v[100:101], off offset:32
	s_nop 0
	global_load_dwordx4 v[108:111], v[86:87], off offset:64
	v_pk_mul_f32 v[102:103], v[246:247], v[96:97] op_sel_hi:[1,0]
	s_waitcnt vmcnt(0) lgkmcnt(0)
; DI size_t kblk(int row, int col, int nrows) { return ((size_t)(col >> 5) * nrows + row) * 32 + (col & 31); }
; DI unsigned pk2(float a, float b) { hwf32x2 f = {a, b}; hwbf16x2 r = __builtin_convertvector(f, hwbf16x2); return __builtin_bit_cast(unsigned, r); }
; DI float sigmoidf_(float z) { return 1.f / (1.f + __expf(-z)); }
; DI float siluf_(float z) { return z / (1.f + __expf(-z)); }
; template <int MX, bool OUT>
; DI void rec_chunk(const Params& p, int l, int b, int h, int dir, int T0, unsigned char* smem, f32x4 (&St)[4], float& nst, float& dtot, int tid, const RecRaw& raw) {
;     ...
;       for (int a = 0; a < 4; ++a) {
;         const int v0 = 16 * a + 4 * g;
;         const uint2 gt = *(const uint2*)(prow + GATE + cb + v0);
;         const float4 gg = *(const float4*)(gvec + v0);
;         float y0 = O[a][0] * rstd * gg.x * siluf_(__uint_as_float(gt.x << 16));
;         float y1 = O[a][1] * rstd * gg.y * siluf_(__uint_as_float(gt.x & 0xffff0000u));
;         float y2 = O[a][2] * rstd * gg.z * siluf_(__uint_as_float(gt.y << 16));
;         float y3 = O[a][3] * rstd * gg.w * siluf_(__uint_as_float(gt.y & 0xffff0000u));
;         if (MX == 1) {
;           const uint2 og = *(const uint2*)(prow + D_OG + h * 64 + v0);
;           y0 *= sigmoidf_(__uint_as_float(og.x << 16)); y1 *= sigmoidf_(__uint_as_float(og.x & 0xffff0000u));
;           y2 *= sigmoidf_(__uint_as_float(og.y << 16)); y3 *= sigmoidf_(__uint_as_float(og.y & 0xffff0000u));
;         }
;         *(uint2*)(MIX + kblk((int)orow, cb + v0, ROWS)) = make_uint2(pk2(y0, y1), pk2(y2, y3));
	v_lshlrev_b32_e32 v91, 16, v40
	v_and_b32_e32 v40, 0xffff0000, v40
	v_mul_f32_e32 v42, 0xbfb8aa3b, v91
	v_mul_f32_e32 v43, 0xbfb8aa3b, v40
	v_exp_f32_e32 v42, v42
	v_exp_f32_e32 v43, v43
	v_pk_mul_f32 v[102:103], v[108:109], v[102:103]
	v_pk_add_f32 v[42:43], v[42:43], 1.0 op_sel_hi:[1,0]
	s_nop 0
	v_rcp_f32_e32 v97, v43
	s_nop 0
	v_fma_f32 v108, -v43, v97, 1.0
	v_fmac_f32_e32 v97, v108, v97
	v_mul_f32_e32 v109, v40, v97
	v_fma_f32 v112, -v43, v109, v40
	v_fmac_f32_e32 v109, v112, v97
	v_fma_f32 v93, -v43, v109, v40
	v_fma_f32 v93, v93, v97, v109
	v_div_fixup_f32 v43, v93, v43, v40
	v_rcp_f32_e32 v93, v42
	s_nop 0
	v_fma_f32 v97, -v42, v93, 1.0
	v_fmac_f32_e32 v93, v97, v93
	v_mul_f32_e32 v108, v91, v93
	v_fma_f32 v109, -v42, v108, v91
	v_fmac_f32_e32 v108, v109, v93
	v_fma_f32 v40, -v42, v108, v91
	v_fma_f32 v40, v40, v93, v108
	v_div_fixup_f32 v42, v40, v42, v91
	v_lshlrev_b32_e32 v91, 16, v41
	v_and_b32_e32 v93, 0xffff0000, v41
	v_mul_f32_e32 v40, 0xbfb8aa3b, v91
	v_mul_f32_e32 v41, 0xbfb8aa3b, v93
	v_exp_f32_e32 v40, v40
	v_exp_f32_e32 v41, v41
	v_pk_mul_f32 v[42:43], v[42:43], v[102:103]
	v_pk_mul_f32 v[102:103], v[242:243], v[96:97] op_sel_hi:[1,0]
	v_pk_add_f32 v[40:41], v[40:41], 1.0 op_sel_hi:[1,0]
	s_nop 0
	v_rcp_f32_e32 v108, v41
	v_pk_mul_f32 v[102:103], v[110:111], v[102:103]
	v_fma_f32 v109, -v41, v108, 1.0
	v_fmac_f32_e32 v108, v109, v108
	v_mul_f32_e32 v110, v93, v108
	v_fma_f32 v111, -v41, v110, v93
	v_fmac_f32_e32 v110, v111, v108
	v_fma_f32 v97, -v41, v110, v93
	v_fma_f32 v97, v97, v108, v110
	v_div_fixup_f32 v41, v97, v41, v93
	v_rcp_f32_e32 v97, v40
	s_nop 0
	v_fma_f32 v108, -v40, v97, 1.0
	v_fmac_f32_e32 v97, v108, v97
	v_mul_f32_e32 v109, v91, v97
	v_fma_f32 v110, -v40, v109, v91
	v_fmac_f32_e32 v109, v110, v97
	v_fma_f32 v93, -v40, v109, v91
	v_fma_f32 v93, v93, v97, v109
	v_div_fixup_f32 v40, v93, v40, v91
	v_pk_mul_f32 v[40:41], v[40:41], v[102:103]
	global_load_dwordx2 v[102:103], v[74:75], off offset:32
	s_waitcnt vmcnt(0) lgkmcnt(0)
	v_lshlrev_b32_e32 v91, 16, v102
	v_mul_f32_e32 v91, 0xbfb8aa3b, v91
	v_exp_f32_e32 v108, v91
	v_and_b32_e32 v91, 0xffff0000, v102
	v_mul_f32_e32 v91, 0xbfb8aa3b, v91
	v_exp_f32_e32 v109, v91
	s_nop 0
	v_pk_add_f32 v[108:109], v[108:109], 1.0 op_sel_hi:[1,0]
	s_nop 0
	v_rcp_f32_e32 v93, v109
	s_nop 0
	v_fma_f32 v97, -v109, v93, 1.0
	v_fmac_f32_e32 v93, v97, v93
	v_mul_f32_e32 v102, 1.0, v93
	v_fma_f32 v110, -v109, v102, 1.0
	v_fmac_f32_e32 v102, v110, v93
	v_fma_f32 v91, -v109, v102, 1.0
	v_fma_f32 v91, v91, v93, v102
	v_div_fixup_f32 v109, v91, v109, 1.0
	v_rcp_f32_e32 v93, v108
	s_nop 0
	v_fma_f32 v97, -v108, v93, 1.0
	v_fmac_f32_e32 v93, v97, v93
	v_mul_f32_e32 v102, 1.0, v93
	v_fma_f32 v110, -v108, v102, 1.0
	v_fmac_f32_e32 v102, v110, v93
	v_fma_f32 v91, -v108, v102, 1.0
	v_fma_f32 v91, v91, v93, v102
	v_div_fixup_f32 v108, v91, v108, 1.0
	v_lshlrev_b32_e32 v91, 16, v103
	v_mul_f32_e32 v91, 0xbfb8aa3b, v91
	v_exp_f32_e32 v102, v91
	v_and_b32_e32 v91, 0xffff0000, v103
	v_mul_f32_e32 v91, 0xbfb8aa3b, v91
	v_exp_f32_e32 v103, v91
	v_pk_mul_f32 v[42:43], v[42:43], v[108:109]
	v_pk_add_f32 v[102:103], v[102:103], 1.0 op_sel_hi:[1,0]
	s_nop 0
	v_rcp_f32_e32 v93, v103
	v_cvt_pk_bf16_f32 v42, v42, v43
	v_fma_f32 v97, -v103, v93, 1.0
	v_fmac_f32_e32 v93, v97, v93
	v_mul_f32_e32 v108, 1.0, v93
	v_fma_f32 v109, -v103, v108, 1.0
	v_fmac_f32_e32 v108, v109, v93
	v_fma_f32 v91, -v103, v108, 1.0
	v_fma_f32 v91, v91, v93, v108
	v_div_fixup_f32 v103, v91, v103, 1.0
	v_rcp_f32_e32 v93, v102
	s_nop 0
	v_fma_f32 v97, -v102, v93, 1.0
	v_fmac_f32_e32 v93, v97, v93
	v_mul_f32_e32 v108, 1.0, v93
	v_fma_f32 v109, -v102, v108, 1.0
	v_fmac_f32_e32 v108, v109, v93
	v_fma_f32 v91, -v102, v108, 1.0
	v_fma_f32 v91, v91, v93, v108
	v_div_fixup_f32 v102, v91, v102, 1.0
	v_pk_mul_f32 v[40:41], v[40:41], v[102:103]
	s_nop 0
	v_cvt_pk_bf16_f32 v43, v40, v41
	global_store_dwordx2 v[98:99], v[42:43], off
	global_load_dwordx2 v[40:41], v[100:101], off offset:64
	global_load_dwordx4 v[108:111], v[86:87], off offset:128
	v_pk_mul_f32 v[98:99], v[106:107], v[96:97] op_sel_hi:[1,0]
	s_waitcnt vmcnt(0) lgkmcnt(0)
	v_lshlrev_b32_e32 v91, 16, v40
	v_and_b32_e32 v40, 0xffff0000, v40
	v_mul_f32_e32 v42, 0xbfb8aa3b, v91
	v_mul_f32_e32 v43, 0xbfb8aa3b, v40
	v_exp_f32_e32 v42, v42
	v_exp_f32_e32 v43, v43
	v_pk_mul_f32 v[98:99], v[98:99], v[108:109]
	v_pk_add_f32 v[42:43], v[42:43], 1.0 op_sel_hi:[1,0]
	s_nop 0
	v_rcp_f32_e32 v97, v43
	s_nop 0
	v_fma_f32 v102, -v43, v97, 1.0
	v_fmac_f32_e32 v97, v102, v97
	v_mul_f32_e32 v103, v40, v97
	v_fma_f32 v106, -v43, v103, v40
	v_fmac_f32_e32 v103, v106, v97
	v_fma_f32 v93, -v43, v103, v40
	v_fma_f32 v93, v93, v97, v103
	v_div_fixup_f32 v43, v93, v43, v40
	v_rcp_f32_e32 v93, v42
	s_nop 0
	v_fma_f32 v97, -v42, v93, 1.0
	v_fmac_f32_e32 v93, v97, v93
	v_mul_f32_e32 v102, v91, v93
	v_fma_f32 v103, -v42, v102, v91
	v_fmac_f32_e32 v102, v103, v93
	v_fma_f32 v40, -v42, v102, v91
	v_fma_f32 v40, v40, v93, v102
	v_div_fixup_f32 v42, v40, v42, v91
	v_lshlrev_b32_e32 v91, 16, v41
	v_and_b32_e32 v93, 0xffff0000, v41
	v_mul_f32_e32 v40, 0xbfb8aa3b, v91
	v_mul_f32_e32 v41, 0xbfb8aa3b, v93
	v_exp_f32_e32 v40, v40
	v_exp_f32_e32 v41, v41
	v_pk_mul_f32 v[42:43], v[98:99], v[42:43]
	v_pk_mul_f32 v[98:99], v[104:105], v[96:97] op_sel_hi:[1,0]
	v_pk_add_f32 v[40:41], v[40:41], 1.0 op_sel_hi:[1,0]
	s_nop 0
	v_rcp_f32_e32 v102, v41
	v_pk_mul_f32 v[98:99], v[98:99], v[110:111]
	v_fma_f32 v103, -v41, v102, 1.0
	v_fmac_f32_e32 v102, v103, v102
	v_mul_f32_e32 v104, v93, v102
	v_fma_f32 v105, -v41, v104, v93
	v_fmac_f32_e32 v104, v105, v102
	v_fma_f32 v97, -v41, v104, v93
	v_fma_f32 v97, v97, v102, v104
	v_div_fixup_f32 v41, v97, v41, v93
	v_rcp_f32_e32 v97, v40
	s_nop 0
	v_fma_f32 v102, -v40, v97, 1.0
	v_fmac_f32_e32 v97, v102, v97
	v_mul_f32_e32 v103, v91, v97
	v_fma_f32 v104, -v40, v103, v91
	v_fmac_f32_e32 v103, v104, v97
	v_fma_f32 v93, -v40, v103, v91
	v_fma_f32 v93, v93, v97, v103
	v_div_fixup_f32 v40, v93, v40, v91
	v_pk_mul_f32 v[40:41], v[98:99], v[40:41]
	global_load_dwordx2 v[98:99], v[74:75], off offset:64
	s_waitcnt vmcnt(0) lgkmcnt(0)
; DI size_t kblk(int row, int col, int nrows) { return ((size_t)(col >> 5) * nrows + row) * 32 + (col & 31); }
; DI unsigned pk2(float a, float b) { hwf32x2 f = {a, b}; hwbf16x2 r = __builtin_convertvector(f, hwbf16x2); return __builtin_bit_cast(unsigned, r); }
; DI float sigmoidf_(float z) { return 1.f / (1.f + __expf(-z)); }
; DI float siluf_(float z) { return z / (1.f + __expf(-z)); }
; template <int MX, bool OUT>
; DI void rec_chunk(const Params& p, int l, int b, int h, int dir, int T0, unsigned char* smem, f32x4 (&St)[4], float& nst, float& dtot, int tid, const RecRaw& raw) {
;     ...
;       for (int a = 0; a < 4; ++a) {
;         const int v0 = 16 * a + 4 * g;
;         const uint2 gt = *(const uint2*)(prow + GATE + cb + v0);
;         const float4 gg = *(const float4*)(gvec + v0);
;         float y0 = O[a][0] * rstd * gg.x * siluf_(__uint_as_float(gt.x << 16));
;         float y1 = O[a][1] * rstd * gg.y * siluf_(__uint_as_float(gt.x & 0xffff0000u));
;         float y2 = O[a][2] * rstd * gg.z * siluf_(__uint_as_float(gt.y << 16));
;         float y3 = O[a][3] * rstd * gg.w * siluf_(__uint_as_float(gt.y & 0xffff0000u));
;         if (MX == 1) {
;           const uint2 og = *(const uint2*)(prow + D_OG + h * 64 + v0);
;           y0 *= sigmoidf_(__uint_as_float(og.x << 16)); y1 *= sigmoidf_(__uint_as_float(og.x & 0xffff0000u));
;           y2 *= sigmoidf_(__uint_as_float(og.y << 16)); y3 *= sigmoidf_(__uint_as_float(og.y & 0xffff0000u));
;         }
;         *(uint2*)(MIX + kblk((int)orow, cb + v0, ROWS)) = make_uint2(pk2(y0, y1), pk2(y2, y3));
	v_lshlrev_b32_e32 v91, 16, v98
	v_mul_f32_e32 v91, 0xbfb8aa3b, v91
	v_exp_f32_e32 v102, v91
	v_and_b32_e32 v91, 0xffff0000, v98
	v_mul_f32_e32 v91, 0xbfb8aa3b, v91
	v_exp_f32_e32 v103, v91
	s_nop 0
	v_pk_add_f32 v[102:103], v[102:103], 1.0 op_sel_hi:[1,0]
	s_nop 0
	v_rcp_f32_e32 v93, v103
	s_nop 0
	v_fma_f32 v97, -v103, v93, 1.0
	v_fmac_f32_e32 v93, v97, v93
	v_mul_f32_e32 v98, 1.0, v93
	v_fma_f32 v104, -v103, v98, 1.0
	v_fmac_f32_e32 v98, v104, v93
	v_fma_f32 v91, -v103, v98, 1.0
	v_fma_f32 v91, v91, v93, v98
	v_div_fixup_f32 v103, v91, v103, 1.0
	v_rcp_f32_e32 v93, v102
	s_nop 0
	v_fma_f32 v97, -v102, v93, 1.0
	v_fmac_f32_e32 v93, v97, v93
	v_mul_f32_e32 v98, 1.0, v93
	v_fma_f32 v104, -v102, v98, 1.0
	v_fmac_f32_e32 v98, v104, v93
	v_fma_f32 v91, -v102, v98, 1.0
	v_fma_f32 v91, v91, v93, v98
	v_div_fixup_f32 v102, v91, v102, 1.0
	v_lshlrev_b32_e32 v91, 16, v99
	v_mul_f32_e32 v91, 0xbfb8aa3b, v91
	v_exp_f32_e32 v98, v91
	v_and_b32_e32 v91, 0xffff0000, v99
	v_mul_f32_e32 v91, 0xbfb8aa3b, v91
	v_exp_f32_e32 v99, v91
	v_pk_mul_f32 v[42:43], v[42:43], v[102:103]
	v_pk_add_f32 v[98:99], v[98:99], 1.0 op_sel_hi:[1,0]
	s_nop 0
	v_rcp_f32_e32 v93, v99
	v_cvt_pk_bf16_f32 v42, v42, v43
	v_fma_f32 v97, -v99, v93, 1.0
	v_fmac_f32_e32 v93, v97, v93
	v_mul_f32_e32 v102, 1.0, v93
	v_fma_f32 v103, -v99, v102, 1.0
	v_fmac_f32_e32 v102, v103, v93
	v_fma_f32 v91, -v99, v102, 1.0
	v_fma_f32 v91, v91, v93, v102
	v_div_fixup_f32 v99, v91, v99, 1.0
	v_rcp_f32_e32 v93, v98
	s_nop 0
	v_fma_f32 v97, -v98, v93, 1.0
	v_fmac_f32_e32 v93, v97, v93
	v_mul_f32_e32 v102, 1.0, v93
	v_fma_f32 v103, -v98, v102, 1.0
	v_fmac_f32_e32 v102, v103, v93
	v_fma_f32 v91, -v98, v102, 1.0
	v_fma_f32 v91, v91, v93, v102
	v_div_fixup_f32 v98, v91, v98, 1.0
	v_pk_mul_f32 v[40:41], v[40:41], v[98:99]
	s_nop 0
	v_cvt_pk_bf16_f32 v43, v40, v41
	global_store_dwordx2 v[72:73], v[42:43], off
	global_load_dwordx2 v[40:41], v[100:101], off offset:96
	s_nop 0
	global_load_dwordx2 v[74:75], v[74:75], off offset:96
	s_waitcnt vmcnt(0) lgkmcnt(0)
	v_lshlrev_b32_e32 v73, 16, v40
	v_and_b32_e32 v91, 0xffff0000, v40
	v_lshlrev_b32_e32 v40, 16, v41
	v_mul_f32_e32 v42, 0xbfb8aa3b, v40
	v_exp_f32_e32 v42, v42
	s_nop 0
	v_add_f32_e32 v42, 1.0, v42
	v_rcp_f32_e32 v72, v42
	s_nop 0
	v_fma_f32 v93, -v42, v72, 1.0
	v_fmac_f32_e32 v72, v93, v72
	v_mul_f32_e32 v97, v40, v72
	v_fma_f32 v98, -v42, v97, v40
	v_fmac_f32_e32 v97, v98, v72
	v_fma_f32 v43, -v42, v97, v40
	v_fma_f32 v43, v43, v72, v97
	v_and_b32_e32 v93, 0xffff0000, v41
	v_div_fixup_f32 v72, v43, v42, v40
	v_mul_f32_e32 v40, 0xbfb8aa3b, v93
	v_exp_f32_e32 v98, v40
	v_lshlrev_b32_e32 v40, 16, v74
	v_mul_f32_e32 v40, 0xbfb8aa3b, v40
	v_exp_f32_e32 v100, v40
	v_and_b32_e32 v40, 0xffff0000, v74
	v_mul_f32_e32 v40, 0xbfb8aa3b, v40
	v_exp_f32_e32 v101, v40
	global_load_dwordx4 v[40:43], v[86:87], off offset:192
	v_pk_mul_f32 v[70:71], v[70:71], v[96:97] op_sel_hi:[1,0]
	v_mul_f32_e32 v74, 0xbfb8aa3b, v73
	v_exp_f32_e32 v102, v74
	s_waitcnt vmcnt(0)
	v_pk_mul_f32 v[40:41], v[70:71], v[40:41]
	v_mul_f32_e32 v70, 0xbfb8aa3b, v91
	v_exp_f32_e32 v103, v70
	s_nop 0
	v_pk_add_f32 v[70:71], v[102:103], 1.0 op_sel_hi:[1,0]
	s_nop 0
	v_rcp_f32_e32 v97, v71
	s_nop 0
	v_fma_f32 v99, -v71, v97, 1.0
	v_fmac_f32_e32 v97, v99, v97
	v_mul_f32_e32 v102, v91, v97
	v_fma_f32 v103, -v71, v102, v91
	v_fmac_f32_e32 v102, v103, v97
	v_fma_f32 v74, -v71, v102, v91
	v_fma_f32 v74, v74, v97, v102
	v_div_fixup_f32 v71, v74, v71, v91
	v_rcp_f32_e32 v91, v70
	s_nop 0
	v_fma_f32 v97, -v70, v91, 1.0
	v_fmac_f32_e32 v91, v97, v91
	v_mul_f32_e32 v99, v73, v91
	v_fma_f32 v102, -v70, v99, v73
	v_fmac_f32_e32 v99, v102, v91
	v_fma_f32 v74, -v70, v99, v73
	v_fma_f32 v74, v74, v91, v99
	v_div_fixup_f32 v70, v74, v70, v73
	v_pk_mul_f32 v[40:41], v[40:41], v[70:71]
	v_pk_add_f32 v[70:71], v[100:101], 1.0 op_sel_hi:[1,0]
	s_nop 0
	v_rcp_f32_e32 v74, v71
	s_nop 0
	v_fma_f32 v91, -v71, v74, 1.0
	v_fmac_f32_e32 v74, v91, v74
	v_mul_f32_e32 v97, 1.0, v74
	v_fma_f32 v99, -v71, v97, 1.0
	v_fmac_f32_e32 v97, v99, v74
	v_fma_f32 v73, -v71, v97, 1.0
	v_fma_f32 v73, v73, v74, v97
	v_div_fixup_f32 v71, v73, v71, 1.0
	v_rcp_f32_e32 v74, v70
	s_nop 0
	v_fma_f32 v91, -v70, v74, 1.0
	v_fmac_f32_e32 v74, v91, v74
	v_mul_f32_e32 v97, 1.0, v74
	v_fma_f32 v99, -v70, v97, 1.0
	v_fmac_f32_e32 v97, v99, v74
	v_fma_f32 v73, -v70, v97, 1.0
	v_fma_f32 v73, v73, v74, v97
	v_div_fixup_f32 v70, v73, v70, 1.0
	v_pk_mul_f32 v[40:41], v[40:41], v[70:71]
	v_lshlrev_b32_e32 v70, 16, v75
	v_mul_f32_e32 v70, 0xbfb8aa3b, v70
	v_exp_f32_e32 v70, v70
	v_cvt_pk_bf16_f32 v40, v40, v41
	v_add_f32_e32 v70, 1.0, v70
	v_rcp_f32_e32 v73, v70
	s_nop 0
	v_fma_f32 v74, -v70, v73, 1.0
	v_fmac_f32_e32 v73, v74, v73
	v_mul_f32_e32 v91, 1.0, v73
	v_fma_f32 v97, -v70, v91, 1.0
	v_fmac_f32_e32 v91, v97, v73
	v_fma_f32 v71, -v70, v91, 1.0
	v_fma_f32 v71, v71, v73, v91
	v_div_fixup_f32 v70, v71, v70, 1.0
	v_and_b32_e32 v71, 0xffff0000, v75
	v_mul_f32_e32 v71, 0xbfb8aa3b, v71
	v_exp_f32_e32 v99, v71
	s_nop 0
	v_pk_add_f32 v[74:75], v[98:99], 1.0 op_sel_hi:[1,0]
	s_nop 0
	v_rcp_f32_e32 v73, v75
	s_nop 0
	v_fma_f32 v91, -v75, v73, 1.0
	v_fmac_f32_e32 v73, v91, v73
	v_mul_f32_e32 v97, 1.0, v73
	v_fma_f32 v98, -v75, v97, 1.0
	v_fmac_f32_e32 v97, v98, v73
	v_fma_f32 v71, -v75, v97, 1.0
	v_fma_f32 v71, v71, v73, v97
	v_div_fixup_f32 v71, v71, v75, 1.0
	v_rcp_f32_e32 v75, v74
	s_mov_b64 s[0:1], 0
	v_fma_f32 v91, -v74, v75, 1.0
	v_fmac_f32_e32 v75, v91, v75
	v_mul_f32_e32 v97, v93, v75
	v_fma_f32 v98, -v74, v97, v93
	v_fmac_f32_e32 v97, v98, v75
	v_fma_f32 v73, -v74, v97, v93
	v_fma_f32 v73, v73, v75, v97
	v_pk_mul_f32 v[68:69], v[68:69], v[96:97] op_sel_hi:[1,0]
	v_div_fixup_f32 v73, v73, v74, v93
	v_pk_mul_f32 v[42:43], v[68:69], v[42:43]
	v_mov_b32_e32 v93, v161
	v_pk_mul_f32 v[42:43], v[42:43], v[72:73]
	v_lshl_add_u64 v[66:67], v[66:67], 0, v[92:93]
	v_pk_mul_f32 v[42:43], v[42:43], v[70:71]
	global_store_dword v[66:67], v40, off

; DI size_t kblk(int row, int col, int nrows) { return ((size_t)(col >> 5) * nrows + row) * 32 + (col & 31); }
; DI float siluf_(float z) { return z / (1.f + __expf(-z)); }
; template <int MX, bool OUT>
; DI void rec_chunk(const Params& p, int l, int b, int h, int dir, int T0, unsigned char* smem, f32x4 (&St)[4], float& nst, float& dtot, int tid, const RecRaw& raw) {
;     ...
;     for (int ks = 0; ks < 2; ++ks) {
;       const bf16x8 fb = *(const bf16x8*)(smem + L_QS + swz(t, ks * 4 + g));
; #pragma unroll
;       for (int a = 0; a < 4; ++a) {
;         const bf16x8 fa = *(const bf16x8*)(smem + L_STT + swz(16 * a + col, ks * 4 + g));
;         O[a] = MFMA16(fa, fb, O[a]);
;       }
;     }
;     if (MX == 1) {
;       const float inv = 1.f / fmaxf(fabsf(den), 1.f);
; #pragma unroll
;       for (int a = 0; a < 4; ++a)
; #pragma unroll
;         for (int j = 0; j < 4; ++j) O[a][j] *= inv;
;     }
;     if (dir == 0) {
; #pragma unroll
;       for (int a = 0; a < 4; ++a) *(uint2*)(MIX + kblk((int)orow, cb + 16 * a + 4 * g, ROWS)) = make_uint2(pk2(O[a][0], O[a][1]), pk2(O[a][2], O[a][3]));
;     } else {
;       float ss = 0.f;
; #pragma unroll
;       for (int a = 0; a < 4; ++a) {
;         const uint2 u = *(const uint2*)(MIX + kblk((int)orow, cb + 16 * a + 4 * g, ROWS));
;         O[a][0] += __uint_as_float(u.x << 16); O[a][1] += __uint_as_float(u.x & 0xffff0000u);
;         O[a][2] += __uint_as_float(u.y << 16); O[a][3] += __uint_as_float(u.y & 0xffff0000u);
; #pragma unroll
;         for (int j = 0; j < 4; ++j) ss += O[a][j] * O[a][j];
;       }
;       ss += __shfl_xor(ss, 16);
;       ss += __shfl_xor(ss, 32);
;       const float rstd = rsqrtf(ss * (1.f / 64.f) + EPS);
;       const float* gvec = (MX ? p.ml_g : p.hg_g) + l * 64;
; #pragma unroll
;       for (int a = 0; a < 4; ++a) {
;         const int v0 = 16 * a + 4 * g;
;         const uint2 gt = *(const uint2*)(prow + GATE + cb + v0);
;         const float4 gg = *(const float4*)(gvec + v0);
;         float y0 = O[a][0] * rstd * gg.x * siluf_(__uint_as_float(gt.x << 16));
;         float y1 = O[a][1] * rstd * gg.y * siluf_(__uint_as_float(gt.x & 0xffff0000u));
;         float y2 = O[a][2] * rstd * gg.z * siluf_(__uint_as_float(gt.y << 16));
;         float y3 = O[a][3] * rstd * gg.w * siluf_(__uint_as_float(gt.y & 0xffff0000u));
.LBB0_765:
	s_or_b64 exec, exec, vcc
	s_add_i32 s10, s13, -1
	v_mov_b32_e32 v40, s10
	v_cndmask_b32_e64 v40, v91, v40, s[6:7]
	v_lshlrev_b32_e32 v40, 6, v40
	v_add_u32_e32 v40, s12, v40
	v_mov_b32_e32 v41, v161
	v_lshl_add_u64 v[68:69], v[40:41], 0, v[82:83]
	ds_read_b128 v[40:43], v202 offset:32768
	ds_read_b128 v[44:47], v200 offset:57344
	ds_read_b128 v[48:51], v200 offset:59392
	ds_read_b128 v[52:55], v200 offset:61440
	s_waitcnt lgkmcnt(0)
	v_mfma_f32_16x16x32_bf16 v[44:47], v[44:47], v[40:43], v[56:59]
	s_mov_b64 s[10:11], -1
	s_nop 1
	ds_read_b128 v[56:59], v200 offset:63488
	s_and_b64 vcc, exec, s[78:79]
	v_mfma_f32_16x16x32_bf16 v[48:51], v[48:51], v[40:43], v[60:63]
	v_ashrrev_i32_e32 v203, 31, v68
	v_mfma_f32_16x16x32_bf16 v[52:55], v[52:55], v[40:43], v[64:67]
	s_waitcnt lgkmcnt(0)
	v_mfma_f32_16x16x32_bf16 v[56:59], v[56:59], v[40:43], v[72:75]
	ds_read_b128 v[60:63], v201 offset:32768
	ds_read_b128 v[40:43], v199 offset:57344
	s_waitcnt lgkmcnt(0)
	v_mfma_f32_16x16x32_bf16 v[40:43], v[40:43], v[60:63], v[44:47]
	s_nop 2
	ds_read_b128 v[44:47], v199 offset:59392
	s_waitcnt lgkmcnt(0)
	v_mfma_f32_16x16x32_bf16 v[48:51], v[44:47], v[60:63], v[48:51]
	ds_read_b128 v[44:47], v199 offset:61440
	s_waitcnt lgkmcnt(0)
	v_mfma_f32_16x16x32_bf16 v[52:55], v[44:47], v[60:63], v[52:55]
	ds_read_b128 v[44:47], v199 offset:63488
	s_waitcnt lgkmcnt(0)
	v_mfma_f32_16x16x32_bf16 v[44:47], v[44:47], v[60:63], v[56:59]
	s_cbranch_vccnz .LBB0_767
	s_nop 1
	v_mov_b64_e32 v[56:57], s[40:41]
	v_mad_u64_u32 v[56:57], s[10:11], v68, s33, v[56:57]
	v_mad_i32_i24 v57, v69, s33, v57
	v_mov_b32_e32 v69, v203
	v_lshl_add_u64 v[60:61], v[68:69], 0, s[30:31]
	v_lshlrev_b64 v[60:61], 6, v[60:61]
	v_lshl_add_u64 v[70:71], v[88:89], 0, v[60:61]
	global_load_dwordx2 v[60:61], v[70:71], off
	v_lshl_add_u64 v[58:59], v[68:69], 0, s[28:29]
	v_lshlrev_b64 v[58:59], 6, v[58:59]
	v_mov_b32_e32 v91, v161
	v_lshl_add_u64 v[96:97], v[84:85], 0, v[58:59]
	global_load_dwordx2 v[58:59], v[96:97], off
	s_mov_b64 s[10:11], 0x41c7a20
	v_lshl_add_u64 v[56:57], v[56:57], 0, s[10:11]
	s_waitcnt vmcnt(0) lgkmcnt(0)
	v_lshlrev_b32_e32 v74, 16, v60
	v_and_b32_e32 v75, 0xffff0000, v60
	v_lshlrev_b32_e32 v98, 16, v61
	v_and_b32_e32 v99, 0xffff0000, v61
	v_lshl_add_u64 v[60:61], v[68:69], 0, s[42:43]
	v_lshlrev_b64 v[60:61], 6, v[60:61]
	v_lshl_add_u64 v[60:61], s[34:35], 0, v[60:61]
	v_lshl_add_u64 v[66:67], v[60:61], 0, v[90:91]
	global_load_dwordx2 v[62:63], v[66:67], off
	v_mbcnt_hi_u32_b32 v69, -1, v185
	v_and_b32_e32 v73, 64, v69
	v_xor_b32_e32 v72, 16, v69
	v_add_u32_e32 v73, 64, v73
	v_cmp_lt_i32_e32 vcc, v72, v73
	v_lshlrev_b32_e32 v112, 16, v58
	v_and_b32_e32 v113, 0xffff0000, v58
	v_cndmask_b32_e32 v72, v69, v72, vcc
	v_lshlrev_b32_e32 v93, 2, v72
	v_xor_b32_e32 v72, 32, v69
	v_cmp_lt_i32_e32 vcc, v72, v73
	v_lshlrev_b32_e32 v58, 16, v59
	v_and_b32_e32 v59, 0xffff0000, v59
	v_cndmask_b32_e32 v69, v69, v72, vcc
	v_lshl_add_u64 v[72:73], v[56:57], 0, s[2:3]
	v_lshl_add_u64 v[56:57], v[56:57], 0, v[90:91]
	v_lshl_add_u64 v[56:57], v[56:57], 0, s[2:3]
	global_load_dwordx2 v[56:57], v[56:57], off
	v_pk_add_f32 v[108:109], v[42:43], v[58:59]
	v_pk_add_f32 v[112:113], v[40:41], v[112:113]
	v_pk_mul_f32 v[110:111], v[108:109], v[108:109]
	v_pk_mul_f32 v[116:117], v[112:113], v[112:113]
	v_lshl_add_u64 v[72:73], v[72:73], 0, v[90:91]
	v_add_f32_e32 v91, v116, v117
	v_add_f32_e32 v91, v91, v110
	v_add_f32_e32 v91, v111, v91
	v_lshlrev_b32_e32 v69, 2, v69
	s_waitcnt vmcnt(0) lgkmcnt(0)
	v_lshlrev_b32_e32 v104, 16, v62
	v_and_b32_e32 v105, 0xffff0000, v62
	v_lshlrev_b32_e32 v106, 16, v63
	v_and_b32_e32 v107, 0xffff0000, v63
	global_load_dwordx2 v[62:63], v[66:67], off offset:32
	v_pk_add_f32 v[104:105], v[52:53], v[104:105]
	v_lshlrev_b32_e32 v204, 16, v56
	v_and_b32_e32 v205, 0xffff0000, v56
	v_mul_f32_e32 v114, 0xbfb8aa3b, v204
	v_mul_f32_e32 v115, 0xbfb8aa3b, v205
	v_exp_f32_e32 v114, v114
	v_exp_f32_e32 v115, v115
	v_lshlrev_b32_e32 v206, 16, v57
	v_and_b32_e32 v207, 0xffff0000, v57
	global_load_dwordx4 v[56:59], v[86:87], off
	v_pk_add_f32 v[114:115], v[114:115], 1.0 op_sel_hi:[1,0]
	s_waitcnt vmcnt(0) lgkmcnt(0)
	v_lshlrev_b32_e32 v64, 16, v62
	v_rcp_f32_e32 v100, v114
	v_rcp_f32_e32 v101, v115
	s_nop 0
	v_pk_fma_f32 v[208:209], v[114:115], v[100:101], 1.0 op_sel_hi:[1,1,0] neg_lo:[1,0,0] neg_hi:[1,0,0]
	v_pk_fma_f32 v[100:101], v[208:209], v[100:101], v[100:101]
	v_pk_mul_f32 v[102:103], v[204:205], v[100:101]
	v_pk_fma_f32 v[208:209], v[114:115], v[102:103], v[204:205] neg_lo:[1,0,0] neg_hi:[1,0,0]
	v_pk_fma_f32 v[102:103], v[208:209], v[100:101], v[102:103]
	v_pk_fma_f32 v[208:209], v[114:115], v[102:103], v[204:205] neg_lo:[1,0,0] neg_hi:[1,0,0]
	v_pk_fma_f32 v[102:103], v[208:209], v[100:101], v[102:103]
	v_div_fixup_f32 v114, v102, v114, v204
	v_div_fixup_f32 v115, v103, v115, v205
	v_and_b32_e32 v65, 0xffff0000, v62
	v_pk_add_f32 v[64:65], v[44:45], v[64:65]
	v_lshlrev_b32_e32 v62, 16, v63
	v_and_b32_e32 v63, 0xffff0000, v63
	v_pk_mul_f32 v[100:101], v[64:65], v[64:65]
	v_pk_add_f32 v[62:63], v[46:47], v[62:63]
	v_mul_f32_e32 v204, 0xbfb8aa3b, v206
	v_mul_f32_e32 v205, 0xbfb8aa3b, v207
	v_exp_f32_e32 v204, v204
	v_exp_f32_e32 v205, v205
	v_pk_mul_f32 v[102:103], v[62:63], v[62:63]
	v_pk_add_f32 v[204:205], v[204:205], 1.0 op_sel_hi:[1,0]
	s_nop 0
	v_rcp_f32_e32 v208, v204
	v_rcp_f32_e32 v209, v205
	s_nop 0
	v_pk_fma_f32 v[212:213], v[204:205], v[208:209], 1.0 op_sel_hi:[1,1,0] neg_lo:[1,0,0] neg_hi:[1,0,0]
	v_pk_fma_f32 v[208:209], v[212:213], v[208:209], v[208:209]
	v_pk_mul_f32 v[210:211], v[206:207], v[208:209]
	v_pk_fma_f32 v[212:213], v[204:205], v[210:211], v[206:207] neg_lo:[1,0,0] neg_hi:[1,0,0]
	v_pk_fma_f32 v[210:211], v[212:213], v[208:209], v[210:211]
	v_pk_fma_f32 v[212:213], v[204:205], v[210:211], v[206:207] neg_lo:[1,0,0] neg_hi:[1,0,0]
	v_pk_fma_f32 v[210:211], v[212:213], v[208:209], v[210:211]
	v_div_fixup_f32 v204, v210, v204, v206
	v_div_fixup_f32 v205, v211, v205, v207
	s_nop 0
	v_pk_mul_f32 v[212:213], v[104:105], v[104:105]
	v_pk_add_f32 v[210:211], v[48:49], v[74:75]
	v_pk_mul_f32 v[74:75], v[210:211], v[210:211]
	v_pk_add_f32 v[206:207], v[50:51], v[98:99]
	v_add_f32_e32 v74, v74, v91
	v_pk_mul_f32 v[208:209], v[206:207], v[206:207]
	v_add_f32_e32 v74, v75, v74
	v_add_f32_e32 v74, v208, v74
	v_add_f32_e32 v74, v209, v74
	v_pk_add_f32 v[98:99], v[54:55], v[106:107]
	v_add_f32_e32 v74, v212, v74
	v_pk_mul_f32 v[106:107], v[98:99], v[98:99]
	v_add_f32_e32 v74, v213, v74
	v_add_f32_e32 v74, v106, v74
	v_add_f32_e32 v74, v107, v74
	v_add_f32_e32 v74, v100, v74
	v_add_f32_e32 v74, v101, v74
	v_add_f32_e32 v74, v102, v74
	v_add_f32_e32 v74, v103, v74
	ds_bpermute_b32 v75, v93, v74
	s_waitcnt lgkmcnt(0)
; DI size_t kblk(int row, int col, int nrows) { return ((size_t)(col >> 5) * nrows + row) * 32 + (col & 31); }
; DI unsigned pk2(float a, float b) { hwf32x2 f = {a, b}; hwbf16x2 r = __builtin_convertvector(f, hwbf16x2); return __builtin_bit_cast(unsigned, r); }
; DI float sigmoidf_(float z) { return 1.f / (1.f + __expf(-z)); }
; DI float siluf_(float z) { return z / (1.f + __expf(-z)); }
; template <int MX, bool OUT>
; DI void rec_chunk(const Params& p, int l, int b, int h, int dir, int T0, unsigned char* smem, f32x4 (&St)[4], float& nst, float& dtot, int tid, const RecRaw& raw) {
;     ...
;       ss += __shfl_xor(ss, 16);
;       ss += __shfl_xor(ss, 32);
;       const float rstd = rsqrtf(ss * (1.f / 64.f) + EPS);
;       const float* gvec = (MX ? p.ml_g : p.hg_g) + l * 64;
; #pragma unroll
;       for (int a = 0; a < 4; ++a) {
;         const int v0 = 16 * a + 4 * g;
;         const uint2 gt = *(const uint2*)(prow + GATE + cb + v0);
;         const float4 gg = *(const float4*)(gvec + v0);
;         float y0 = O[a][0] * rstd * gg.x * siluf_(__uint_as_float(gt.x << 16));
;         float y1 = O[a][1] * rstd * gg.y * siluf_(__uint_as_float(gt.x & 0xffff0000u));
;         float y2 = O[a][2] * rstd * gg.z * siluf_(__uint_as_float(gt.y << 16));
;         float y3 = O[a][3] * rstd * gg.w * siluf_(__uint_as_float(gt.y & 0xffff0000u));
;         if (MX == 1) {
;           const uint2 og = *(const uint2*)(prow + D_OG + h * 64 + v0);
;           y0 *= sigmoidf_(__uint_as_float(og.x << 16)); y1 *= sigmoidf_(__uint_as_float(og.x & 0xffff0000u));
;           y2 *= sigmoidf_(__uint_as_float(og.y << 16)); y3 *= sigmoidf_(__uint_as_float(og.y & 0xffff0000u));
;         }
;         *(uint2*)(MIX + kblk((int)orow, cb + v0, ROWS)) = make_uint2(pk2(y0, y1), pk2(y2, y3));
	v_add_f32_e32 v74, v74, v75
	ds_bpermute_b32 v69, v69, v74
	s_waitcnt lgkmcnt(0)
	v_add_f32_e32 v69, v74, v69
	v_fmamk_f32 v69, v69, 0x3c800000, v162
	v_cmp_gt_f32_e32 vcc, s38, v69
	v_mul_f32_e32 v74, 0x4b800000, v69
	s_nop 0
	v_cndmask_b32_e32 v69, v69, v74, vcc
	v_rsq_f32_e32 v69, v69
	s_nop 0
	v_mul_f32_e32 v74, 0x45800000, v69
	v_cndmask_b32_e32 v74, v69, v74, vcc
	v_pk_mul_f32 v[100:101], v[112:113], v[74:75] op_sel_hi:[1,0]
	s_nop 0
	v_pk_mul_f32 v[56:57], v[56:57], v[100:101]
	v_pk_mul_f32 v[100:101], v[108:109], v[74:75] op_sel_hi:[1,0]
	v_pk_mul_f32 v[56:57], v[114:115], v[56:57]
	v_pk_mul_f32 v[58:59], v[58:59], v[100:101]
	v_cvt_pk_bf16_f32 v56, v56, v57
	v_pk_mul_f32 v[58:59], v[204:205], v[58:59]
	s_nop 0
	v_cvt_pk_bf16_f32 v57, v58, v59
	global_store_dwordx2 v[96:97], v[56:57], off
	global_load_dwordx2 v[96:97], v[72:73], off offset:32
	s_nop 0
	global_load_dwordx4 v[56:59], v[86:87], off offset:64
	s_waitcnt vmcnt(0) lgkmcnt(0)
	v_lshlrev_b32_e32 v69, 16, v96
	v_and_b32_e32 v75, 0xffff0000, v96
	v_mul_f32_e32 v91, 0xbfb8aa3b, v69
	v_exp_f32_e32 v100, v91
	v_mul_f32_e32 v91, 0xbfb8aa3b, v75
	v_exp_f32_e32 v101, v91
	v_pk_mul_f32 v[102:103], v[210:211], v[74:75] op_sel_hi:[1,0]
	v_pk_add_f32 v[100:101], v[100:101], 1.0 op_sel_hi:[1,0]
	s_nop 0
	v_rcp_f32_e32 v93, v101
	v_pk_mul_f32 v[56:57], v[56:57], v[102:103]
	v_fma_f32 v96, -v101, v93, 1.0
	v_fmac_f32_e32 v93, v96, v93
	v_mul_f32_e32 v102, v75, v93
	v_fma_f32 v103, -v101, v102, v75
	v_fmac_f32_e32 v102, v103, v93
	v_fma_f32 v91, -v101, v102, v75
	v_fma_f32 v91, v91, v93, v102
	v_div_fixup_f32 v101, v91, v101, v75
	v_rcp_f32_e32 v91, v100
	s_nop 0
	v_fma_f32 v93, -v100, v91, 1.0
	v_fmac_f32_e32 v91, v93, v91
	v_mul_f32_e32 v96, v69, v91
	v_fma_f32 v102, -v100, v96, v69
	v_fmac_f32_e32 v96, v102, v91
	v_fma_f32 v75, -v100, v96, v69
	v_fma_f32 v75, v75, v91, v96
	v_div_fixup_f32 v100, v75, v100, v69
	v_lshlrev_b32_e32 v69, 16, v97
	v_and_b32_e32 v75, 0xffff0000, v97
	v_mul_f32_e32 v91, 0xbfb8aa3b, v69
	v_exp_f32_e32 v96, v91
	v_mul_f32_e32 v91, 0xbfb8aa3b, v75
	v_exp_f32_e32 v97, v91
	v_pk_mul_f32 v[56:57], v[100:101], v[56:57]
	v_pk_mul_f32 v[100:101], v[206:207], v[74:75] op_sel_hi:[1,0]
	v_cvt_pk_bf16_f32 v56, v56, v57
	v_pk_add_f32 v[96:97], v[96:97], 1.0 op_sel_hi:[1,0]
	v_pk_mul_f32 v[58:59], v[58:59], v[100:101]
	v_rcp_f32_e32 v93, v97
	s_nop 0
	v_fma_f32 v100, -v97, v93, 1.0
	v_fmac_f32_e32 v93, v100, v93
	v_mul_f32_e32 v101, v75, v93
	v_fma_f32 v102, -v97, v101, v75
	v_fmac_f32_e32 v101, v102, v93
	v_fma_f32 v91, -v97, v101, v75
	v_fma_f32 v91, v91, v93, v101
	v_div_fixup_f32 v97, v91, v97, v75
	v_rcp_f32_e32 v91, v96
	s_nop 0
	v_fma_f32 v93, -v96, v91, 1.0
	v_fmac_f32_e32 v91, v93, v91
	v_mul_f32_e32 v100, v69, v91
	v_fma_f32 v101, -v96, v100, v69
	v_fmac_f32_e32 v100, v101, v91
	v_fma_f32 v75, -v96, v100, v69
	v_fma_f32 v75, v75, v91, v100
	v_div_fixup_f32 v96, v75, v96, v69
	v_pk_mul_f32 v[58:59], v[96:97], v[58:59]
	s_nop 0
	v_cvt_pk_bf16_f32 v57, v58, v59
	global_store_dwordx2 v[70:71], v[56:57], off
	global_load_dwordx2 v[70:71], v[72:73], off offset:64
	s_nop 0
	global_load_dwordx4 v[56:59], v[86:87], off offset:128
	s_waitcnt vmcnt(0) lgkmcnt(0)
; DI size_t kblk(int row, int col, int nrows) { return ((size_t)(col >> 5) * nrows + row) * 32 + (col & 31); }
; DI unsigned pk2(float a, float b) { hwf32x2 f = {a, b}; hwbf16x2 r = __builtin_convertvector(f, hwbf16x2); return __builtin_bit_cast(unsigned, r); }
; DI float sigmoidf_(float z) { return 1.f / (1.f + __expf(-z)); }
; DI float siluf_(float z) { return z / (1.f + __expf(-z)); }
; template <int MX, bool OUT>
; DI void rec_chunk(const Params& p, int l, int b, int h, int dir, int T0, unsigned char* smem, f32x4 (&St)[4], float& nst, float& dtot, int tid, const RecRaw& raw) {
;     ...
;       for (int a = 0; a < 4; ++a) {
;         const int v0 = 16 * a + 4 * g;
;         const uint2 gt = *(const uint2*)(prow + GATE + cb + v0);
;         const float4 gg = *(const float4*)(gvec + v0);
;         float y0 = O[a][0] * rstd * gg.x * siluf_(__uint_as_float(gt.x << 16));
;         float y1 = O[a][1] * rstd * gg.y * siluf_(__uint_as_float(gt.x & 0xffff0000u));
;         float y2 = O[a][2] * rstd * gg.z * siluf_(__uint_as_float(gt.y << 16));
;         float y3 = O[a][3] * rstd * gg.w * siluf_(__uint_as_float(gt.y & 0xffff0000u));
;         if (MX == 1) {
;           const uint2 og = *(const uint2*)(prow + D_OG + h * 64 + v0);
;           y0 *= sigmoidf_(__uint_as_float(og.x << 16)); y1 *= sigmoidf_(__uint_as_float(og.x & 0xffff0000u));
;           y2 *= sigmoidf_(__uint_as_float(og.y << 16)); y3 *= sigmoidf_(__uint_as_float(og.y & 0xffff0000u));
;         }
;         *(uint2*)(MIX + kblk((int)orow, cb + v0, ROWS)) = make_uint2(pk2(y0, y1), pk2(y2, y3));
	v_lshlrev_b32_e32 v69, 16, v70
	v_and_b32_e32 v70, 0xffff0000, v70
	v_mul_f32_e32 v75, 0xbfb8aa3b, v69
	v_exp_f32_e32 v96, v75
	v_pk_mul_f32 v[100:101], v[104:105], v[74:75] op_sel_hi:[1,0]
	v_mul_f32_e32 v75, 0xbfb8aa3b, v70
	v_exp_f32_e32 v97, v75
	v_pk_mul_f32 v[56:57], v[100:101], v[56:57]
	v_pk_add_f32 v[96:97], v[96:97], 1.0 op_sel_hi:[1,0]
	s_nop 0
	v_rcp_f32_e32 v91, v97
	s_nop 0
	v_fma_f32 v93, -v97, v91, 1.0
	v_fmac_f32_e32 v91, v93, v91
	v_mul_f32_e32 v100, v70, v91
	v_fma_f32 v101, -v97, v100, v70
	v_fmac_f32_e32 v100, v101, v91
	v_fma_f32 v75, -v97, v100, v70
	v_fma_f32 v75, v75, v91, v100
	v_div_fixup_f32 v97, v75, v97, v70
	v_rcp_f32_e32 v75, v96
	s_nop 0
	v_fma_f32 v91, -v96, v75, 1.0
	v_fmac_f32_e32 v75, v91, v75
	v_mul_f32_e32 v93, v69, v75
	v_fma_f32 v100, -v96, v93, v69
	v_fmac_f32_e32 v93, v100, v75
	v_fma_f32 v70, -v96, v93, v69
	v_fma_f32 v70, v70, v75, v93
	v_div_fixup_f32 v96, v70, v96, v69
	v_lshlrev_b32_e32 v69, 16, v71
	v_and_b32_e32 v75, 0xffff0000, v71
	v_mul_f32_e32 v70, 0xbfb8aa3b, v69
	v_mul_f32_e32 v71, 0xbfb8aa3b, v75
	v_exp_f32_e32 v70, v70
	v_exp_f32_e32 v71, v71
	v_pk_mul_f32 v[56:57], v[56:57], v[96:97]
	v_pk_mul_f32 v[96:97], v[98:99], v[74:75] op_sel_hi:[1,0]
	v_cvt_pk_bf16_f32 v56, v56, v57
	v_pk_add_f32 v[70:71], v[70:71], 1.0 op_sel_hi:[1,0]
	v_pk_mul_f32 v[58:59], v[96:97], v[58:59]
	v_rcp_f32_e32 v93, v71
	s_nop 0
	v_fma_f32 v96, -v71, v93, 1.0
	v_fmac_f32_e32 v93, v96, v93
	v_mul_f32_e32 v97, v75, v93
	v_fma_f32 v98, -v71, v97, v75
	v_fmac_f32_e32 v97, v98, v93
	v_fma_f32 v91, -v71, v97, v75
	v_fma_f32 v91, v91, v93, v97
	v_div_fixup_f32 v71, v91, v71, v75
	v_rcp_f32_e32 v91, v70
	s_nop 0
	v_fma_f32 v93, -v70, v91, 1.0
	v_fmac_f32_e32 v91, v93, v91
	v_mul_f32_e32 v96, v69, v91
	v_fma_f32 v97, -v70, v96, v69
	v_fmac_f32_e32 v96, v97, v91
	v_fma_f32 v75, -v70, v96, v69
	v_fma_f32 v75, v75, v91, v96
	v_div_fixup_f32 v70, v75, v70, v69
	v_pk_mul_f32 v[58:59], v[58:59], v[70:71]
	v_pk_mul_f32 v[64:65], v[64:65], v[74:75] op_sel_hi:[1,0]
	v_cvt_pk_bf16_f32 v57, v58, v59
	global_store_dwordx2 v[66:67], v[56:57], off
	global_load_dwordx2 v[66:67], v[72:73], off offset:96
	v_mov_b32_e32 v93, v161
	global_load_dwordx4 v[56:59], v[86:87], off offset:192
	s_waitcnt vmcnt(0) lgkmcnt(0)
	v_lshlrev_b32_e32 v69, 16, v66
	v_and_b32_e32 v66, 0xffff0000, v66
	v_mul_f32_e32 v70, 0xbfb8aa3b, v69
	v_pk_mul_f32 v[56:57], v[64:65], v[56:57]
	v_mul_f32_e32 v64, 0xbfb8aa3b, v66
	v_exp_f32_e32 v70, v70
	v_exp_f32_e32 v71, v64
	s_nop 0
	v_pk_add_f32 v[64:65], v[70:71], 1.0 op_sel_hi:[1,0]
	s_nop 0
	v_rcp_f32_e32 v71, v65
	s_nop 0
	v_fma_f32 v72, -v65, v71, 1.0
	v_fmac_f32_e32 v71, v72, v71
	v_mul_f32_e32 v73, v66, v71
	v_fma_f32 v75, -v65, v73, v66
	v_fmac_f32_e32 v73, v75, v71
	v_fma_f32 v70, -v65, v73, v66
	v_fma_f32 v70, v70, v71, v73
	v_div_fixup_f32 v65, v70, v65, v66
	v_rcp_f32_e32 v70, v64
	v_pk_mul_f32 v[62:63], v[62:63], v[74:75] op_sel_hi:[1,0]
	v_fma_f32 v71, -v64, v70, 1.0
	v_fmac_f32_e32 v70, v71, v70
	v_mul_f32_e32 v72, v69, v70
	v_fma_f32 v73, -v64, v72, v69
	v_fmac_f32_e32 v72, v73, v70
	v_fma_f32 v66, -v64, v72, v69
	v_fma_f32 v66, v66, v70, v72
	v_div_fixup_f32 v64, v66, v64, v69
	v_lshlrev_b32_e32 v66, 16, v67
	v_and_b32_e32 v67, 0xffff0000, v67
	v_pk_mul_f32 v[64:65], v[56:57], v[64:65]
	v_mul_f32_e32 v56, 0xbfb8aa3b, v66
	v_mul_f32_e32 v57, 0xbfb8aa3b, v67
	v_exp_f32_e32 v56, v56
	v_exp_f32_e32 v57, v57
	v_pk_mul_f32 v[58:59], v[62:63], v[58:59]
	v_pk_add_f32 v[56:57], v[56:57], 1.0 op_sel_hi:[1,0]
	s_nop 0
	v_rcp_f32_e32 v63, v57
	s_nop 0
	v_fma_f32 v69, -v57, v63, 1.0
	v_fmac_f32_e32 v63, v69, v63
	v_mul_f32_e32 v70, v67, v63
	v_fma_f32 v71, -v57, v70, v67
	v_fmac_f32_e32 v70, v71, v63
	v_fma_f32 v62, -v57, v70, v67
	v_fma_f32 v62, v62, v63, v70
	v_div_fixup_f32 v57, v62, v57, v67
	v_rcp_f32_e32 v63, v56
	s_mov_b64 s[10:11], 0
	v_fma_f32 v67, -v56, v63, 1.0
	v_fmac_f32_e32 v63, v67, v63
	v_mul_f32_e32 v69, v66, v63
	v_fma_f32 v70, -v56, v69, v66
	v_fmac_f32_e32 v69, v70, v63
	v_fma_f32 v62, -v56, v69, v66
	v_fma_f32 v62, v62, v63, v69
	v_div_fixup_f32 v56, v62, v56, v66
	v_pk_mul_f32 v[56:57], v[58:59], v[56:57]
	v_cvt_pk_bf16_f32 v62, v64, v65
	v_lshl_add_u64 v[58:59], v[60:61], 0, v[92:93]
	global_store_dword v[58:59], v62, off

; DI size_t kblk(int row, int col, int nrows) { return ((size_t)(col >> 5) * nrows + row) * 32 + (col & 31); }
; DI unsigned pk2(float a, float b) { hwf32x2 f = {a, b}; hwbf16x2 r = __builtin_convertvector(f, hwbf16x2); return __builtin_bit_cast(unsigned, r); }
; #define MFMA16(a, b, c) __builtin_amdgcn_mfma_f32_16x16x32_bf16((a), (b), (c), 0, 0, 0)
; template <int MX, bool OUT>
; DI void rec_chunk(const Params& p, int l, int b, int h, int dir, int T0, unsigned char* smem, f32x4 (&St)[4], float& nst, float& dtot, int tid, const RecRaw& raw) {
;     ...
; #pragma unroll
;     for (int ks = 0; ks < 2; ++ks) {
;       const bf16x8 fb = *(const bf16x8*)(smem + L_QS + swz(t, ks * 4 + g));
; #pragma unroll
;       for (int a = 0; a < 4; ++a) {
;         const bf16x8 fa = *(const bf16x8*)(smem + L_STT + swz(16 * a + col, ks * 4 + g));
;         O[a] = MFMA16(fa, fb, O[a]);
;       }
;     }
;     if (MX == 1) {
;       const float inv = 1.f / fmaxf(fabsf(den), 1.f);
; #pragma unroll
;       for (int a = 0; a < 4; ++a)
; #pragma unroll
;         for (int j = 0; j < 4; ++j) O[a][j] *= inv;
;     }
;     if (dir == 0) {
; #pragma unroll
;       for (int a = 0; a < 4; ++a) *(uint2*)(MIX + kblk((int)orow, cb + 16 * a + 4 * g, ROWS)) = make_uint2(pk2(O[a][0], O[a][1]), pk2(O[a][2], O[a][3]));
;     } else {
;       float ss = 0.f;
; #pragma unroll
;       for (int a = 0; a < 4; ++a) {
;         const uint2 u = *(const uint2*)(MIX + kblk((int)orow, cb + 16 * a + 4 * g, ROWS));
;         O[a][0] += __uint_as_float(u.x << 16); O[a][1] += __uint_as_float(u.x & 0xffff0000u);
.LBB0_928:
	s_or_b64 exec, exec, s[0:1]
	ds_read_b128 v[42:45], v242 offset:32768
	ds_read_b128 v[46:49], v240 offset:57344
	ds_read_b128 v[50:53], v240 offset:59392
	s_add_i32 s0, s54, -1
	v_mov_b32_e32 v40, s0
	v_cndmask_b32_e64 v40, v93, v40, s[40:41]
	s_waitcnt lgkmcnt(1)
	v_mfma_f32_16x16x32_bf16 v[46:49], v[46:49], v[42:45], v[56:59]
	v_lshlrev_b32_e32 v40, 6, v40
	v_add_u32_e32 v40, s49, v40
	v_mov_b32_e32 v41, v161
	ds_read_b128 v[54:57], v240 offset:61440
	s_waitcnt lgkmcnt(1)
	v_mfma_f32_16x16x32_bf16 v[50:53], v[50:53], v[42:45], v[60:63]
	v_lshl_add_u64 v[40:41], v[40:41], 0, v[84:85]
	s_nop 1
	ds_read_b128 v[58:61], v240 offset:63488
	s_waitcnt lgkmcnt(1)
	v_mfma_f32_16x16x32_bf16 v[54:57], v[54:57], v[42:45], v[64:67]
	s_waitcnt lgkmcnt(0)
	v_mfma_f32_16x16x32_bf16 v[42:45], v[58:61], v[42:45], v[72:75]
	ds_read_b128 v[58:61], v241 offset:32768
	ds_read_b128 v[62:65], v239 offset:57344
	s_waitcnt lgkmcnt(0)
	v_mfma_f32_16x16x32_bf16 v[46:49], v[62:65], v[58:61], v[46:49]
	ds_read_b128 v[62:65], v239 offset:59392
	s_waitcnt lgkmcnt(0)
	v_mfma_f32_16x16x32_bf16 v[50:53], v[62:65], v[58:61], v[50:53]
	ds_read_b128 v[62:65], v239 offset:61440
	s_waitcnt lgkmcnt(0)
	v_mfma_f32_16x16x32_bf16 v[62:65], v[62:65], v[58:61], v[54:57]
	s_nop 2
	ds_read_b128 v[54:57], v239 offset:63488
	s_waitcnt lgkmcnt(0)
	v_mfma_f32_16x16x32_bf16 v[42:45], v[54:57], v[58:61], v[42:45]
	v_add_f32_e32 v54, v95, v100
	v_max_f32_e64 v54, |v54|, 1.0
	v_rcp_f32_e32 v56, v54
	s_mov_b64 s[0:1], -1
	v_fma_f32 v57, -v54, v56, 1.0
	v_fmac_f32_e32 v56, v57, v56
	v_mul_f32_e32 v58, 1.0, v56
	v_fma_f32 v59, -v54, v58, 1.0
	v_fmac_f32_e32 v58, v59, v56
	v_fma_f32 v55, -v54, v58, 1.0
	v_fma_f32 v55, v55, v56, v58
	v_div_fixup_f32 v60, v55, v54, 1.0
	v_pk_mul_f32 v[54:55], v[60:61], v[46:47] op_sel_hi:[0,1]
	v_pk_mul_f32 v[46:47], v[60:61], v[42:43] op_sel_hi:[0,1]
	v_ashrrev_i32_e32 v43, 31, v40
	v_mov_b32_e32 v42, v40
	v_pk_mul_f32 v[58:59], v[60:61], v[48:49] op_sel_hi:[0,1]
	v_pk_mul_f32 v[50:51], v[60:61], v[50:51] op_sel_hi:[0,1]
	v_pk_mul_f32 v[56:57], v[60:61], v[52:53] op_sel_hi:[0,1]
	v_pk_mul_f32 v[48:49], v[60:61], v[62:63] op_sel_hi:[0,1]
	v_pk_mul_f32 v[52:53], v[60:61], v[64:65] op_sel_hi:[0,1]
	v_pk_mul_f32 v[44:45], v[60:61], v[44:45] op_sel_hi:[0,1]
	v_lshl_add_u64 v[60:61], v[42:43], 0, s[42:43]
	v_lshl_add_u64 v[62:63], v[42:43], 0, s[28:29]
	v_lshl_add_u64 v[42:43], v[42:43], 0, s[30:31]
	s_andn2_b64 vcc, exec, s[12:13]
	v_lshlrev_b64 v[64:65], 6, v[60:61]
	v_lshlrev_b64 v[62:63], 6, v[62:63]
	v_lshlrev_b64 v[60:61], 6, v[42:43]
	s_cbranch_vccnz .LBB0_930
	v_lshl_add_u64 v[102:103], v[90:91], 0, v[62:63]
	global_load_dwordx2 v[66:67], v[102:103], off
	v_mov_b64_e32 v[42:43], s[24:25]
	v_mad_u64_u32 v[42:43], s[0:1], v40, s33, v[42:43]
	v_mad_i32_i24 v43, v41, s33, v43
	s_mov_b64 s[0:1], 0x1a20
	v_mov_b32_e32 v93, v161
	v_lshl_add_u64 v[74:75], v[42:43], 0, s[0:1]
	v_lshl_add_u64 v[104:105], v[74:75], 0, s[2:3]
	v_lshl_add_u64 v[74:75], v[74:75], 0, v[92:93]
	v_lshl_add_u64 v[106:107], v[86:87], 0, v[64:65]
	v_lshl_add_u64 v[74:75], v[74:75], 0, s[2:3]
	global_load_dwordx2 v[40:41], v[106:107], off
	s_mov_b32 s21, s3
	v_lshl_add_u64 v[42:43], v[42:43], 0, s[20:21]
	v_lshl_add_u64 v[42:43], v[42:43], 0, v[92:93]
	s_mov_b64 s[0:1], 0x1820
	v_lshl_add_u64 v[104:105], v[104:105], 0, v[92:93]
	global_load_dwordx2 v[74:75], v[74:75], off
	s_waitcnt vmcnt(0) lgkmcnt(0)
	v_lshlrev_b32_e32 v100, 16, v66
	v_and_b32_e32 v101, 0xffff0000, v66
	v_lshlrev_b32_e32 v108, 16, v67
	v_and_b32_e32 v109, 0xffff0000, v67
	v_lshl_add_u64 v[66:67], s[22:23], 0, v[60:61]
	v_lshl_add_u64 v[72:73], v[66:67], 0, v[92:93]
	global_load_dwordx2 v[68:69], v[72:73], off
	v_lshlrev_b32_e32 v128, 16, v40
	v_and_b32_e32 v129, 0xffff0000, v40
	v_lshlrev_b32_e32 v40, 16, v41
	v_and_b32_e32 v41, 0xffff0000, v41
	v_pk_add_f32 v[128:129], v[54:55], v[128:129]
	v_lshlrev_b32_e32 v95, 16, v74
	v_and_b32_e32 v243, 0xffff0000, v74
	v_lshlrev_b32_e32 v130, 16, v75
	v_and_b32_e32 v131, 0xffff0000, v75
	v_lshl_add_u64 v[74:75], v[42:43], 0, s[0:1]
	v_add_co_u32_e32 v42, vcc, s16, v42
	v_mul_f32_e32 v120, 0xbfb8aa3b, v130
	s_nop 0
	v_addc_co_u32_e32 v43, vcc, 0, v43, vcc
	v_mul_f32_e32 v121, 0xbfb8aa3b, v131
	global_load_dwordx2 v[42:43], v[42:43], off offset:2080
	v_exp_f32_e32 v120, v120
	v_exp_f32_e32 v121, v121
	s_waitcnt vmcnt(0) lgkmcnt(0)
; DI size_t kblk(int row, int col, int nrows) { return ((size_t)(col >> 5) * nrows + row) * 32 + (col & 31); }
; DI unsigned pk2(float a, float b) { hwf32x2 f = {a, b}; hwbf16x2 r = __builtin_convertvector(f, hwbf16x2); return __builtin_bit_cast(unsigned, r); }
; DI float sigmoidf_(float z) { return 1.f / (1.f + __expf(-z)); }
; DI float siluf_(float z) { return z / (1.f + __expf(-z)); }
; template <int MX, bool OUT>
; DI void rec_chunk(const Params& p, int l, int b, int h, int dir, int T0, unsigned char* smem, f32x4 (&St)[4], float& nst, float& dtot, int tid, const RecRaw& raw) {
;     ...
;       float ss = 0.f;
; #pragma unroll
;       for (int a = 0; a < 4; ++a) {
;         const uint2 u = *(const uint2*)(MIX + kblk((int)orow, cb + 16 * a + 4 * g, ROWS));
;         O[a][0] += __uint_as_float(u.x << 16); O[a][1] += __uint_as_float(u.x & 0xffff0000u);
;         O[a][2] += __uint_as_float(u.y << 16); O[a][3] += __uint_as_float(u.y & 0xffff0000u);
; #pragma unroll
;         for (int j = 0; j < 4; ++j) ss += O[a][j] * O[a][j];
;       }
;       ss += __shfl_xor(ss, 16);
;       ss += __shfl_xor(ss, 32);
;       const float rstd = rsqrtf(ss * (1.f / 64.f) + EPS);
;       const float* gvec = (MX ? p.ml_g : p.hg_g) + l * 64;
; #pragma unroll
;       for (int a = 0; a < 4; ++a) {
;         const int v0 = 16 * a + 4 * g;
;         const uint2 gt = *(const uint2*)(prow + GATE + cb + v0);
;         const float4 gg = *(const float4*)(gvec + v0);
;         float y0 = O[a][0] * rstd * gg.x * siluf_(__uint_as_float(gt.x << 16));
;         float y1 = O[a][1] * rstd * gg.y * siluf_(__uint_as_float(gt.x & 0xffff0000u));
;         float y2 = O[a][2] * rstd * gg.z * siluf_(__uint_as_float(gt.y << 16));
;         float y3 = O[a][3] * rstd * gg.w * siluf_(__uint_as_float(gt.y & 0xffff0000u));
;         if (MX == 1) {
;           const uint2 og = *(const uint2*)(prow + D_OG + h * 64 + v0);
;           y0 *= sigmoidf_(__uint_as_float(og.x << 16)); y1 *= sigmoidf_(__uint_as_float(og.x & 0xffff0000u));
;           y2 *= sigmoidf_(__uint_as_float(og.y << 16)); y3 *= sigmoidf_(__uint_as_float(og.y & 0xffff0000u));
;         }
;         *(uint2*)(MIX + kblk((int)orow, cb + v0, ROWS)) = make_uint2(pk2(y0, y1), pk2(y2, y3));
	v_lshlrev_b32_e32 v110, 16, v68
	v_and_b32_e32 v111, 0xffff0000, v68
	v_pk_add_f32 v[120:121], v[120:121], 1.0 op_sel_hi:[1,0]
	v_lshlrev_b32_e32 v112, 16, v69
	v_rcp_f32_e32 v70, v120
	v_rcp_f32_e32 v71, v121
	s_nop 0
	v_pk_fma_f32 v[116:117], v[120:121], v[70:71], 1.0 op_sel_hi:[1,1,0] neg_lo:[1,0,0] neg_hi:[1,0,0]
	v_pk_fma_f32 v[70:71], v[116:117], v[70:71], v[70:71]
	v_pk_mul_f32 v[114:115], v[130:131], v[70:71]
	v_pk_fma_f32 v[116:117], v[120:121], v[114:115], v[130:131] neg_lo:[1,0,0] neg_hi:[1,0,0]
	v_pk_fma_f32 v[114:115], v[116:117], v[70:71], v[114:115]
	v_pk_fma_f32 v[116:117], v[120:121], v[114:115], v[130:131] neg_lo:[1,0,0] neg_hi:[1,0,0]
	v_pk_fma_f32 v[114:115], v[116:117], v[70:71], v[114:115]
	v_div_fixup_f32 v120, v114, v120, v130
	v_div_fixup_f32 v121, v115, v121, v131
	v_and_b32_e32 v113, 0xffff0000, v69
	global_load_dwordx2 v[68:69], v[72:73], off offset:32
	v_pk_add_f32 v[110:111], v[48:49], v[110:111]
	v_pk_mul_f32 v[250:251], v[110:111], v[110:111]
	v_lshlrev_b32_e32 v118, 16, v42
	v_and_b32_e32 v42, 0xffff0000, v42
	v_mul_f32_e32 v132, 0xbfb8aa3b, v95
	v_mul_f32_e32 v133, 0xbfb8aa3b, v243
	v_exp_f32_e32 v132, v132
	v_exp_f32_e32 v133, v133
	v_pk_mul_f32 v[130:131], v[128:129], v[128:129]
	v_mul_f32_e32 v118, 0xbfb8aa3b, v118
	v_pk_add_f32 v[132:133], v[132:133], 1.0 op_sel_hi:[1,0]
	v_mul_f32_e32 v42, 0xbfb8aa3b, v42
	v_mov_b32_e32 v122, v95
	v_mov_b32_e32 v123, v243
	v_rcp_f32_e32 v70, v132
	v_rcp_f32_e32 v71, v133
	s_nop 0
	v_pk_fma_f32 v[116:117], v[132:133], v[70:71], 1.0 op_sel_hi:[1,1,0] neg_lo:[1,0,0] neg_hi:[1,0,0]
	v_pk_fma_f32 v[70:71], v[116:117], v[70:71], v[70:71]
	v_pk_mul_f32 v[114:115], v[122:123], v[70:71]
	v_pk_fma_f32 v[116:117], v[132:133], v[114:115], v[122:123] neg_lo:[1,0,0] neg_hi:[1,0,0]
	v_pk_fma_f32 v[114:115], v[116:117], v[70:71], v[114:115]
	v_pk_fma_f32 v[116:117], v[132:133], v[114:115], v[122:123] neg_lo:[1,0,0] neg_hi:[1,0,0]
	v_pk_fma_f32 v[114:115], v[116:117], v[70:71], v[114:115]
	v_div_fixup_f32 v132, v114, v132, v95
	v_div_fixup_f32 v133, v115, v133, v243
	v_add_f32_e32 v93, v130, v131
	v_exp_f32_e32 v126, v118
	v_exp_f32_e32 v127, v42
	v_lshlrev_b32_e32 v42, 16, v43
	v_pk_add_f32 v[118:119], v[58:59], v[40:41]
	v_pk_add_f32 v[248:249], v[50:51], v[100:101]
	v_pk_mul_f32 v[100:101], v[248:249], v[248:249]
	v_mul_f32_e32 v42, 0xbfb8aa3b, v42
	v_pk_mul_f32 v[122:123], v[118:119], v[118:119]
	v_exp_f32_e32 v124, v42
	v_and_b32_e32 v42, 0xffff0000, v43
	v_add_f32_e32 v93, v93, v122
	v_mul_f32_e32 v42, 0xbfb8aa3b, v42
	v_add_f32_e32 v93, v123, v93
	v_pk_add_f32 v[126:127], v[126:127], 1.0 op_sel_hi:[1,0]
	v_exp_f32_e32 v125, v42
	global_load_dwordx4 v[40:43], v[88:89], off
	v_rcp_f32_e32 v70, v126
	v_rcp_f32_e32 v71, v127
	s_nop 0
	v_pk_fma_f32 v[116:117], v[126:127], v[70:71], 1.0 op_sel_hi:[1,1,0] neg_lo:[1,0,0] neg_hi:[1,0,0]
	v_pk_fma_f32 v[70:71], v[116:117], v[70:71], v[70:71]
	v_pk_mul_f32 v[114:115], v[70:71], 1.0 op_sel_hi:[1,0]
	v_pk_fma_f32 v[116:117], v[126:127], v[114:115], 1.0 op_sel_hi:[1,1,0] neg_lo:[1,0,0] neg_hi:[1,0,0]
	v_pk_fma_f32 v[114:115], v[116:117], v[70:71], v[114:115]
	v_pk_fma_f32 v[116:117], v[126:127], v[114:115], 1.0 op_sel_hi:[1,1,0] neg_lo:[1,0,0] neg_hi:[1,0,0]
	v_pk_fma_f32 v[114:115], v[116:117], v[70:71], v[114:115]
	v_div_fixup_f32 v126, v114, v126, 1.0
	v_div_fixup_f32 v127, v115, v127, 1.0
	v_pk_add_f32 v[124:125], v[124:125], 1.0 op_sel_hi:[1,0]
	v_add_f32_e32 v93, v100, v93
	v_add_f32_e32 v93, v101, v93
	s_waitcnt vmcnt(0) lgkmcnt(0)
	v_lshlrev_b32_e32 v70, 16, v68
	v_and_b32_e32 v71, 0xffff0000, v68
	v_pk_add_f32 v[70:71], v[46:47], v[70:71]
	v_rcp_f32_e32 v243, v125
	v_lshlrev_b32_e32 v68, 16, v69
	v_and_b32_e32 v69, 0xffff0000, v69
	v_pk_mul_f32 v[114:115], v[70:71], v[70:71]
	v_fma_f32 v244, -v125, v243, 1.0
	v_fmac_f32_e32 v243, v244, v243
	v_mul_f32_e32 v245, 1.0, v243
	v_fma_f32 v246, -v125, v245, 1.0
	v_fmac_f32_e32 v245, v246, v243
	v_fma_f32 v95, -v125, v245, 1.0
	v_fma_f32 v95, v95, v243, v245
	v_div_fixup_f32 v125, v95, v125, 1.0
	v_div_scale_f32 v95, s[0:1], v124, v124, 1.0
	v_rcp_f32_e32 v243, v95
	v_pk_add_f32 v[68:69], v[44:45], v[68:69]
	v_fma_f32 v244, -v95, v243, 1.0
	v_fmac_f32_e32 v243, v244, v243
	v_div_scale_f32 v244, vcc, 1.0, v124, 1.0
	v_mul_f32_e32 v245, v244, v243
	v_fma_f32 v246, -v95, v245, v244
	v_fmac_f32_e32 v245, v246, v243
	v_fma_f32 v95, -v95, v245, v244
	v_div_fmas_f32 v95, v95, v243, v245
	v_pk_add_f32 v[244:245], v[56:57], v[108:109]
	v_pk_add_f32 v[108:109], v[52:53], v[112:113]
	v_pk_mul_f32 v[246:247], v[244:245], v[244:245]
	v_pk_mul_f32 v[112:113], v[108:109], v[108:109]
	v_add_f32_e32 v93, v246, v93
	v_add_f32_e32 v93, v247, v93
	v_add_f32_e32 v93, v250, v93
	v_add_f32_e32 v93, v251, v93
	v_add_f32_e32 v93, v112, v93
	v_add_f32_e32 v93, v113, v93
	v_add_f32_e32 v93, v114, v93
	v_pk_mul_f32 v[116:117], v[68:69], v[68:69]
	v_add_f32_e32 v93, v115, v93
	v_add_f32_e32 v93, v116, v93
	v_add_f32_e32 v93, v117, v93
	v_div_fixup_f32 v124, v95, v124, 1.0
	ds_bpermute_b32 v95, v149, v93
	s_waitcnt lgkmcnt(0)
	v_add_f32_e32 v93, v93, v95
	ds_bpermute_b32 v95, v150, v93
	s_waitcnt lgkmcnt(0)
; DI size_t kblk(int row, int col, int nrows) { return ((size_t)(col >> 5) * nrows + row) * 32 + (col & 31); }
; DI unsigned pk2(float a, float b) { hwf32x2 f = {a, b}; hwbf16x2 r = __builtin_convertvector(f, hwbf16x2); return __builtin_bit_cast(unsigned, r); }
; DI float sigmoidf_(float z) { return 1.f / (1.f + __expf(-z)); }
; DI float siluf_(float z) { return z / (1.f + __expf(-z)); }
; template <int MX, bool OUT>
; DI void rec_chunk(const Params& p, int l, int b, int h, int dir, int T0, unsigned char* smem, f32x4 (&St)[4], float& nst, float& dtot, int tid, const RecRaw& raw) {
;     ...
;       ss += __shfl_xor(ss, 16);
;       ss += __shfl_xor(ss, 32);
;       const float rstd = rsqrtf(ss * (1.f / 64.f) + EPS);
;       const float* gvec = (MX ? p.ml_g : p.hg_g) + l * 64;
; #pragma unroll
;       for (int a = 0; a < 4; ++a) {
;         const int v0 = 16 * a + 4 * g;
;         const uint2 gt = *(const uint2*)(prow + GATE + cb + v0);
;         const float4 gg = *(const float4*)(gvec + v0);
;         float y0 = O[a][0] * rstd * gg.x * siluf_(__uint_as_float(gt.x << 16));
;         float y1 = O[a][1] * rstd * gg.y * siluf_(__uint_as_float(gt.x & 0xffff0000u));
;         float y2 = O[a][2] * rstd * gg.z * siluf_(__uint_as_float(gt.y << 16));
;         float y3 = O[a][3] * rstd * gg.w * siluf_(__uint_as_float(gt.y & 0xffff0000u));
;         if (MX == 1) {
;           const uint2 og = *(const uint2*)(prow + D_OG + h * 64 + v0);
;           y0 *= sigmoidf_(__uint_as_float(og.x << 16)); y1 *= sigmoidf_(__uint_as_float(og.x & 0xffff0000u));
;           y2 *= sigmoidf_(__uint_as_float(og.y << 16)); y3 *= sigmoidf_(__uint_as_float(og.y & 0xffff0000u));
;         }
;         *(uint2*)(MIX + kblk((int)orow, cb + v0, ROWS)) = make_uint2(pk2(y0, y1), pk2(y2, y3));
	v_add_f32_e32 v93, v93, v95
	v_fmamk_f32 v93, v93, 0x3c800000, v162
	v_cmp_gt_f32_e32 vcc, s38, v93
	v_mul_f32_e32 v95, 0x4b800000, v93
	s_nop 0
	v_cndmask_b32_e32 v93, v93, v95, vcc
	v_rsq_f32_e32 v93, v93
	s_nop 0
	v_mul_f32_e32 v95, 0x45800000, v93
	v_cndmask_b32_e32 v100, v93, v95, vcc
	v_pk_mul_f32 v[112:113], v[128:129], v[100:101] op_sel_hi:[1,0]
	s_nop 0
	v_pk_mul_f32 v[40:41], v[40:41], v[112:113]
	v_pk_mul_f32 v[112:113], v[118:119], v[100:101] op_sel_hi:[1,0]
	v_pk_mul_f32 v[40:41], v[132:133], v[40:41]
	v_pk_mul_f32 v[42:43], v[42:43], v[112:113]
	v_pk_mul_f32 v[40:41], v[126:127], v[40:41]
	v_pk_mul_f32 v[42:43], v[120:121], v[42:43]
	v_cvt_pk_bf16_f32 v40, v40, v41
	v_pk_mul_f32 v[42:43], v[124:125], v[42:43]
	s_nop 0
	v_cvt_pk_bf16_f32 v41, v42, v43
	global_store_dwordx2 v[106:107], v[40:41], off
	global_load_dwordx2 v[40:41], v[104:105], off offset:32
	s_nop 0
	global_load_dwordx4 v[112:115], v[88:89], off offset:64
	v_pk_mul_f32 v[106:107], v[248:249], v[100:101] op_sel_hi:[1,0]
	s_waitcnt vmcnt(0) lgkmcnt(0)
	v_lshlrev_b32_e32 v93, 16, v40
	v_and_b32_e32 v40, 0xffff0000, v40
	v_mul_f32_e32 v42, 0xbfb8aa3b, v93
	v_mul_f32_e32 v43, 0xbfb8aa3b, v40
	v_exp_f32_e32 v42, v42
	v_exp_f32_e32 v43, v43
	v_pk_mul_f32 v[106:107], v[112:113], v[106:107]
	v_pk_add_f32 v[42:43], v[42:43], 1.0 op_sel_hi:[1,0]
	s_nop 0
	v_rcp_f32_e32 v101, v43
	s_nop 0
	v_fma_f32 v112, -v43, v101, 1.0
	v_fmac_f32_e32 v101, v112, v101
	v_mul_f32_e32 v113, v40, v101
	v_fma_f32 v116, -v43, v113, v40
	v_fmac_f32_e32 v113, v116, v101
	v_fma_f32 v95, -v43, v113, v40
	v_fma_f32 v95, v95, v101, v113
	v_div_fixup_f32 v43, v95, v43, v40
	v_rcp_f32_e32 v95, v42
	s_nop 0
	v_fma_f32 v101, -v42, v95, 1.0
	v_fmac_f32_e32 v95, v101, v95
	v_mul_f32_e32 v112, v93, v95
	v_fma_f32 v113, -v42, v112, v93
	v_fmac_f32_e32 v112, v113, v95
	v_fma_f32 v40, -v42, v112, v93
	v_fma_f32 v40, v40, v95, v112
	v_div_fixup_f32 v42, v40, v42, v93
	v_lshlrev_b32_e32 v93, 16, v41
	v_and_b32_e32 v95, 0xffff0000, v41
	v_mul_f32_e32 v40, 0xbfb8aa3b, v93
	v_mul_f32_e32 v41, 0xbfb8aa3b, v95
	v_exp_f32_e32 v40, v40
	v_exp_f32_e32 v41, v41
	v_pk_mul_f32 v[42:43], v[42:43], v[106:107]
	v_pk_mul_f32 v[106:107], v[244:245], v[100:101] op_sel_hi:[1,0]
	v_pk_add_f32 v[40:41], v[40:41], 1.0 op_sel_hi:[1,0]
	s_nop 0
	v_rcp_f32_e32 v112, v41
	v_pk_mul_f32 v[106:107], v[114:115], v[106:107]
	v_fma_f32 v113, -v41, v112, 1.0
	v_fmac_f32_e32 v112, v113, v112
	v_mul_f32_e32 v114, v95, v112
	v_fma_f32 v115, -v41, v114, v95
	v_fmac_f32_e32 v114, v115, v112
	v_fma_f32 v101, -v41, v114, v95
	v_fma_f32 v101, v101, v112, v114
	v_div_fixup_f32 v41, v101, v41, v95
	v_rcp_f32_e32 v101, v40
	s_nop 0
	v_fma_f32 v112, -v40, v101, 1.0
	v_fmac_f32_e32 v101, v112, v101
	v_mul_f32_e32 v113, v93, v101
	v_fma_f32 v114, -v40, v113, v93
	v_fmac_f32_e32 v113, v114, v101
	v_fma_f32 v95, -v40, v113, v93
	v_fma_f32 v95, v95, v101, v113
	v_div_fixup_f32 v40, v95, v40, v93
	v_pk_mul_f32 v[40:41], v[40:41], v[106:107]
	global_load_dwordx2 v[106:107], v[74:75], off offset:32
	s_waitcnt vmcnt(0) lgkmcnt(0)
	v_lshlrev_b32_e32 v93, 16, v106
	v_mul_f32_e32 v93, 0xbfb8aa3b, v93
	v_exp_f32_e32 v112, v93
	v_and_b32_e32 v93, 0xffff0000, v106
	v_mul_f32_e32 v93, 0xbfb8aa3b, v93
	v_exp_f32_e32 v113, v93
	s_nop 0
	v_pk_add_f32 v[112:113], v[112:113], 1.0 op_sel_hi:[1,0]
	s_nop 0
	v_rcp_f32_e32 v95, v113
	s_nop 0
	v_fma_f32 v101, -v113, v95, 1.0
	v_fmac_f32_e32 v95, v101, v95
	v_mul_f32_e32 v106, 1.0, v95
	v_fma_f32 v114, -v113, v106, 1.0
	v_fmac_f32_e32 v106, v114, v95
	v_fma_f32 v93, -v113, v106, 1.0
	v_fma_f32 v93, v93, v95, v106
	v_div_fixup_f32 v113, v93, v113, 1.0
	v_rcp_f32_e32 v95, v112
	s_nop 0
	v_fma_f32 v101, -v112, v95, 1.0
	v_fmac_f32_e32 v95, v101, v95
	v_mul_f32_e32 v106, 1.0, v95
	v_fma_f32 v114, -v112, v106, 1.0
	v_fmac_f32_e32 v106, v114, v95
	v_fma_f32 v93, -v112, v106, 1.0
	v_fma_f32 v93, v93, v95, v106
	v_div_fixup_f32 v112, v93, v112, 1.0
	v_lshlrev_b32_e32 v93, 16, v107
	v_mul_f32_e32 v93, 0xbfb8aa3b, v93
	v_exp_f32_e32 v106, v93
	v_and_b32_e32 v93, 0xffff0000, v107
	v_mul_f32_e32 v93, 0xbfb8aa3b, v93
	v_exp_f32_e32 v107, v93
	v_pk_mul_f32 v[42:43], v[42:43], v[112:113]
	v_pk_add_f32 v[106:107], v[106:107], 1.0 op_sel_hi:[1,0]
	s_nop 0
	v_rcp_f32_e32 v95, v107
	v_cvt_pk_bf16_f32 v42, v42, v43
	v_fma_f32 v101, -v107, v95, 1.0
	v_fmac_f32_e32 v95, v101, v95
	v_mul_f32_e32 v112, 1.0, v95
	v_fma_f32 v113, -v107, v112, 1.0
	v_fmac_f32_e32 v112, v113, v95
	v_fma_f32 v93, -v107, v112, 1.0
	v_fma_f32 v93, v93, v95, v112
	v_div_fixup_f32 v107, v93, v107, 1.0
	v_rcp_f32_e32 v95, v106
	s_nop 0
	v_fma_f32 v101, -v106, v95, 1.0
	v_fmac_f32_e32 v95, v101, v95
	v_mul_f32_e32 v112, 1.0, v95
	v_fma_f32 v113, -v106, v112, 1.0
	v_fmac_f32_e32 v112, v113, v95
	v_fma_f32 v93, -v106, v112, 1.0
	v_fma_f32 v93, v93, v95, v112
	v_div_fixup_f32 v106, v93, v106, 1.0
	v_pk_mul_f32 v[40:41], v[40:41], v[106:107]
	s_nop 0
	v_cvt_pk_bf16_f32 v43, v40, v41
	global_store_dwordx2 v[102:103], v[42:43], off
	global_load_dwordx2 v[40:41], v[104:105], off offset:64
	global_load_dwordx4 v[112:115], v[88:89], off offset:128
	v_pk_mul_f32 v[102:103], v[110:111], v[100:101] op_sel_hi:[1,0]
	s_waitcnt vmcnt(0) lgkmcnt(0)
; DI size_t kblk(int row, int col, int nrows) { return ((size_t)(col >> 5) * nrows + row) * 32 + (col & 31); }
; DI unsigned pk2(float a, float b) { hwf32x2 f = {a, b}; hwbf16x2 r = __builtin_convertvector(f, hwbf16x2); return __builtin_bit_cast(unsigned, r); }
; DI float sigmoidf_(float z) { return 1.f / (1.f + __expf(-z)); }
; DI float siluf_(float z) { return z / (1.f + __expf(-z)); }
; template <int MX, bool OUT>
; DI void rec_chunk(const Params& p, int l, int b, int h, int dir, int T0, unsigned char* smem, f32x4 (&St)[4], float& nst, float& dtot, int tid, const RecRaw& raw) {
;     ...
;       for (int a = 0; a < 4; ++a) {
;         const int v0 = 16 * a + 4 * g;
;         const uint2 gt = *(const uint2*)(prow + GATE + cb + v0);
;         const float4 gg = *(const float4*)(gvec + v0);
;         float y0 = O[a][0] * rstd * gg.x * siluf_(__uint_as_float(gt.x << 16));
;         float y1 = O[a][1] * rstd * gg.y * siluf_(__uint_as_float(gt.x & 0xffff0000u));
;         float y2 = O[a][2] * rstd * gg.z * siluf_(__uint_as_float(gt.y << 16));
;         float y3 = O[a][3] * rstd * gg.w * siluf_(__uint_as_float(gt.y & 0xffff0000u));
;         if (MX == 1) {
;           const uint2 og = *(const uint2*)(prow + D_OG + h * 64 + v0);
;           y0 *= sigmoidf_(__uint_as_float(og.x << 16)); y1 *= sigmoidf_(__uint_as_float(og.x & 0xffff0000u));
;           y2 *= sigmoidf_(__uint_as_float(og.y << 16)); y3 *= sigmoidf_(__uint_as_float(og.y & 0xffff0000u));
;         }
;         *(uint2*)(MIX + kblk((int)orow, cb + v0, ROWS)) = make_uint2(pk2(y0, y1), pk2(y2, y3));
	v_lshlrev_b32_e32 v93, 16, v40
	v_and_b32_e32 v40, 0xffff0000, v40
	v_mul_f32_e32 v42, 0xbfb8aa3b, v93
	v_mul_f32_e32 v43, 0xbfb8aa3b, v40
	v_exp_f32_e32 v42, v42
	v_exp_f32_e32 v43, v43
	v_pk_mul_f32 v[102:103], v[102:103], v[112:113]
	v_pk_add_f32 v[42:43], v[42:43], 1.0 op_sel_hi:[1,0]
	s_nop 0
	v_rcp_f32_e32 v101, v43
	s_nop 0
	v_fma_f32 v106, -v43, v101, 1.0
	v_fmac_f32_e32 v101, v106, v101
	v_mul_f32_e32 v107, v40, v101
	v_fma_f32 v110, -v43, v107, v40
	v_fmac_f32_e32 v107, v110, v101
	v_fma_f32 v95, -v43, v107, v40
	v_fma_f32 v95, v95, v101, v107
	v_div_fixup_f32 v43, v95, v43, v40
	v_rcp_f32_e32 v95, v42
	s_nop 0
	v_fma_f32 v101, -v42, v95, 1.0
	v_fmac_f32_e32 v95, v101, v95
	v_mul_f32_e32 v106, v93, v95
	v_fma_f32 v107, -v42, v106, v93
	v_fmac_f32_e32 v106, v107, v95
	v_fma_f32 v40, -v42, v106, v93
	v_fma_f32 v40, v40, v95, v106
	v_div_fixup_f32 v42, v40, v42, v93
	v_lshlrev_b32_e32 v93, 16, v41
	v_and_b32_e32 v95, 0xffff0000, v41
	v_mul_f32_e32 v40, 0xbfb8aa3b, v93
	v_mul_f32_e32 v41, 0xbfb8aa3b, v95
	v_exp_f32_e32 v40, v40
	v_exp_f32_e32 v41, v41
	v_pk_mul_f32 v[42:43], v[102:103], v[42:43]
	v_pk_mul_f32 v[102:103], v[108:109], v[100:101] op_sel_hi:[1,0]
	v_pk_add_f32 v[40:41], v[40:41], 1.0 op_sel_hi:[1,0]
	s_nop 0
	v_rcp_f32_e32 v106, v41
	v_pk_mul_f32 v[102:103], v[102:103], v[114:115]
	v_fma_f32 v107, -v41, v106, 1.0
	v_fmac_f32_e32 v106, v107, v106
	v_mul_f32_e32 v108, v95, v106
	v_fma_f32 v109, -v41, v108, v95
	v_fmac_f32_e32 v108, v109, v106
	v_fma_f32 v101, -v41, v108, v95
	v_fma_f32 v101, v101, v106, v108
	v_div_fixup_f32 v41, v101, v41, v95
	v_rcp_f32_e32 v101, v40
	s_nop 0
	v_fma_f32 v106, -v40, v101, 1.0
	v_fmac_f32_e32 v101, v106, v101
	v_mul_f32_e32 v107, v93, v101
	v_fma_f32 v108, -v40, v107, v93
	v_fmac_f32_e32 v107, v108, v101
	v_fma_f32 v95, -v40, v107, v93
	v_fma_f32 v95, v95, v101, v107
	v_div_fixup_f32 v40, v95, v40, v93
	v_pk_mul_f32 v[40:41], v[102:103], v[40:41]
	global_load_dwordx2 v[102:103], v[74:75], off offset:64
	s_waitcnt vmcnt(0) lgkmcnt(0)
	v_lshlrev_b32_e32 v93, 16, v102
	v_mul_f32_e32 v93, 0xbfb8aa3b, v93
	v_exp_f32_e32 v106, v93
	v_and_b32_e32 v93, 0xffff0000, v102
	v_mul_f32_e32 v93, 0xbfb8aa3b, v93
	v_exp_f32_e32 v107, v93
	s_nop 0
	v_pk_add_f32 v[106:107], v[106:107], 1.0 op_sel_hi:[1,0]
	s_nop 0
	v_rcp_f32_e32 v95, v107
	s_nop 0
	v_fma_f32 v101, -v107, v95, 1.0
	v_fmac_f32_e32 v95, v101, v95
	v_mul_f32_e32 v102, 1.0, v95
	v_fma_f32 v108, -v107, v102, 1.0
	v_fmac_f32_e32 v102, v108, v95
	v_fma_f32 v93, -v107, v102, 1.0
	v_fma_f32 v93, v93, v95, v102
	v_div_fixup_f32 v107, v93, v107, 1.0
	v_rcp_f32_e32 v95, v106
	s_nop 0
	v_fma_f32 v101, -v106, v95, 1.0
	v_fmac_f32_e32 v95, v101, v95
	v_mul_f32_e32 v102, 1.0, v95
	v_fma_f32 v108, -v106, v102, 1.0
	v_fmac_f32_e32 v102, v108, v95
	v_fma_f32 v93, -v106, v102, 1.0
	v_fma_f32 v93, v93, v95, v102
	v_div_fixup_f32 v106, v93, v106, 1.0
	v_lshlrev_b32_e32 v93, 16, v103
	v_mul_f32_e32 v93, 0xbfb8aa3b, v93
	v_exp_f32_e32 v102, v93
	v_and_b32_e32 v93, 0xffff0000, v103
	v_mul_f32_e32 v93, 0xbfb8aa3b, v93
	v_exp_f32_e32 v103, v93
	v_pk_mul_f32 v[42:43], v[42:43], v[106:107]
	v_pk_add_f32 v[102:103], v[102:103], 1.0 op_sel_hi:[1,0]
	s_nop 0
	v_rcp_f32_e32 v95, v103
	v_cvt_pk_bf16_f32 v42, v42, v43
	v_fma_f32 v101, -v103, v95, 1.0
	v_fmac_f32_e32 v95, v101, v95
	v_mul_f32_e32 v106, 1.0, v95
	v_fma_f32 v107, -v103, v106, 1.0
	v_fmac_f32_e32 v106, v107, v95
	v_fma_f32 v93, -v103, v106, 1.0
	v_fma_f32 v93, v93, v95, v106
	v_div_fixup_f32 v103, v93, v103, 1.0
	v_rcp_f32_e32 v95, v102
	s_nop 0
	v_fma_f32 v101, -v102, v95, 1.0
	v_fmac_f32_e32 v95, v101, v95
	v_mul_f32_e32 v106, 1.0, v95
	v_fma_f32 v107, -v102, v106, 1.0
	v_fmac_f32_e32 v106, v107, v95
	v_fma_f32 v93, -v102, v106, 1.0
	v_fma_f32 v93, v93, v95, v106
	v_div_fixup_f32 v102, v93, v102, 1.0
	v_pk_mul_f32 v[40:41], v[40:41], v[102:103]
	s_nop 0
	v_cvt_pk_bf16_f32 v43, v40, v41
	global_store_dwordx2 v[72:73], v[42:43], off
	global_load_dwordx2 v[40:41], v[104:105], off offset:96
	s_nop 0
	global_load_dwordx2 v[74:75], v[74:75], off offset:96
	s_waitcnt vmcnt(0) lgkmcnt(0)
; DI size_t kblk(int row, int col, int nrows) { return ((size_t)(col >> 5) * nrows + row) * 32 + (col & 31); }
; DI unsigned pk2(float a, float b) { hwf32x2 f = {a, b}; hwbf16x2 r = __builtin_convertvector(f, hwbf16x2); return __builtin_bit_cast(unsigned, r); }
; DI float sigmoidf_(float z) { return 1.f / (1.f + __expf(-z)); }
; DI float siluf_(float z) { return z / (1.f + __expf(-z)); }
; template <int MX, bool OUT>
; DI void rec_chunk(const Params& p, int l, int b, int h, int dir, int T0, unsigned char* smem, f32x4 (&St)[4], float& nst, float& dtot, int tid, const RecRaw& raw) {
;     ...
;       for (int a = 0; a < 4; ++a) {
;         const int v0 = 16 * a + 4 * g;
;         const uint2 gt = *(const uint2*)(prow + GATE + cb + v0);
;         const float4 gg = *(const float4*)(gvec + v0);
;         float y0 = O[a][0] * rstd * gg.x * siluf_(__uint_as_float(gt.x << 16));
;         float y1 = O[a][1] * rstd * gg.y * siluf_(__uint_as_float(gt.x & 0xffff0000u));
;         float y2 = O[a][2] * rstd * gg.z * siluf_(__uint_as_float(gt.y << 16));
;         float y3 = O[a][3] * rstd * gg.w * siluf_(__uint_as_float(gt.y & 0xffff0000u));
;         if (MX == 1) {
;           const uint2 og = *(const uint2*)(prow + D_OG + h * 64 + v0);
;           y0 *= sigmoidf_(__uint_as_float(og.x << 16)); y1 *= sigmoidf_(__uint_as_float(og.x & 0xffff0000u));
;           y2 *= sigmoidf_(__uint_as_float(og.y << 16)); y3 *= sigmoidf_(__uint_as_float(og.y & 0xffff0000u));
;         }
;         *(uint2*)(MIX + kblk((int)orow, cb + v0, ROWS)) = make_uint2(pk2(y0, y1), pk2(y2, y3));
	v_lshlrev_b32_e32 v73, 16, v40
	v_and_b32_e32 v93, 0xffff0000, v40
	v_lshlrev_b32_e32 v40, 16, v41
	v_mul_f32_e32 v42, 0xbfb8aa3b, v40
	v_exp_f32_e32 v42, v42
	s_nop 0
	v_add_f32_e32 v42, 1.0, v42
	v_rcp_f32_e32 v72, v42
	s_nop 0
	v_fma_f32 v95, -v42, v72, 1.0
	v_fmac_f32_e32 v72, v95, v72
	v_mul_f32_e32 v101, v40, v72
	v_fma_f32 v102, -v42, v101, v40
	v_fmac_f32_e32 v101, v102, v72
	v_fma_f32 v43, -v42, v101, v40
	v_fma_f32 v43, v43, v72, v101
	v_and_b32_e32 v95, 0xffff0000, v41
	v_div_fixup_f32 v72, v43, v42, v40
	v_mul_f32_e32 v40, 0xbfb8aa3b, v95
	v_exp_f32_e32 v102, v40
	v_lshlrev_b32_e32 v40, 16, v74
	v_mul_f32_e32 v40, 0xbfb8aa3b, v40
	v_exp_f32_e32 v104, v40
	v_and_b32_e32 v40, 0xffff0000, v74
	v_mul_f32_e32 v40, 0xbfb8aa3b, v40
	v_exp_f32_e32 v105, v40
	global_load_dwordx4 v[40:43], v[88:89], off offset:192
	v_pk_mul_f32 v[70:71], v[70:71], v[100:101] op_sel_hi:[1,0]
	v_mul_f32_e32 v74, 0xbfb8aa3b, v73
	v_exp_f32_e32 v106, v74
	s_waitcnt vmcnt(0)
	v_pk_mul_f32 v[40:41], v[70:71], v[40:41]
	v_mul_f32_e32 v70, 0xbfb8aa3b, v93
	v_exp_f32_e32 v107, v70
	s_nop 0
	v_pk_add_f32 v[70:71], v[106:107], 1.0 op_sel_hi:[1,0]
	s_nop 0
	v_rcp_f32_e32 v101, v71
	s_nop 0
	v_fma_f32 v103, -v71, v101, 1.0
	v_fmac_f32_e32 v101, v103, v101
	v_mul_f32_e32 v106, v93, v101
	v_fma_f32 v107, -v71, v106, v93
	v_fmac_f32_e32 v106, v107, v101
	v_fma_f32 v74, -v71, v106, v93
	v_fma_f32 v74, v74, v101, v106
	v_div_fixup_f32 v71, v74, v71, v93
	v_rcp_f32_e32 v93, v70
	s_nop 0
	v_fma_f32 v101, -v70, v93, 1.0
	v_fmac_f32_e32 v93, v101, v93
	v_mul_f32_e32 v103, v73, v93
	v_fma_f32 v106, -v70, v103, v73
	v_fmac_f32_e32 v103, v106, v93
	v_fma_f32 v74, -v70, v103, v73
	v_fma_f32 v74, v74, v93, v103
	v_div_fixup_f32 v70, v74, v70, v73
	v_pk_mul_f32 v[40:41], v[40:41], v[70:71]
	v_pk_add_f32 v[70:71], v[104:105], 1.0 op_sel_hi:[1,0]
	s_nop 0
	v_rcp_f32_e32 v74, v71
	s_nop 0
	v_fma_f32 v93, -v71, v74, 1.0
	v_fmac_f32_e32 v74, v93, v74
	v_mul_f32_e32 v101, 1.0, v74
	v_fma_f32 v103, -v71, v101, 1.0
	v_fmac_f32_e32 v101, v103, v74
	v_fma_f32 v73, -v71, v101, 1.0
	v_fma_f32 v73, v73, v74, v101
	v_div_fixup_f32 v71, v73, v71, 1.0
	v_rcp_f32_e32 v74, v70
	s_nop 0
	v_fma_f32 v93, -v70, v74, 1.0
	v_fmac_f32_e32 v74, v93, v74
	v_mul_f32_e32 v101, 1.0, v74
	v_fma_f32 v103, -v70, v101, 1.0
	v_fmac_f32_e32 v101, v103, v74
	v_fma_f32 v73, -v70, v101, 1.0
	v_fma_f32 v73, v73, v74, v101
	v_div_fixup_f32 v70, v73, v70, 1.0
	v_pk_mul_f32 v[40:41], v[40:41], v[70:71]
	v_lshlrev_b32_e32 v70, 16, v75
	v_mul_f32_e32 v70, 0xbfb8aa3b, v70
	v_exp_f32_e32 v70, v70
	v_cvt_pk_bf16_f32 v40, v40, v41
	v_add_f32_e32 v70, 1.0, v70
	v_rcp_f32_e32 v73, v70
	s_nop 0
	v_fma_f32 v74, -v70, v73, 1.0
	v_fmac_f32_e32 v73, v74, v73
	v_mul_f32_e32 v93, 1.0, v73
	v_fma_f32 v101, -v70, v93, 1.0
	v_fmac_f32_e32 v93, v101, v73
	v_fma_f32 v71, -v70, v93, 1.0
	v_fma_f32 v71, v71, v73, v93
	v_div_fixup_f32 v70, v71, v70, 1.0
	v_and_b32_e32 v71, 0xffff0000, v75
	v_mul_f32_e32 v71, 0xbfb8aa3b, v71
	v_exp_f32_e32 v103, v71
	s_nop 0
	v_pk_add_f32 v[74:75], v[102:103], 1.0 op_sel_hi:[1,0]
	s_nop 0
	v_rcp_f32_e32 v73, v75
	s_nop 0
	v_fma_f32 v93, -v75, v73, 1.0
	v_fmac_f32_e32 v73, v93, v73
	v_mul_f32_e32 v101, 1.0, v73
	v_fma_f32 v102, -v75, v101, 1.0
	v_fmac_f32_e32 v101, v102, v73
	v_fma_f32 v71, -v75, v101, 1.0
	v_fma_f32 v71, v71, v73, v101
	v_div_fixup_f32 v71, v71, v75, 1.0
	v_rcp_f32_e32 v75, v74
	s_mov_b64 s[0:1], 0
	v_fma_f32 v93, -v74, v75, 1.0
	v_fmac_f32_e32 v75, v93, v75
	v_mul_f32_e32 v101, v95, v75
	v_fma_f32 v102, -v74, v101, v95
	v_fmac_f32_e32 v101, v102, v75
	v_fma_f32 v73, -v74, v101, v95
	v_fma_f32 v73, v73, v75, v101
	v_pk_mul_f32 v[68:69], v[68:69], v[100:101] op_sel_hi:[1,0]
	v_div_fixup_f32 v73, v73, v74, v95
	v_pk_mul_f32 v[42:43], v[68:69], v[42:43]
	v_mov_b32_e32 v95, v161
	v_pk_mul_f32 v[42:43], v[42:43], v[72:73]
	v_lshl_add_u64 v[66:67], v[66:67], 0, v[94:95]
	v_pk_mul_f32 v[42:43], v[42:43], v[70:71]
	global_store_dword v[66:67], v40, off

; DI size_t kblk(int row, int col, int nrows) { return ((size_t)(col >> 5) * nrows + row) * 32 + (col & 31); }
; DI unsigned pk2(float a, float b) { hwf32x2 f = {a, b}; hwbf16x2 r = __builtin_convertvector(f, hwbf16x2); return __builtin_bit_cast(unsigned, r); }
; DI float siluf_(float z) { return z / (1.f + __expf(-z)); }
; #define MFMA16(a, b, c) __builtin_amdgcn_mfma_f32_16x16x32_bf16((a), (b), (c), 0, 0, 0)
; template <int MX, bool OUT>
; DI void rec_chunk(const Params& p, int l, int b, int h, int dir, int T0, unsigned char* smem, f32x4 (&St)[4], float& nst, float& dtot, int tid, const RecRaw& raw) {
;     ...
;     for (int ks = 0; ks < 2; ++ks) {
;       const bf16x8 fb = *(const bf16x8*)(smem + L_QS + swz(t, ks * 4 + g));
; #pragma unroll
;       for (int a = 0; a < 4; ++a) {
;         const bf16x8 fa = *(const bf16x8*)(smem + L_STT + swz(16 * a + col, ks * 4 + g));
;         O[a] = MFMA16(fa, fb, O[a]);
;       }
;     }
;     if (MX == 1) {
;       const float inv = 1.f / fmaxf(fabsf(den), 1.f);
; #pragma unroll
;       for (int a = 0; a < 4; ++a)
; #pragma unroll
;         for (int j = 0; j < 4; ++j) O[a][j] *= inv;
;     }
;     if (dir == 0) {
; #pragma unroll
;       for (int a = 0; a < 4; ++a) *(uint2*)(MIX + kblk((int)orow, cb + 16 * a + 4 * g, ROWS)) = make_uint2(pk2(O[a][0], O[a][1]), pk2(O[a][2], O[a][3]));
;     } else {
;       float ss = 0.f;
; #pragma unroll
;       for (int a = 0; a < 4; ++a) {
;         const uint2 u = *(const uint2*)(MIX + kblk((int)orow, cb + 16 * a + 4 * g, ROWS));
;         O[a][0] += __uint_as_float(u.x << 16); O[a][1] += __uint_as_float(u.x & 0xffff0000u);
;         O[a][2] += __uint_as_float(u.y << 16); O[a][3] += __uint_as_float(u.y & 0xffff0000u);
; #pragma unroll
;         for (int j = 0; j < 4; ++j) ss += O[a][j] * O[a][j];
;       }
;       ss += __shfl_xor(ss, 16);
;       ss += __shfl_xor(ss, 32);
;       const float rstd = rsqrtf(ss * (1.f / 64.f) + EPS);
;       const float* gvec = (MX ? p.ml_g : p.hg_g) + l * 64;
; #pragma unroll
;       for (int a = 0; a < 4; ++a) {
;         const int v0 = 16 * a + 4 * g;
;         const uint2 gt = *(const uint2*)(prow + GATE + cb + v0);
;         const float4 gg = *(const float4*)(gvec + v0);
;         float y0 = O[a][0] * rstd * gg.x * siluf_(__uint_as_float(gt.x << 16));
.LBB0_1014:
	s_or_b64 exec, exec, s[26:27]
	s_add_i32 s26, s83, -1
	v_mov_b32_e32 v40, s26
	v_cndmask_b32_e64 v40, v95, v40, s[8:9]
	v_lshlrev_b32_e32 v40, 6, v40
	v_add_u32_e32 v40, s81, v40
	v_mov_b32_e32 v41, v161
	v_lshl_add_u64 v[68:69], v[40:41], 0, v[84:85]
	ds_read_b128 v[40:43], v203 offset:32768
	ds_read_b128 v[44:47], v201 offset:57344
	ds_read_b128 v[48:51], v201 offset:59392
	ds_read_b128 v[52:55], v201 offset:61440
	s_waitcnt lgkmcnt(0)
	v_mfma_f32_16x16x32_bf16 v[44:47], v[44:47], v[40:43], v[56:59]
	s_mov_b64 s[26:27], -1
	s_nop 1
	ds_read_b128 v[56:59], v201 offset:63488
	s_and_b64 vcc, exec, s[78:79]
	v_mfma_f32_16x16x32_bf16 v[48:51], v[48:51], v[40:43], v[60:63]
	v_ashrrev_i32_e32 v204, 31, v68
	v_mfma_f32_16x16x32_bf16 v[52:55], v[52:55], v[40:43], v[64:67]
	s_waitcnt lgkmcnt(0)
	v_mfma_f32_16x16x32_bf16 v[56:59], v[56:59], v[40:43], v[72:75]
	ds_read_b128 v[60:63], v202 offset:32768
	ds_read_b128 v[40:43], v200 offset:57344
	s_waitcnt lgkmcnt(0)
	v_mfma_f32_16x16x32_bf16 v[40:43], v[40:43], v[60:63], v[44:47]
	s_nop 2
	ds_read_b128 v[44:47], v200 offset:59392
	s_waitcnt lgkmcnt(0)
	v_mfma_f32_16x16x32_bf16 v[48:51], v[44:47], v[60:63], v[48:51]
	ds_read_b128 v[44:47], v200 offset:61440
	s_waitcnt lgkmcnt(0)
	v_mfma_f32_16x16x32_bf16 v[52:55], v[44:47], v[60:63], v[52:55]
	ds_read_b128 v[44:47], v200 offset:63488
	s_waitcnt lgkmcnt(0)
	v_mfma_f32_16x16x32_bf16 v[44:47], v[44:47], v[60:63], v[56:59]
	s_cbranch_vccnz .LBB0_1016
	s_nop 1
	v_mov_b64_e32 v[56:57], s[14:15]
	v_mad_u64_u32 v[56:57], s[26:27], v68, s33, v[56:57]
	v_mad_i32_i24 v57, v69, s33, v57
	v_mov_b32_e32 v69, v204
	v_lshl_add_u64 v[60:61], v[68:69], 0, s[30:31]
	v_lshlrev_b64 v[60:61], 6, v[60:61]
	v_lshl_add_u64 v[70:71], v[90:91], 0, v[60:61]
	global_load_dwordx2 v[60:61], v[70:71], off
	v_lshl_add_u64 v[58:59], v[68:69], 0, s[28:29]
	v_lshlrev_b64 v[58:59], 6, v[58:59]
	v_mov_b32_e32 v95, v161
	v_lshl_add_u64 v[100:101], v[86:87], 0, v[58:59]
	global_load_dwordx2 v[58:59], v[100:101], off
	s_mov_b64 s[26:27], 0x41c7a20
	v_lshl_add_u64 v[56:57], v[56:57], 0, s[26:27]
	v_lshl_add_u64 v[72:73], v[56:57], 0, s[2:3]
	v_lshl_add_u64 v[56:57], v[56:57], 0, v[94:95]
	v_lshl_add_u64 v[56:57], v[56:57], 0, s[2:3]
	v_cmp_lt_i32_e32 vcc, v183, v178
	v_lshl_add_u64 v[72:73], v[72:73], 0, v[94:95]
	global_load_dwordx2 v[56:57], v[56:57], off
	s_waitcnt vmcnt(0) lgkmcnt(0)
	v_lshlrev_b32_e32 v74, 16, v60
	v_and_b32_e32 v75, 0xffff0000, v60
	v_lshlrev_b32_e32 v102, 16, v61
	v_and_b32_e32 v103, 0xffff0000, v61
	v_lshl_add_u64 v[60:61], v[68:69], 0, s[42:43]
	v_lshlrev_b64 v[60:61], 6, v[60:61]
	v_lshl_add_u64 v[60:61], s[6:7], 0, v[60:61]
	v_lshl_add_u64 v[66:67], v[60:61], 0, v[94:95]
	global_load_dwordx2 v[62:63], v[66:67], off
	v_cndmask_b32_e32 v69, v177, v183, vcc
	v_cmp_lt_i32_e32 vcc, v184, v178
	v_lshlrev_b32_e32 v97, 2, v69
	v_lshlrev_b32_e32 v116, 16, v58
	v_cndmask_b32_e32 v69, v177, v184, vcc
	v_and_b32_e32 v117, 0xffff0000, v58
	v_lshlrev_b32_e32 v58, 16, v59
	v_and_b32_e32 v59, 0xffff0000, v59
	v_pk_add_f32 v[112:113], v[42:43], v[58:59]
	v_pk_add_f32 v[116:117], v[40:41], v[116:117]
	v_pk_mul_f32 v[114:115], v[112:113], v[112:113]
	v_pk_mul_f32 v[120:121], v[116:117], v[116:117]
	v_lshlrev_b32_e32 v69, 2, v69
	v_add_f32_e32 v95, v120, v121
	v_add_f32_e32 v95, v95, v114
	v_add_f32_e32 v95, v115, v95
	v_lshlrev_b32_e32 v205, 16, v56
	v_and_b32_e32 v206, 0xffff0000, v56
	v_lshlrev_b32_e32 v208, 16, v57
	v_and_b32_e32 v209, 0xffff0000, v57
	global_load_dwordx4 v[56:59], v[88:89], off
	v_mul_f32_e32 v118, 0xbfb8aa3b, v205
	v_mul_f32_e32 v119, 0xbfb8aa3b, v206
	v_exp_f32_e32 v118, v118
	v_exp_f32_e32 v119, v119
	s_waitcnt vmcnt(0) lgkmcnt(0)
	v_lshlrev_b32_e32 v108, 16, v62
	v_and_b32_e32 v109, 0xffff0000, v62
	v_lshlrev_b32_e32 v110, 16, v63
	v_and_b32_e32 v111, 0xffff0000, v63
	global_load_dwordx2 v[62:63], v[66:67], off offset:32
	v_pk_add_f32 v[118:119], v[118:119], 1.0 op_sel_hi:[1,0]
	v_pk_add_f32 v[108:109], v[52:53], v[108:109]
	v_mov_b32_e32 v210, v205
	v_mov_b32_e32 v211, v206
	v_rcp_f32_e32 v64, v118
	v_rcp_f32_e32 v65, v119
	s_nop 0
	v_pk_fma_f32 v[106:107], v[118:119], v[64:65], 1.0 op_sel_hi:[1,1,0] neg_lo:[1,0,0] neg_hi:[1,0,0]
	v_pk_fma_f32 v[64:65], v[106:107], v[64:65], v[64:65]
	v_pk_mul_f32 v[104:105], v[210:211], v[64:65]
	v_pk_fma_f32 v[106:107], v[118:119], v[104:105], v[210:211] neg_lo:[1,0,0] neg_hi:[1,0,0]
	v_pk_fma_f32 v[104:105], v[106:107], v[64:65], v[104:105]
	v_pk_fma_f32 v[106:107], v[118:119], v[104:105], v[210:211] neg_lo:[1,0,0] neg_hi:[1,0,0]
	v_pk_fma_f32 v[104:105], v[106:107], v[64:65], v[104:105]
	v_div_fixup_f32 v118, v104, v118, v205
	v_div_fixup_f32 v119, v105, v119, v206
	v_pk_mul_f32 v[214:215], v[108:109], v[108:109]
	s_waitcnt vmcnt(0) lgkmcnt(0)
; DI size_t kblk(int row, int col, int nrows) { return ((size_t)(col >> 5) * nrows + row) * 32 + (col & 31); }
; DI float siluf_(float z) { return z / (1.f + __expf(-z)); }
; template <int MX, bool OUT>
; DI void rec_chunk(const Params& p, int l, int b, int h, int dir, int T0, unsigned char* smem, f32x4 (&St)[4], float& nst, float& dtot, int tid, const RecRaw& raw) {
;     ...
;         const uint2 u = *(const uint2*)(MIX + kblk((int)orow, cb + 16 * a + 4 * g, ROWS));
;         O[a][0] += __uint_as_float(u.x << 16); O[a][1] += __uint_as_float(u.x & 0xffff0000u);
;         O[a][2] += __uint_as_float(u.y << 16); O[a][3] += __uint_as_float(u.y & 0xffff0000u);
; #pragma unroll
;         for (int j = 0; j < 4; ++j) ss += O[a][j] * O[a][j];
;       }
;       ss += __shfl_xor(ss, 16);
;       ss += __shfl_xor(ss, 32);
;       const float rstd = rsqrtf(ss * (1.f / 64.f) + EPS);
;       const float* gvec = (MX ? p.ml_g : p.hg_g) + l * 64;
; #pragma unroll
;       for (int a = 0; a < 4; ++a) {
;         const int v0 = 16 * a + 4 * g;
;         const uint2 gt = *(const uint2*)(prow + GATE + cb + v0);
;         const float4 gg = *(const float4*)(gvec + v0);
;         float y0 = O[a][0] * rstd * gg.x * siluf_(__uint_as_float(gt.x << 16));
;         float y1 = O[a][1] * rstd * gg.y * siluf_(__uint_as_float(gt.x & 0xffff0000u));
;         float y2 = O[a][2] * rstd * gg.z * siluf_(__uint_as_float(gt.y << 16));
;         float y3 = O[a][3] * rstd * gg.w * siluf_(__uint_as_float(gt.y & 0xffff0000u));
	v_lshlrev_b32_e32 v64, 16, v62
	v_mul_f32_e32 v205, 0xbfb8aa3b, v208
	v_exp_f32_e32 v206, v205
	v_mul_f32_e32 v205, 0xbfb8aa3b, v209
	v_exp_f32_e32 v207, v205
	v_and_b32_e32 v65, 0xffff0000, v62
	v_pk_add_f32 v[64:65], v[44:45], v[64:65]
	v_lshlrev_b32_e32 v62, 16, v63
	v_pk_add_f32 v[206:207], v[206:207], 1.0 op_sel_hi:[1,0]
	v_and_b32_e32 v63, 0xffff0000, v63
	v_rcp_f32_e32 v104, v206
	v_rcp_f32_e32 v105, v207
	s_nop 0
	v_pk_fma_f32 v[210:211], v[206:207], v[104:105], 1.0 op_sel_hi:[1,1,0] neg_lo:[1,0,0] neg_hi:[1,0,0]
	v_pk_fma_f32 v[104:105], v[210:211], v[104:105], v[104:105]
	v_pk_mul_f32 v[106:107], v[208:209], v[104:105]
	v_pk_fma_f32 v[210:211], v[206:207], v[106:107], v[208:209] neg_lo:[1,0,0] neg_hi:[1,0,0]
	v_pk_fma_f32 v[106:107], v[210:211], v[104:105], v[106:107]
	v_pk_fma_f32 v[210:211], v[206:207], v[106:107], v[208:209] neg_lo:[1,0,0] neg_hi:[1,0,0]
	v_pk_fma_f32 v[106:107], v[210:211], v[104:105], v[106:107]
	v_div_fixup_f32 v206, v106, v206, v208
	v_div_fixup_f32 v207, v107, v207, v209
	v_pk_mul_f32 v[104:105], v[64:65], v[64:65]
	v_pk_add_f32 v[62:63], v[46:47], v[62:63]
	v_pk_mul_f32 v[106:107], v[62:63], v[62:63]
	v_pk_add_f32 v[212:213], v[48:49], v[74:75]
	v_pk_mul_f32 v[74:75], v[212:213], v[212:213]
	v_pk_add_f32 v[208:209], v[50:51], v[102:103]
	v_add_f32_e32 v74, v74, v95
	v_pk_mul_f32 v[210:211], v[208:209], v[208:209]
	v_add_f32_e32 v74, v75, v74
	v_add_f32_e32 v74, v210, v74
	v_add_f32_e32 v74, v211, v74
	v_pk_add_f32 v[102:103], v[54:55], v[110:111]
	v_add_f32_e32 v74, v214, v74
	v_pk_mul_f32 v[110:111], v[102:103], v[102:103]
	v_add_f32_e32 v74, v215, v74
	v_add_f32_e32 v74, v110, v74
	v_add_f32_e32 v74, v111, v74
	v_add_f32_e32 v74, v104, v74
	v_add_f32_e32 v74, v105, v74
	v_add_f32_e32 v74, v106, v74
	v_add_f32_e32 v74, v107, v74
	ds_bpermute_b32 v75, v97, v74
	s_waitcnt lgkmcnt(0)
	v_add_f32_e32 v74, v74, v75
	ds_bpermute_b32 v69, v69, v74
	s_waitcnt lgkmcnt(0)
	v_add_f32_e32 v69, v74, v69
	v_fmamk_f32 v69, v69, 0x3c800000, v162
	v_cmp_gt_f32_e32 vcc, s38, v69
	v_mul_f32_e32 v74, 0x4b800000, v69
	s_nop 0
	v_cndmask_b32_e32 v69, v69, v74, vcc
	v_rsq_f32_e32 v69, v69
	s_nop 0
	v_mul_f32_e32 v74, 0x45800000, v69
	v_cndmask_b32_e32 v74, v69, v74, vcc
	v_pk_mul_f32 v[104:105], v[116:117], v[74:75] op_sel_hi:[1,0]
	s_nop 0
	v_pk_mul_f32 v[56:57], v[56:57], v[104:105]
	v_pk_mul_f32 v[104:105], v[112:113], v[74:75] op_sel_hi:[1,0]
	v_pk_mul_f32 v[56:57], v[118:119], v[56:57]
	v_pk_mul_f32 v[58:59], v[58:59], v[104:105]
	v_cvt_pk_bf16_f32 v56, v56, v57
	v_pk_mul_f32 v[58:59], v[206:207], v[58:59]
	s_nop 0
	v_cvt_pk_bf16_f32 v57, v58, v59
	global_store_dwordx2 v[100:101], v[56:57], off
	global_load_dwordx2 v[100:101], v[72:73], off offset:32
	s_nop 0
	global_load_dwordx4 v[56:59], v[88:89], off offset:64
	s_waitcnt vmcnt(0) lgkmcnt(0)
	v_lshlrev_b32_e32 v69, 16, v100
	v_and_b32_e32 v75, 0xffff0000, v100
	v_mul_f32_e32 v95, 0xbfb8aa3b, v69
	v_exp_f32_e32 v104, v95
	v_mul_f32_e32 v95, 0xbfb8aa3b, v75
	v_exp_f32_e32 v105, v95
	v_pk_mul_f32 v[106:107], v[212:213], v[74:75] op_sel_hi:[1,0]
	v_pk_add_f32 v[104:105], v[104:105], 1.0 op_sel_hi:[1,0]
	s_nop 0
	v_rcp_f32_e32 v97, v105
	v_pk_mul_f32 v[56:57], v[56:57], v[106:107]
	v_fma_f32 v100, -v105, v97, 1.0
	v_fmac_f32_e32 v97, v100, v97
	v_mul_f32_e32 v106, v75, v97
	v_fma_f32 v107, -v105, v106, v75
	v_fmac_f32_e32 v106, v107, v97
	v_fma_f32 v95, -v105, v106, v75
	v_fma_f32 v95, v95, v97, v106
	v_div_fixup_f32 v105, v95, v105, v75
	v_rcp_f32_e32 v95, v104
	s_nop 0
	v_fma_f32 v97, -v104, v95, 1.0
	v_fmac_f32_e32 v95, v97, v95
	v_mul_f32_e32 v100, v69, v95
	v_fma_f32 v106, -v104, v100, v69
	v_fmac_f32_e32 v100, v106, v95
	v_fma_f32 v75, -v104, v100, v69
	v_fma_f32 v75, v75, v95, v100
	v_div_fixup_f32 v104, v75, v104, v69
	v_lshlrev_b32_e32 v69, 16, v101
	v_and_b32_e32 v75, 0xffff0000, v101
	v_mul_f32_e32 v95, 0xbfb8aa3b, v69
	v_exp_f32_e32 v100, v95
	v_mul_f32_e32 v95, 0xbfb8aa3b, v75
	v_exp_f32_e32 v101, v95
	v_pk_mul_f32 v[56:57], v[104:105], v[56:57]
	v_pk_mul_f32 v[104:105], v[208:209], v[74:75] op_sel_hi:[1,0]
	v_cvt_pk_bf16_f32 v56, v56, v57
	v_pk_add_f32 v[100:101], v[100:101], 1.0 op_sel_hi:[1,0]
	v_pk_mul_f32 v[58:59], v[58:59], v[104:105]
	v_rcp_f32_e32 v97, v101
	s_nop 0
	v_fma_f32 v104, -v101, v97, 1.0
	v_fmac_f32_e32 v97, v104, v97
	v_mul_f32_e32 v105, v75, v97
	v_fma_f32 v106, -v101, v105, v75
	v_fmac_f32_e32 v105, v106, v97
	v_fma_f32 v95, -v101, v105, v75
	v_fma_f32 v95, v95, v97, v105
	v_div_fixup_f32 v101, v95, v101, v75
	v_rcp_f32_e32 v95, v100
	s_nop 0
	v_fma_f32 v97, -v100, v95, 1.0
	v_fmac_f32_e32 v95, v97, v95
	v_mul_f32_e32 v104, v69, v95
	v_fma_f32 v105, -v100, v104, v69
	v_fmac_f32_e32 v104, v105, v95
	v_fma_f32 v75, -v100, v104, v69
	v_fma_f32 v75, v75, v95, v104
	v_div_fixup_f32 v100, v75, v100, v69
	v_pk_mul_f32 v[58:59], v[100:101], v[58:59]
	s_nop 0
	v_cvt_pk_bf16_f32 v57, v58, v59
	global_store_dwordx2 v[70:71], v[56:57], off
	global_load_dwordx2 v[70:71], v[72:73], off offset:64
	s_nop 0
	global_load_dwordx4 v[56:59], v[88:89], off offset:128
	s_waitcnt vmcnt(0) lgkmcnt(0)
; DI size_t kblk(int row, int col, int nrows) { return ((size_t)(col >> 5) * nrows + row) * 32 + (col & 31); }
; DI unsigned pk2(float a, float b) { hwf32x2 f = {a, b}; hwbf16x2 r = __builtin_convertvector(f, hwbf16x2); return __builtin_bit_cast(unsigned, r); }
; DI float sigmoidf_(float z) { return 1.f / (1.f + __expf(-z)); }
; DI float siluf_(float z) { return z / (1.f + __expf(-z)); }
; template <int MX, bool OUT>
; DI void rec_chunk(const Params& p, int l, int b, int h, int dir, int T0, unsigned char* smem, f32x4 (&St)[4], float& nst, float& dtot, int tid, const RecRaw& raw) {
;     ...
;       for (int a = 0; a < 4; ++a) {
;         const int v0 = 16 * a + 4 * g;
;         const uint2 gt = *(const uint2*)(prow + GATE + cb + v0);
;         const float4 gg = *(const float4*)(gvec + v0);
;         float y0 = O[a][0] * rstd * gg.x * siluf_(__uint_as_float(gt.x << 16));
;         float y1 = O[a][1] * rstd * gg.y * siluf_(__uint_as_float(gt.x & 0xffff0000u));
;         float y2 = O[a][2] * rstd * gg.z * siluf_(__uint_as_float(gt.y << 16));
;         float y3 = O[a][3] * rstd * gg.w * siluf_(__uint_as_float(gt.y & 0xffff0000u));
;         if (MX == 1) {
;           const uint2 og = *(const uint2*)(prow + D_OG + h * 64 + v0);
;           y0 *= sigmoidf_(__uint_as_float(og.x << 16)); y1 *= sigmoidf_(__uint_as_float(og.x & 0xffff0000u));
;           y2 *= sigmoidf_(__uint_as_float(og.y << 16)); y3 *= sigmoidf_(__uint_as_float(og.y & 0xffff0000u));
;         }
;         *(uint2*)(MIX + kblk((int)orow, cb + v0, ROWS)) = make_uint2(pk2(y0, y1), pk2(y2, y3));
	v_lshlrev_b32_e32 v69, 16, v70
	v_and_b32_e32 v70, 0xffff0000, v70
	v_mul_f32_e32 v75, 0xbfb8aa3b, v69
	v_exp_f32_e32 v100, v75
	v_pk_mul_f32 v[104:105], v[108:109], v[74:75] op_sel_hi:[1,0]
	v_mul_f32_e32 v75, 0xbfb8aa3b, v70
	v_exp_f32_e32 v101, v75
	v_pk_mul_f32 v[56:57], v[104:105], v[56:57]
	v_pk_add_f32 v[100:101], v[100:101], 1.0 op_sel_hi:[1,0]
	s_nop 0
	v_rcp_f32_e32 v95, v101
	s_nop 0
	v_fma_f32 v97, -v101, v95, 1.0
	v_fmac_f32_e32 v95, v97, v95
	v_mul_f32_e32 v104, v70, v95
	v_fma_f32 v105, -v101, v104, v70
	v_fmac_f32_e32 v104, v105, v95
	v_fma_f32 v75, -v101, v104, v70
	v_fma_f32 v75, v75, v95, v104
	v_div_fixup_f32 v101, v75, v101, v70
	v_rcp_f32_e32 v75, v100
	s_nop 0
	v_fma_f32 v95, -v100, v75, 1.0
	v_fmac_f32_e32 v75, v95, v75
	v_mul_f32_e32 v97, v69, v75
	v_fma_f32 v104, -v100, v97, v69
	v_fmac_f32_e32 v97, v104, v75
	v_fma_f32 v70, -v100, v97, v69
	v_fma_f32 v70, v70, v75, v97
	v_div_fixup_f32 v100, v70, v100, v69
	v_lshlrev_b32_e32 v69, 16, v71
	v_and_b32_e32 v75, 0xffff0000, v71
	v_mul_f32_e32 v70, 0xbfb8aa3b, v69
	v_mul_f32_e32 v71, 0xbfb8aa3b, v75
	v_exp_f32_e32 v70, v70
	v_exp_f32_e32 v71, v71
	v_pk_mul_f32 v[56:57], v[56:57], v[100:101]
	v_pk_mul_f32 v[100:101], v[102:103], v[74:75] op_sel_hi:[1,0]
	v_cvt_pk_bf16_f32 v56, v56, v57
	v_pk_add_f32 v[70:71], v[70:71], 1.0 op_sel_hi:[1,0]
	v_pk_mul_f32 v[58:59], v[100:101], v[58:59]
	v_rcp_f32_e32 v97, v71
	s_nop 0
	v_fma_f32 v100, -v71, v97, 1.0
	v_fmac_f32_e32 v97, v100, v97
	v_mul_f32_e32 v101, v75, v97
	v_fma_f32 v102, -v71, v101, v75
	v_fmac_f32_e32 v101, v102, v97
	v_fma_f32 v95, -v71, v101, v75
	v_fma_f32 v95, v95, v97, v101
	v_div_fixup_f32 v71, v95, v71, v75
	v_rcp_f32_e32 v95, v70
	s_nop 0
	v_fma_f32 v97, -v70, v95, 1.0
	v_fmac_f32_e32 v95, v97, v95
	v_mul_f32_e32 v100, v69, v95
	v_fma_f32 v101, -v70, v100, v69
	v_fmac_f32_e32 v100, v101, v95
	v_fma_f32 v75, -v70, v100, v69
	v_fma_f32 v75, v75, v95, v100
	v_div_fixup_f32 v70, v75, v70, v69
	v_pk_mul_f32 v[58:59], v[58:59], v[70:71]
	v_pk_mul_f32 v[64:65], v[64:65], v[74:75] op_sel_hi:[1,0]
	v_cvt_pk_bf16_f32 v57, v58, v59
	global_store_dwordx2 v[66:67], v[56:57], off
	global_load_dwordx2 v[66:67], v[72:73], off offset:96
	v_mov_b32_e32 v97, v161
	global_load_dwordx4 v[56:59], v[88:89], off offset:192
	s_waitcnt vmcnt(0) lgkmcnt(0)
	v_lshlrev_b32_e32 v69, 16, v66
	v_and_b32_e32 v66, 0xffff0000, v66
	v_mul_f32_e32 v70, 0xbfb8aa3b, v69
	v_pk_mul_f32 v[56:57], v[64:65], v[56:57]
	v_mul_f32_e32 v64, 0xbfb8aa3b, v66
	v_exp_f32_e32 v70, v70
	v_exp_f32_e32 v71, v64
	s_nop 0
	v_pk_add_f32 v[64:65], v[70:71], 1.0 op_sel_hi:[1,0]
	s_nop 0
	v_rcp_f32_e32 v71, v65
	s_nop 0
	v_fma_f32 v72, -v65, v71, 1.0
	v_fmac_f32_e32 v71, v72, v71
	v_mul_f32_e32 v73, v66, v71
	v_fma_f32 v75, -v65, v73, v66
	v_fmac_f32_e32 v73, v75, v71
	v_fma_f32 v70, -v65, v73, v66
	v_fma_f32 v70, v70, v71, v73
	v_div_fixup_f32 v65, v70, v65, v66
	v_rcp_f32_e32 v70, v64
	v_pk_mul_f32 v[62:63], v[62:63], v[74:75] op_sel_hi:[1,0]
	v_fma_f32 v71, -v64, v70, 1.0
	v_fmac_f32_e32 v70, v71, v70
	v_mul_f32_e32 v72, v69, v70
	v_fma_f32 v73, -v64, v72, v69
	v_fmac_f32_e32 v72, v73, v70
	v_fma_f32 v66, -v64, v72, v69
	v_fma_f32 v66, v66, v70, v72
	v_div_fixup_f32 v64, v66, v64, v69
	v_lshlrev_b32_e32 v66, 16, v67
	v_and_b32_e32 v67, 0xffff0000, v67
	v_pk_mul_f32 v[64:65], v[56:57], v[64:65]
	v_mul_f32_e32 v56, 0xbfb8aa3b, v66
	v_mul_f32_e32 v57, 0xbfb8aa3b, v67
	v_exp_f32_e32 v56, v56
	v_exp_f32_e32 v57, v57
	v_pk_mul_f32 v[58:59], v[62:63], v[58:59]
	v_pk_add_f32 v[56:57], v[56:57], 1.0 op_sel_hi:[1,0]
	s_nop 0
	v_rcp_f32_e32 v63, v57
	s_nop 0
	v_fma_f32 v69, -v57, v63, 1.0
	v_fmac_f32_e32 v63, v69, v63
	v_mul_f32_e32 v70, v67, v63
	v_fma_f32 v71, -v57, v70, v67
	v_fmac_f32_e32 v70, v71, v63
	v_fma_f32 v62, -v57, v70, v67
	v_fma_f32 v62, v62, v63, v70
	v_div_fixup_f32 v57, v62, v57, v67
	v_rcp_f32_e32 v63, v56
	s_mov_b64 s[26:27], 0
	v_fma_f32 v67, -v56, v63, 1.0
	v_fmac_f32_e32 v63, v67, v63
	v_mul_f32_e32 v69, v66, v63
	v_fma_f32 v70, -v56, v69, v66
	v_fmac_f32_e32 v69, v70, v63
	v_fma_f32 v62, -v56, v69, v66
	v_fma_f32 v62, v62, v63, v69
	v_div_fixup_f32 v56, v62, v56, v66
	v_pk_mul_f32 v[56:57], v[58:59], v[56:57]
	v_cvt_pk_bf16_f32 v62, v64, v65
	v_lshl_add_u64 v[58:59], v[60:61], 0, v[96:97]
	global_store_dword v[58:59], v62, off
